# final candidate re-measure: all kept edits (GEMM early barrier, attention cleanups + P.V pipelining, scan pipelining, final-norm weight hoist, SSD-out tile loads)
# speedup vs baseline: 1.0089x; 1.0054x over previous
; #define PG8_STAGE(bufoff, gbase, voff) do { if constexpr (!pg8_noload<Epi>::value) { _Pragma("unroll") for (int _i = 0; _i < 2; ++_i) \
;         __builtin_amdgcn_global_load_lds((const unsigned*)((const char*)(gbase) + (size_t)_i * pstep + (voff)[0]), (PG8_LAS unsigned*)(lds + (bufoff) + ldsw + _i * 8192), 16, 0, 0); } } while (0)
; #define PG8_LDA(dst, b, h) do { _Pragma("unroll") for (int m = 0; m < 4; ++m) _Pragma("unroll") for (int k = 0; k < 2; ++k) dst[m][k] = *(const PG8_LAS bf16x8*)(lds + PG8_SA(b, h) + aoff + m * 2048 + k * 1024); } while (0)
; #define PG8_LDB(dst, b, h) do { _Pragma("unroll") for (int n = 0; n < 2; ++n) _Pragma("unroll") for (int k = 0; k < 2; ++k) dst[n][k] = *(const PG8_LAS bf16x8*)(lds + PG8_SB(b, h) + boff + n * 2048 + k * 1024); } while (0)
; #define PG8_MMA(ai, bj, At, Bt) do { __builtin_amdgcn_s_setprio(1); _Pragma("unroll") for (int m = 0; m < 4; ++m) _Pragma("unroll") for (int n = 0; n < 2; ++n) _Pragma("unroll") for (int k = 0; k < 2; ++k) \
;         acc[ai][bj][m][n] = __builtin_amdgcn_mfma_f32_16x16x32_bf16(Bt[n][k], At[m][k], acc[ai][bj][m][n], 0, 0, 0); __builtin_amdgcn_s_setprio(0); } while (0)
; #define PG8_WAIT_V(n) asm volatile("s_waitcnt vmcnt(" #n ")" ::: "memory")
; #define PG8_WAIT_L(n) asm volatile("s_waitcnt lgkmcnt(" #n ")" ::: "memory")
; template <class Epi, class Sched, bool ALIGN_EPI = false, bool SP2 = false, bool ABLK = false>
; __device__ __forceinline__ void gemm_phase(PG8_LAS unsigned char* lds, const Gemm g, const Sched& S, const Epi& E) {
;     ...
;             const char* a1 = cA + (size_t)(t + 1) * kstep;
;             const char* a2 = last ? nA : cA + (size_t)(t + 2) * kstep; const char* b2 = last ? nB : cB + (size_t)(t + 2) * kstepB;
;             const char* a3 = a2 + kstep; const char* b3 = b2 + kstepB;
;             if (last && has_next) S.a_ready(nxt);
;             if constexpr (SP2) {
;             PG8_LDB(B0, 0, 0); PG8_LDB(B1, 0, 1); PG8_SCHED; PG8_LDA(At, 0, 0); PG8_STAGE(PG8_SA(1, 1), a1 + hstep, voffA);
;             PG8_WAIT_V(8); PG8_WAIT_L(0); PG8_BAR; PG8_MMA(0, 0, At, B0); PG8_MMA(0, 1, At, B1); PG8_BAR; PG8_SCHED;
;             PG8_LDA(At, 0, 1); PG8_STAGE(PG8_SB(0, 0), b2, voffB); PG8_STAGE(PG8_SB(0, 1), b2 + hstep, voffB); PG8_STAGE(PG8_SA(0, 0), a2, voffA);
;             PG8_WAIT_V(8); PG8_WAIT_L(0); PG8_BAR; PG8_MMA(1, 0, At, B0); PG8_MMA(1, 1, At, B1); PG8_BAR; PG8_SCHED;
.LBB0_114:
	ds_read_b128 v[144:147], v168
	ds_read_b128 v[184:187], v168 offset:1024
	ds_read_b128 v[188:191], v168 offset:2048
	ds_read_b128 v[192:195], v168 offset:3072
	ds_read_b128 v[196:199], v169
	ds_read_b128 v[200:203], v169 offset:1024
	ds_read_b128 v[204:207], v169 offset:2048
	ds_read_b128 v[208:211], v169 offset:3072
	s_add_u32 s71, vcc_lo, 0xfff80800
	s_addc_u32 s73, vcc_hi, -1
	s_cmp_eq_u32 s70, 28
	s_cselect_b32 s75, s3, s73
	s_cselect_b32 s74, s7, s71
	s_cselect_b32 s77, s21, s17
	s_cselect_b32 s76, s72, s16
	v_lshl_add_u64 v[244:245], vcc, 0, v[136:137]
	s_add_i32 m0, s53, 0xc000
	ds_read_b128 v[212:215], v170
	ds_read_b128 v[216:219], v170 offset:1024
	ds_read_b128 v[220:223], v170 offset:2048
	ds_read_b128 v[224:227], v170 offset:3072
	ds_read_b128 v[228:231], v170 offset:4096
	ds_read_b128 v[232:235], v170 offset:5120
	ds_read_b128 v[236:239], v170 offset:6144
	ds_read_b128 v[240:243], v170 offset:7168
	global_load_lds_dwordx4 v[244:245], off
	v_lshl_add_u64 v[244:245], v[244:245], 0, s[0:1]
	s_add_i32 m0, s53, 0xe000
	s_nop 0
	global_load_lds_dwordx4 v[244:245], off
	s_waitcnt vmcnt(8)
	s_waitcnt lgkmcnt(0)
	s_barrier
	s_setprio 1
	s_waitcnt lgkmcnt(0)
	v_mfma_f32_16x16x32_bf16 v[126:129], v[144:147], v[212:215], v[126:129]
	v_mfma_f32_16x16x32_bf16 v[126:129], v[184:187], v[216:219], v[126:129]
	v_mfma_f32_16x16x32_bf16 v[122:125], v[188:191], v[212:215], v[122:125]
	v_mfma_f32_16x16x32_bf16 v[122:125], v[192:195], v[216:219], v[122:125]
	v_mfma_f32_16x16x32_bf16 v[110:113], v[144:147], v[220:223], v[110:113]
	v_mfma_f32_16x16x32_bf16 v[110:113], v[184:187], v[224:227], v[110:113]
	v_mfma_f32_16x16x32_bf16 v[106:109], v[188:191], v[220:223], v[106:109]
	v_mfma_f32_16x16x32_bf16 v[106:109], v[192:195], v[224:227], v[106:109]
	v_mfma_f32_16x16x32_bf16 v[94:97], v[144:147], v[228:231], v[94:97]
	v_mfma_f32_16x16x32_bf16 v[94:97], v[184:187], v[232:235], v[94:97]
	v_mfma_f32_16x16x32_bf16 v[90:93], v[188:191], v[228:231], v[90:93]
	v_mfma_f32_16x16x32_bf16 v[90:93], v[192:195], v[232:235], v[90:93]
	v_mfma_f32_16x16x32_bf16 v[78:81], v[144:147], v[236:239], v[78:81]
	v_mfma_f32_16x16x32_bf16 v[78:81], v[184:187], v[240:243], v[78:81]
	v_mfma_f32_16x16x32_bf16 v[74:77], v[188:191], v[236:239], v[74:77]
	v_mfma_f32_16x16x32_bf16 v[74:77], v[192:195], v[240:243], v[74:77]
	v_mfma_f32_16x16x32_bf16 v[118:121], v[196:199], v[212:215], v[118:121]
	v_mfma_f32_16x16x32_bf16 v[118:121], v[200:203], v[216:219], v[118:121]
	v_mfma_f32_16x16x32_bf16 v[114:117], v[204:207], v[212:215], v[114:117]
	v_mfma_f32_16x16x32_bf16 v[114:117], v[208:211], v[216:219], v[114:117]
	v_mfma_f32_16x16x32_bf16 v[102:105], v[196:199], v[220:223], v[102:105]
	v_mfma_f32_16x16x32_bf16 v[102:105], v[200:203], v[224:227], v[102:105]
	v_mfma_f32_16x16x32_bf16 v[98:101], v[204:207], v[220:223], v[98:101]
	v_mfma_f32_16x16x32_bf16 v[98:101], v[208:211], v[224:227], v[98:101]
	v_mfma_f32_16x16x32_bf16 v[86:89], v[196:199], v[228:231], v[86:89]
	v_mfma_f32_16x16x32_bf16 v[86:89], v[200:203], v[232:235], v[86:89]
	v_mfma_f32_16x16x32_bf16 v[82:85], v[204:207], v[228:231], v[82:85]
	v_mfma_f32_16x16x32_bf16 v[82:85], v[208:211], v[232:235], v[82:85]
	s_barrier
	s_setprio 2
	v_mfma_f32_16x16x32_bf16 v[70:73], v[196:199], v[236:239], v[70:73]
	v_mfma_f32_16x16x32_bf16 v[70:73], v[200:203], v[240:243], v[70:73]
	v_mfma_f32_16x16x32_bf16 v[66:69], v[204:207], v[236:239], v[66:69]
	v_mfma_f32_16x16x32_bf16 v[66:69], v[208:211], v[240:243], v[66:69]
	s_setprio 0
	s_add_i32 s71, s64, s52
	v_lshl_add_u64 v[244:245], s[76:77], 0, v[130:131]
	s_mov_b32 m0, s71
	ds_read_b128 v[212:215], v170 offset:16384
	ds_read_b128 v[216:219], v170 offset:17408
	ds_read_b128 v[220:223], v170 offset:18432
	ds_read_b128 v[224:227], v170 offset:19456
	ds_read_b128 v[228:231], v170 offset:20480
	ds_read_b128 v[232:235], v170 offset:21504
	ds_read_b128 v[236:239], v170 offset:22528
	ds_read_b128 v[240:243], v170 offset:23552
	global_load_lds_dwordx4 v[244:245], off
	v_lshl_add_u64 v[246:247], v[244:245], 0, s[0:1]
	s_add_i32 m0, s71, 0x2000
	s_add_i32 s71, s65, s52
	global_load_lds_dwordx4 v[246:247], off
	v_lshl_add_u64 v[246:247], v[244:245], 0, s[14:15]
	s_mov_b32 m0, s71
	s_nop 0
	global_load_lds_dwordx4 v[246:247], off
	v_lshl_add_u64 v[246:247], v[244:245], 0, s[18:19]
	s_add_i32 m0, s71, 0x2000
	s_nop 0
	global_load_lds_dwordx4 v[246:247], off
	v_lshl_add_u64 v[246:247], s[74:75], 0, v[130:131]
	s_mov_b32 m0, s53
	v_lshl_add_u64 v[248:249], v[246:247], 0, s[0:1]
	global_load_lds_dwordx4 v[246:247], off
	s_mov_b32 m0, s54
	s_nop 0
	global_load_lds_dwordx4 v[248:249], off
	s_waitcnt vmcnt(8)
	s_waitcnt lgkmcnt(0)
	s_barrier
; #define PG8_STAGE(bufoff, gbase, voff) do { if constexpr (!pg8_noload<Epi>::value) { _Pragma("unroll") for (int _i = 0; _i < 2; ++_i) \
;         __builtin_amdgcn_global_load_lds((const unsigned*)((const char*)(gbase) + (size_t)_i * pstep + (voff)[0]), (PG8_LAS unsigned*)(lds + (bufoff) + ldsw + _i * 8192), 16, 0, 0); } } while (0)
; #define PG8_LDA(dst, b, h) do { _Pragma("unroll") for (int m = 0; m < 4; ++m) _Pragma("unroll") for (int k = 0; k < 2; ++k) dst[m][k] = *(const PG8_LAS bf16x8*)(lds + PG8_SA(b, h) + aoff + m * 2048 + k * 1024); } while (0)
; #define PG8_LDB(dst, b, h) do { _Pragma("unroll") for (int n = 0; n < 2; ++n) _Pragma("unroll") for (int k = 0; k < 2; ++k) dst[n][k] = *(const PG8_LAS bf16x8*)(lds + PG8_SB(b, h) + boff + n * 2048 + k * 1024); } while (0)
; #define PG8_MMA(ai, bj, At, Bt) do { __builtin_amdgcn_s_setprio(1); _Pragma("unroll") for (int m = 0; m < 4; ++m) _Pragma("unroll") for (int n = 0; n < 2; ++n) _Pragma("unroll") for (int k = 0; k < 2; ++k) \
;         acc[ai][bj][m][n] = __builtin_amdgcn_mfma_f32_16x16x32_bf16(Bt[n][k], At[m][k], acc[ai][bj][m][n], 0, 0, 0); __builtin_amdgcn_s_setprio(0); } while (0)
; #define PG8_WAIT_V(n) asm volatile("s_waitcnt vmcnt(" #n ")" ::: "memory")
; #define PG8_WAIT_L(n) asm volatile("s_waitcnt lgkmcnt(" #n ")" ::: "memory")
; #define PG8_BAR __builtin_amdgcn_s_barrier()
; #define PG8_SCHED __builtin_amdgcn_sched_barrier(0)
; template <class Epi, class Sched, bool ALIGN_EPI = false, bool SP2 = false, bool ABLK = false>
; __device__ __forceinline__ void gemm_phase(PG8_LAS unsigned char* lds, const Gemm g, const Sched& S, const Epi& E) {
;     ...
;             PG8_WAIT_V(8); PG8_WAIT_L(0); PG8_BAR; PG8_MMA(1, 0, At, B0); PG8_MMA(1, 1, At, B1); PG8_BAR; PG8_SCHED;
;             PG8_LDB(B0, 1, 0); PG8_LDB(B1, 1, 1); PG8_SCHED; PG8_LDA(At, 1, 0); PG8_STAGE(PG8_SA(0, 1), a2 + hstep, voffA);
;             PG8_WAIT_V(8); PG8_WAIT_L(0); PG8_BAR; PG8_MMA(0, 0, At, B0); PG8_MMA(0, 1, At, B1); PG8_BAR; PG8_SCHED;
;             PG8_LDA(At, 1, 1); PG8_STAGE(PG8_SB(1, 0), b3, voffB); PG8_STAGE(PG8_SB(1, 1), b3 + hstep, voffB); PG8_STAGE(PG8_SA(1, 0), a3, voffA);
	s_setprio 1
	s_waitcnt lgkmcnt(0)
	v_mfma_f32_16x16x32_bf16 v[62:65], v[144:147], v[212:215], v[62:65]
	v_mfma_f32_16x16x32_bf16 v[62:65], v[184:187], v[216:219], v[62:65]
	v_mfma_f32_16x16x32_bf16 v[58:61], v[188:191], v[212:215], v[58:61]
	v_mfma_f32_16x16x32_bf16 v[58:61], v[192:195], v[216:219], v[58:61]
	v_mfma_f32_16x16x32_bf16 v[46:49], v[144:147], v[220:223], v[46:49]
	v_mfma_f32_16x16x32_bf16 v[46:49], v[184:187], v[224:227], v[46:49]
	v_mfma_f32_16x16x32_bf16 v[42:45], v[188:191], v[220:223], v[42:45]
	v_mfma_f32_16x16x32_bf16 v[42:45], v[192:195], v[224:227], v[42:45]
	v_mfma_f32_16x16x32_bf16 v[30:33], v[144:147], v[228:231], v[30:33]
	v_mfma_f32_16x16x32_bf16 v[30:33], v[184:187], v[232:235], v[30:33]
	v_mfma_f32_16x16x32_bf16 v[26:29], v[188:191], v[228:231], v[26:29]
	v_mfma_f32_16x16x32_bf16 v[26:29], v[192:195], v[232:235], v[26:29]
	v_mfma_f32_16x16x32_bf16 v[14:17], v[144:147], v[236:239], v[14:17]
	v_mfma_f32_16x16x32_bf16 v[14:17], v[184:187], v[240:243], v[14:17]
	v_mfma_f32_16x16x32_bf16 v[10:13], v[188:191], v[236:239], v[10:13]
	v_mfma_f32_16x16x32_bf16 v[10:13], v[192:195], v[240:243], v[10:13]
	v_mfma_f32_16x16x32_bf16 v[54:57], v[196:199], v[212:215], v[54:57]
	v_mfma_f32_16x16x32_bf16 v[54:57], v[200:203], v[216:219], v[54:57]
	v_mfma_f32_16x16x32_bf16 v[50:53], v[204:207], v[212:215], v[50:53]
	v_mfma_f32_16x16x32_bf16 v[50:53], v[208:211], v[216:219], v[50:53]
	v_mfma_f32_16x16x32_bf16 v[38:41], v[196:199], v[220:223], v[38:41]
	v_mfma_f32_16x16x32_bf16 v[38:41], v[200:203], v[224:227], v[38:41]
	v_mfma_f32_16x16x32_bf16 v[34:37], v[204:207], v[220:223], v[34:37]
	v_mfma_f32_16x16x32_bf16 v[34:37], v[208:211], v[224:227], v[34:37]
	v_mfma_f32_16x16x32_bf16 v[22:25], v[196:199], v[228:231], v[22:25]
	v_mfma_f32_16x16x32_bf16 v[22:25], v[200:203], v[232:235], v[22:25]
	v_mfma_f32_16x16x32_bf16 v[18:21], v[204:207], v[228:231], v[18:21]
	v_mfma_f32_16x16x32_bf16 v[18:21], v[208:211], v[232:235], v[18:21]
	s_barrier
	s_setprio 2
	v_mfma_f32_16x16x32_bf16 v[6:9], v[196:199], v[236:239], v[6:9]
	v_mfma_f32_16x16x32_bf16 v[6:9], v[200:203], v[240:243], v[6:9]
	v_mfma_f32_16x16x32_bf16 v[2:5], v[204:207], v[236:239], v[2:5]
	v_mfma_f32_16x16x32_bf16 v[2:5], v[208:211], v[240:243], v[2:5]
	s_setprio 0
	s_add_i32 s71, 0, 0x18000
	v_add_u32_e32 v133, s71, v149
	s_add_i32 s73, 0, 0x1c000
	ds_read_b128 v[144:147], v133
	ds_read_b128 v[184:187], v133 offset:1024
	ds_read_b128 v[188:191], v133 offset:2048
	ds_read_b128 v[192:195], v133 offset:3072
	v_add_u32_e32 v133, s73, v149
	ds_read_b128 v[196:199], v133
	ds_read_b128 v[200:203], v133 offset:1024
	ds_read_b128 v[204:207], v133 offset:2048
	ds_read_b128 v[208:211], v133 offset:3072
	s_mov_b32 m0, s55
	v_lshl_add_u64 v[248:249], v[246:247], 0, s[14:15]
	ds_read_b128 v[212:215], v170 offset:32768
	ds_read_b128 v[216:219], v170 offset:33792
	ds_read_b128 v[220:223], v170 offset:34816
	ds_read_b128 v[224:227], v170 offset:35840
	ds_read_b128 v[228:231], v170 offset:36864
	ds_read_b128 v[232:235], v170 offset:37888
	ds_read_b128 v[236:239], v170 offset:38912
	ds_read_b128 v[240:243], v170 offset:39936
	global_load_lds_dwordx4 v[248:249], off
	v_lshl_add_u64 v[248:249], v[246:247], 0, s[18:19]
	s_mov_b32 m0, s56
	s_nop 0
	global_load_lds_dwordx4 v[248:249], off
	s_waitcnt vmcnt(8)
	s_waitcnt lgkmcnt(0)
	s_barrier
	s_setprio 1
	s_waitcnt lgkmcnt(0)
	v_mfma_f32_16x16x32_bf16 v[126:129], v[144:147], v[212:215], v[126:129]
	v_mfma_f32_16x16x32_bf16 v[126:129], v[184:187], v[216:219], v[126:129]
	v_mfma_f32_16x16x32_bf16 v[122:125], v[188:191], v[212:215], v[122:125]
	v_mfma_f32_16x16x32_bf16 v[122:125], v[192:195], v[216:219], v[122:125]
	v_mfma_f32_16x16x32_bf16 v[110:113], v[144:147], v[220:223], v[110:113]
	v_mfma_f32_16x16x32_bf16 v[110:113], v[184:187], v[224:227], v[110:113]
	v_mfma_f32_16x16x32_bf16 v[106:109], v[188:191], v[220:223], v[106:109]
	v_mfma_f32_16x16x32_bf16 v[106:109], v[192:195], v[224:227], v[106:109]
	v_mfma_f32_16x16x32_bf16 v[94:97], v[144:147], v[228:231], v[94:97]
	v_mfma_f32_16x16x32_bf16 v[94:97], v[184:187], v[232:235], v[94:97]
	v_mfma_f32_16x16x32_bf16 v[90:93], v[188:191], v[228:231], v[90:93]
	v_mfma_f32_16x16x32_bf16 v[90:93], v[192:195], v[232:235], v[90:93]
	v_mfma_f32_16x16x32_bf16 v[78:81], v[144:147], v[236:239], v[78:81]
	v_mfma_f32_16x16x32_bf16 v[78:81], v[184:187], v[240:243], v[78:81]
	v_mfma_f32_16x16x32_bf16 v[74:77], v[188:191], v[236:239], v[74:77]
	v_mfma_f32_16x16x32_bf16 v[74:77], v[192:195], v[240:243], v[74:77]
	v_mfma_f32_16x16x32_bf16 v[118:121], v[196:199], v[212:215], v[118:121]
	v_mfma_f32_16x16x32_bf16 v[118:121], v[200:203], v[216:219], v[118:121]
	v_mfma_f32_16x16x32_bf16 v[114:117], v[204:207], v[212:215], v[114:117]
	v_mfma_f32_16x16x32_bf16 v[114:117], v[208:211], v[216:219], v[114:117]
	v_mfma_f32_16x16x32_bf16 v[102:105], v[196:199], v[220:223], v[102:105]
	v_mfma_f32_16x16x32_bf16 v[102:105], v[200:203], v[224:227], v[102:105]
	v_mfma_f32_16x16x32_bf16 v[98:101], v[204:207], v[220:223], v[98:101]
	v_mfma_f32_16x16x32_bf16 v[98:101], v[208:211], v[224:227], v[98:101]
	v_mfma_f32_16x16x32_bf16 v[86:89], v[196:199], v[228:231], v[86:89]
	v_mfma_f32_16x16x32_bf16 v[86:89], v[200:203], v[232:235], v[86:89]
	v_mfma_f32_16x16x32_bf16 v[82:85], v[204:207], v[228:231], v[82:85]
	v_mfma_f32_16x16x32_bf16 v[82:85], v[208:211], v[232:235], v[82:85]
	s_barrier
; #define PG8_STAGE(bufoff, gbase, voff) do { if constexpr (!pg8_noload<Epi>::value) { _Pragma("unroll") for (int _i = 0; _i < 2; ++_i) \
;         __builtin_amdgcn_global_load_lds((const unsigned*)((const char*)(gbase) + (size_t)_i * pstep + (voff)[0]), (PG8_LAS unsigned*)(lds + (bufoff) + ldsw + _i * 8192), 16, 0, 0); } } while (0)
; #define PG8_LDA(dst, b, h) do { _Pragma("unroll") for (int m = 0; m < 4; ++m) _Pragma("unroll") for (int k = 0; k < 2; ++k) dst[m][k] = *(const PG8_LAS bf16x8*)(lds + PG8_SA(b, h) + aoff + m * 2048 + k * 1024); } while (0)
; #define PG8_LDB(dst, b, h) do { _Pragma("unroll") for (int n = 0; n < 2; ++n) _Pragma("unroll") for (int k = 0; k < 2; ++k) dst[n][k] = *(const PG8_LAS bf16x8*)(lds + PG8_SB(b, h) + boff + n * 2048 + k * 1024); } while (0)
; #define PG8_MMA(ai, bj, At, Bt) do { __builtin_amdgcn_s_setprio(1); _Pragma("unroll") for (int m = 0; m < 4; ++m) _Pragma("unroll") for (int n = 0; n < 2; ++n) _Pragma("unroll") for (int k = 0; k < 2; ++k) \
;         acc[ai][bj][m][n] = __builtin_amdgcn_mfma_f32_16x16x32_bf16(Bt[n][k], At[m][k], acc[ai][bj][m][n], 0, 0, 0); __builtin_amdgcn_s_setprio(0); } while (0)
; #define PG8_WAIT_V(n) asm volatile("s_waitcnt vmcnt(" #n ")" ::: "memory")
; #define PG8_WAIT_L(n) asm volatile("s_waitcnt lgkmcnt(" #n ")" ::: "memory")
; #define PG8_BAR __builtin_amdgcn_s_barrier()
; #define PG8_SCHED __builtin_amdgcn_sched_barrier(0)
; template <class Epi, class Sched, bool ALIGN_EPI = false, bool SP2 = false, bool ABLK = false>
; __device__ __forceinline__ void gemm_phase(PG8_LAS unsigned char* lds, const Gemm g, const Sched& S, const Epi& E) {
;     ...
;             PG8_WAIT_V(8); PG8_WAIT_L(0); PG8_BAR; PG8_MMA(1, 0, At, B0); PG8_MMA(1, 1, At, B1); PG8_BAR; PG8_SCHED;
;             PG8_LDB(B0, 1, 0); PG8_LDB(B1, 1, 1); PG8_SCHED; PG8_LDA(At, 1, 0); PG8_STAGE(PG8_SA(0, 1), a2 + hstep, voffA);
;             PG8_WAIT_V(8); PG8_WAIT_L(0); PG8_BAR; PG8_MMA(0, 0, At, B0); PG8_MMA(0, 1, At, B1); PG8_BAR; PG8_SCHED;
;             PG8_LDA(At, 1, 1); PG8_STAGE(PG8_SB(1, 0), b3, voffB); PG8_STAGE(PG8_SB(1, 1), b3 + hstep, voffB); PG8_STAGE(PG8_SA(1, 0), a3, voffA);
;             PG8_WAIT_V(8); PG8_WAIT_L(0); PG8_BAR; PG8_MMA(1, 0, At, B0); PG8_MMA(1, 1, At, B1); PG8_BAR; PG8_SCHED;
	s_setprio 2
	v_mfma_f32_16x16x32_bf16 v[70:73], v[196:199], v[236:239], v[70:73]
	v_mfma_f32_16x16x32_bf16 v[70:73], v[200:203], v[240:243], v[70:73]
	v_mfma_f32_16x16x32_bf16 v[66:69], v[204:207], v[236:239], v[66:69]
	v_mfma_f32_16x16x32_bf16 v[66:69], v[208:211], v[240:243], v[66:69]
	s_setprio 0
	s_add_i32 s71, s71, s52
	v_lshl_add_u64 v[248:249], v[244:245], 0, s[28:29]
	s_mov_b32 m0, s71
	ds_read_b128 v[212:215], v170 offset:49152
	ds_read_b128 v[216:219], v170 offset:50176
	ds_read_b128 v[220:223], v170 offset:51200
	ds_read_b128 v[224:227], v170 offset:52224
	ds_read_b128 v[228:231], v170 offset:53248
	ds_read_b128 v[232:235], v170 offset:54272
	ds_read_b128 v[236:239], v170 offset:55296
	ds_read_b128 v[240:243], v170 offset:56320
	global_load_lds_dwordx4 v[248:249], off
	v_lshl_add_u64 v[248:249], v[244:245], 0, s[30:31]
	s_add_i32 m0, s71, 0x2000
	s_add_i32 s71, s73, s52
	global_load_lds_dwordx4 v[248:249], off
	v_lshl_add_u64 v[248:249], v[244:245], 0, s[34:35]
	s_mov_b32 m0, s71
	v_lshl_add_u64 v[244:245], v[244:245], 0, s[36:37]
	global_load_lds_dwordx4 v[248:249], off
	s_add_i32 m0, s71, 0x2000
	s_nop 0
	global_load_lds_dwordx4 v[244:245], off
	v_lshl_add_u64 v[244:245], v[246:247], 0, s[28:29]
	s_mov_b32 m0, s59
	s_nop 0
	global_load_lds_dwordx4 v[244:245], off
	v_lshl_add_u64 v[244:245], v[246:247], 0, s[30:31]
	s_mov_b32 m0, s60
	s_nop 0
	global_load_lds_dwordx4 v[244:245], off
	s_waitcnt vmcnt(8)
	s_waitcnt lgkmcnt(0)
	s_barrier
	s_setprio 1
	s_waitcnt lgkmcnt(0)
	v_mfma_f32_16x16x32_bf16 v[62:65], v[144:147], v[212:215], v[62:65]
	v_mfma_f32_16x16x32_bf16 v[62:65], v[184:187], v[216:219], v[62:65]
	v_mfma_f32_16x16x32_bf16 v[58:61], v[188:191], v[212:215], v[58:61]
	v_mfma_f32_16x16x32_bf16 v[58:61], v[192:195], v[216:219], v[58:61]
	v_mfma_f32_16x16x32_bf16 v[46:49], v[144:147], v[220:223], v[46:49]
	v_mfma_f32_16x16x32_bf16 v[46:49], v[184:187], v[224:227], v[46:49]
	v_mfma_f32_16x16x32_bf16 v[42:45], v[188:191], v[220:223], v[42:45]
	v_mfma_f32_16x16x32_bf16 v[42:45], v[192:195], v[224:227], v[42:45]
	v_mfma_f32_16x16x32_bf16 v[30:33], v[144:147], v[228:231], v[30:33]
	v_mfma_f32_16x16x32_bf16 v[30:33], v[184:187], v[232:235], v[30:33]
	v_mfma_f32_16x16x32_bf16 v[26:29], v[188:191], v[228:231], v[26:29]
	v_mfma_f32_16x16x32_bf16 v[26:29], v[192:195], v[232:235], v[26:29]
	v_mfma_f32_16x16x32_bf16 v[14:17], v[144:147], v[236:239], v[14:17]
	v_mfma_f32_16x16x32_bf16 v[14:17], v[184:187], v[240:243], v[14:17]
	v_mfma_f32_16x16x32_bf16 v[10:13], v[188:191], v[236:239], v[10:13]
	v_mfma_f32_16x16x32_bf16 v[10:13], v[192:195], v[240:243], v[10:13]
	v_mfma_f32_16x16x32_bf16 v[54:57], v[196:199], v[212:215], v[54:57]
	v_mfma_f32_16x16x32_bf16 v[54:57], v[200:203], v[216:219], v[54:57]
	v_mfma_f32_16x16x32_bf16 v[50:53], v[204:207], v[212:215], v[50:53]
	v_mfma_f32_16x16x32_bf16 v[50:53], v[208:211], v[216:219], v[50:53]
	v_mfma_f32_16x16x32_bf16 v[38:41], v[196:199], v[220:223], v[38:41]
	v_mfma_f32_16x16x32_bf16 v[38:41], v[200:203], v[224:227], v[38:41]
	v_mfma_f32_16x16x32_bf16 v[34:37], v[204:207], v[220:223], v[34:37]
	v_mfma_f32_16x16x32_bf16 v[34:37], v[208:211], v[224:227], v[34:37]
	v_mfma_f32_16x16x32_bf16 v[22:25], v[196:199], v[228:231], v[22:25]
	v_mfma_f32_16x16x32_bf16 v[22:25], v[200:203], v[232:235], v[22:25]
	v_mfma_f32_16x16x32_bf16 v[18:21], v[204:207], v[228:231], v[18:21]
	v_mfma_f32_16x16x32_bf16 v[18:21], v[208:211], v[232:235], v[18:21]
	s_barrier
	s_setprio 2
	v_mfma_f32_16x16x32_bf16 v[6:9], v[196:199], v[236:239], v[6:9]
	v_mfma_f32_16x16x32_bf16 v[6:9], v[200:203], v[240:243], v[6:9]
	v_mfma_f32_16x16x32_bf16 v[2:5], v[204:207], v[236:239], v[2:5]
	v_mfma_f32_16x16x32_bf16 v[2:5], v[208:211], v[240:243], v[2:5]
	s_setprio 0
	s_add_i32 s70, s70, 2
	s_add_u32 vcc_lo, vcc_lo, 0x1000
	s_addc_u32 vcc_hi, vcc_hi, 0
	s_add_u32 s16, s16, 0x1000
	s_addc_u32 s17, s17, 0
	s_cmp_gt_u32 s70, 29
	s_cbranch_scc0 .LBB0_114
	s_and_b64 vcc, exec, s[38:39]
	s_cbranch_vccz .LBB0_117
	s_barrier

; #define PG8_STAGE(bufoff, gbase, voff) do { if constexpr (!pg8_noload<Epi>::value) { _Pragma("unroll") for (int _i = 0; _i < 2; ++_i) \
;         __builtin_amdgcn_global_load_lds((const unsigned*)((const char*)(gbase) + (size_t)_i * pstep + (voff)[0]), (PG8_LAS unsigned*)(lds + (bufoff) + ldsw + _i * 8192), 16, 0, 0); } } while (0)
; #define PG8_LDA(dst, b, h) do { _Pragma("unroll") for (int m = 0; m < 4; ++m) _Pragma("unroll") for (int k = 0; k < 2; ++k) dst[m][k] = *(const PG8_LAS bf16x8*)(lds + PG8_SA(b, h) + aoff + m * 2048 + k * 1024); } while (0)
; #define PG8_LDB(dst, b, h) do { _Pragma("unroll") for (int n = 0; n < 2; ++n) _Pragma("unroll") for (int k = 0; k < 2; ++k) dst[n][k] = *(const PG8_LAS bf16x8*)(lds + PG8_SB(b, h) + boff + n * 2048 + k * 1024); } while (0)
; #define PG8_MMA(ai, bj, At, Bt) do { __builtin_amdgcn_s_setprio(1); _Pragma("unroll") for (int m = 0; m < 4; ++m) _Pragma("unroll") for (int n = 0; n < 2; ++n) _Pragma("unroll") for (int k = 0; k < 2; ++k) \
;         acc[ai][bj][m][n] = __builtin_amdgcn_mfma_f32_16x16x32_bf16(Bt[n][k], At[m][k], acc[ai][bj][m][n], 0, 0, 0); __builtin_amdgcn_s_setprio(0); } while (0)
; #define PG8_WAIT_V(n) asm volatile("s_waitcnt vmcnt(" #n ")" ::: "memory")
; #define PG8_WAIT_L(n) asm volatile("s_waitcnt lgkmcnt(" #n ")" ::: "memory")
; template <class Epi, class Sched, bool ALIGN_EPI = false, bool SP2 = false, bool ABLK = false>
; __device__ __forceinline__ void gemm_phase(PG8_LAS unsigned char* lds, const Gemm g, const Sched& S, const Epi& E) {
;     ...
;             const char* a1 = cA + (size_t)(t + 1) * kstep;
;             const char* a2 = last ? nA : cA + (size_t)(t + 2) * kstep; const char* b2 = last ? nB : cB + (size_t)(t + 2) * kstepB;
;             const char* a3 = a2 + kstep; const char* b3 = b2 + kstepB;
;             if (last && has_next) S.a_ready(nxt);
;             if constexpr (SP2) {
;             PG8_LDB(B0, 0, 0); PG8_LDB(B1, 0, 1); PG8_SCHED; PG8_LDA(At, 0, 0); PG8_STAGE(PG8_SA(1, 1), a1 + hstep, voffA);
;             PG8_WAIT_V(8); PG8_WAIT_L(0); PG8_BAR; PG8_MMA(0, 0, At, B0); PG8_MMA(0, 1, At, B1); PG8_BAR; PG8_SCHED;
;             PG8_LDA(At, 0, 1); PG8_STAGE(PG8_SB(0, 0), b2, voffB); PG8_STAGE(PG8_SB(0, 1), b2 + hstep, voffB); PG8_STAGE(PG8_SA(0, 0), a2, voffA);
;             PG8_WAIT_V(8); PG8_WAIT_L(0); PG8_BAR; PG8_MMA(1, 0, At, B0); PG8_MMA(1, 1, At, B1); PG8_BAR; PG8_SCHED;
.LBB0_487:
	ds_read_b128 v[114:117], v167
	ds_read_b128 v[126:129], v167 offset:1024
	ds_read_b128 v[130:133], v167 offset:2048
	ds_read_b128 v[142:145], v167 offset:3072
	ds_read_b128 v[146:149], v168
	ds_read_b128 v[150:153], v168 offset:1024
	ds_read_b128 v[174:177], v168 offset:2048
	ds_read_b128 v[178:181], v168 offset:3072
	s_add_i32 s65, s39, 2
	s_add_u32 s68, s92, 0xfff00800
	s_addc_u32 s69, s93, -1
	s_cmp_eq_u32 s3, s39
	s_cselect_b32 s69, s79, s69
	s_cselect_b32 s68, s78, s68
	s_cselect_b32 s71, s89, s37
	s_cselect_b32 s70, s88, s11
	v_lshl_add_u64 v[162:163], s[92:93], 0, v[158:159]
	s_add_i32 m0, s56, 0xc000
	ds_read_b128 v[184:187], v169
	ds_read_b128 v[188:191], v169 offset:1024
	ds_read_b128 v[192:195], v169 offset:2048
	ds_read_b128 v[196:199], v169 offset:3072
	ds_read_b128 v[200:203], v169 offset:4096
	ds_read_b128 v[204:207], v169 offset:5120
	ds_read_b128 v[208:211], v169 offset:6144
	ds_read_b128 v[212:215], v169 offset:7168
	global_load_lds_dwordx4 v[162:163], off
	v_lshl_add_u64 v[162:163], v[162:163], 0, s[12:13]
	s_add_i32 m0, s56, 0xe000
	s_nop 0
	global_load_lds_dwordx4 v[162:163], off
	s_waitcnt vmcnt(8)
	s_waitcnt lgkmcnt(0)
	s_barrier
	s_setprio 1
	s_waitcnt lgkmcnt(0)
	v_mfma_f32_16x16x32_bf16 v[138:141], v[114:117], v[184:187], v[138:141]
	v_mfma_f32_16x16x32_bf16 v[138:141], v[126:129], v[188:191], v[138:141]
	v_mfma_f32_16x16x32_bf16 v[134:137], v[130:133], v[184:187], v[134:137]
	v_mfma_f32_16x16x32_bf16 v[134:137], v[142:145], v[188:191], v[134:137]
	v_mfma_f32_16x16x32_bf16 v[110:113], v[114:117], v[192:195], v[110:113]
	v_mfma_f32_16x16x32_bf16 v[110:113], v[126:129], v[196:199], v[110:113]
	v_mfma_f32_16x16x32_bf16 v[106:109], v[130:133], v[192:195], v[106:109]
	v_mfma_f32_16x16x32_bf16 v[106:109], v[142:145], v[196:199], v[106:109]
	v_mfma_f32_16x16x32_bf16 v[94:97], v[114:117], v[200:203], v[94:97]
	v_mfma_f32_16x16x32_bf16 v[94:97], v[126:129], v[204:207], v[94:97]
	v_mfma_f32_16x16x32_bf16 v[90:93], v[130:133], v[200:203], v[90:93]
	v_mfma_f32_16x16x32_bf16 v[90:93], v[142:145], v[204:207], v[90:93]
	v_mfma_f32_16x16x32_bf16 v[78:81], v[114:117], v[208:211], v[78:81]
	v_mfma_f32_16x16x32_bf16 v[78:81], v[126:129], v[212:215], v[78:81]
	v_mfma_f32_16x16x32_bf16 v[74:77], v[130:133], v[208:211], v[74:77]
	v_mfma_f32_16x16x32_bf16 v[74:77], v[142:145], v[212:215], v[74:77]
	v_mfma_f32_16x16x32_bf16 v[122:125], v[146:149], v[184:187], v[122:125]
	v_mfma_f32_16x16x32_bf16 v[122:125], v[150:153], v[188:191], v[122:125]
	v_mfma_f32_16x16x32_bf16 v[118:121], v[174:177], v[184:187], v[118:121]
	v_mfma_f32_16x16x32_bf16 v[118:121], v[178:181], v[188:191], v[118:121]
	v_mfma_f32_16x16x32_bf16 v[102:105], v[146:149], v[192:195], v[102:105]
	v_mfma_f32_16x16x32_bf16 v[102:105], v[150:153], v[196:199], v[102:105]
	v_mfma_f32_16x16x32_bf16 v[98:101], v[174:177], v[192:195], v[98:101]
	v_mfma_f32_16x16x32_bf16 v[98:101], v[178:181], v[196:199], v[98:101]
	v_mfma_f32_16x16x32_bf16 v[86:89], v[146:149], v[200:203], v[86:89]
	v_mfma_f32_16x16x32_bf16 v[86:89], v[150:153], v[204:207], v[86:89]
	v_mfma_f32_16x16x32_bf16 v[82:85], v[174:177], v[200:203], v[82:85]
	v_mfma_f32_16x16x32_bf16 v[82:85], v[178:181], v[204:207], v[82:85]
	s_barrier
	s_setprio 2
	v_mfma_f32_16x16x32_bf16 v[70:73], v[146:149], v[208:211], v[70:73]
	v_mfma_f32_16x16x32_bf16 v[70:73], v[150:153], v[212:215], v[70:73]
	v_mfma_f32_16x16x32_bf16 v[66:69], v[174:177], v[208:211], v[66:69]
	v_mfma_f32_16x16x32_bf16 v[66:69], v[178:181], v[212:215], v[66:69]
	s_setprio 0
	s_add_i32 s39, s73, s55
	v_lshl_add_u64 v[162:163], s[70:71], 0, v[154:155]
	s_mov_b32 m0, s39
	ds_read_b128 v[184:187], v169 offset:16384
	ds_read_b128 v[188:191], v169 offset:17408
	ds_read_b128 v[192:195], v169 offset:18432
	ds_read_b128 v[196:199], v169 offset:19456
	ds_read_b128 v[200:203], v169 offset:20480
	ds_read_b128 v[204:207], v169 offset:21504
	ds_read_b128 v[208:211], v169 offset:22528
	ds_read_b128 v[212:215], v169 offset:23552
	global_load_lds_dwordx4 v[162:163], off
	v_lshl_add_u64 v[216:217], v[162:163], 0, s[12:13]
	s_add_i32 m0, s39, 0x2000
	s_add_i32 s39, s74, s55
	global_load_lds_dwordx4 v[216:217], off
	v_lshl_add_u64 v[216:217], v[162:163], 0, s[14:15]
	s_mov_b32 m0, s39
	s_nop 0
	global_load_lds_dwordx4 v[216:217], off
	v_lshl_add_u64 v[216:217], v[162:163], 0, s[16:17]
	s_add_i32 m0, s39, 0x2000
	s_nop 0
	global_load_lds_dwordx4 v[216:217], off
	v_lshl_add_u64 v[216:217], s[68:69], 0, v[154:155]
	s_mov_b32 m0, s56
	v_lshl_add_u64 v[218:219], v[216:217], 0, s[12:13]
	global_load_lds_dwordx4 v[216:217], off
	s_mov_b32 m0, s57
	s_nop 0
	global_load_lds_dwordx4 v[218:219], off
	s_waitcnt vmcnt(8)
	s_waitcnt lgkmcnt(0)
	s_barrier
; #define PG8_STAGE(bufoff, gbase, voff) do { if constexpr (!pg8_noload<Epi>::value) { _Pragma("unroll") for (int _i = 0; _i < 2; ++_i) \
;         __builtin_amdgcn_global_load_lds((const unsigned*)((const char*)(gbase) + (size_t)_i * pstep + (voff)[0]), (PG8_LAS unsigned*)(lds + (bufoff) + ldsw + _i * 8192), 16, 0, 0); } } while (0)
; #define PG8_LDA(dst, b, h) do { _Pragma("unroll") for (int m = 0; m < 4; ++m) _Pragma("unroll") for (int k = 0; k < 2; ++k) dst[m][k] = *(const PG8_LAS bf16x8*)(lds + PG8_SA(b, h) + aoff + m * 2048 + k * 1024); } while (0)
; #define PG8_LDB(dst, b, h) do { _Pragma("unroll") for (int n = 0; n < 2; ++n) _Pragma("unroll") for (int k = 0; k < 2; ++k) dst[n][k] = *(const PG8_LAS bf16x8*)(lds + PG8_SB(b, h) + boff + n * 2048 + k * 1024); } while (0)
; #define PG8_MMA(ai, bj, At, Bt) do { __builtin_amdgcn_s_setprio(1); _Pragma("unroll") for (int m = 0; m < 4; ++m) _Pragma("unroll") for (int n = 0; n < 2; ++n) _Pragma("unroll") for (int k = 0; k < 2; ++k) \
;         acc[ai][bj][m][n] = __builtin_amdgcn_mfma_f32_16x16x32_bf16(Bt[n][k], At[m][k], acc[ai][bj][m][n], 0, 0, 0); __builtin_amdgcn_s_setprio(0); } while (0)
; #define PG8_WAIT_V(n) asm volatile("s_waitcnt vmcnt(" #n ")" ::: "memory")
; #define PG8_WAIT_L(n) asm volatile("s_waitcnt lgkmcnt(" #n ")" ::: "memory")
; #define PG8_BAR __builtin_amdgcn_s_barrier()
; #define PG8_SCHED __builtin_amdgcn_sched_barrier(0)
; template <class Epi, class Sched, bool ALIGN_EPI = false, bool SP2 = false, bool ABLK = false>
; __device__ __forceinline__ void gemm_phase(PG8_LAS unsigned char* lds, const Gemm g, const Sched& S, const Epi& E) {
;     ...
;             PG8_WAIT_V(8); PG8_WAIT_L(0); PG8_BAR; PG8_MMA(1, 0, At, B0); PG8_MMA(1, 1, At, B1); PG8_BAR; PG8_SCHED;
;             PG8_LDB(B0, 1, 0); PG8_LDB(B1, 1, 1); PG8_SCHED; PG8_LDA(At, 1, 0); PG8_STAGE(PG8_SA(0, 1), a2 + hstep, voffA);
;             PG8_WAIT_V(8); PG8_WAIT_L(0); PG8_BAR; PG8_MMA(0, 0, At, B0); PG8_MMA(0, 1, At, B1); PG8_BAR; PG8_SCHED;
;             PG8_LDA(At, 1, 1); PG8_STAGE(PG8_SB(1, 0), b3, voffB); PG8_STAGE(PG8_SB(1, 1), b3 + hstep, voffB); PG8_STAGE(PG8_SA(1, 0), a3, voffA);
	s_setprio 1
	s_waitcnt lgkmcnt(0)
	v_mfma_f32_16x16x32_bf16 v[62:65], v[114:117], v[184:187], v[62:65]
	v_mfma_f32_16x16x32_bf16 v[62:65], v[126:129], v[188:191], v[62:65]
	v_mfma_f32_16x16x32_bf16 v[58:61], v[130:133], v[184:187], v[58:61]
	v_mfma_f32_16x16x32_bf16 v[58:61], v[142:145], v[188:191], v[58:61]
	v_mfma_f32_16x16x32_bf16 v[46:49], v[114:117], v[192:195], v[46:49]
	v_mfma_f32_16x16x32_bf16 v[46:49], v[126:129], v[196:199], v[46:49]
	v_mfma_f32_16x16x32_bf16 v[42:45], v[130:133], v[192:195], v[42:45]
	v_mfma_f32_16x16x32_bf16 v[42:45], v[142:145], v[196:199], v[42:45]
	v_mfma_f32_16x16x32_bf16 v[30:33], v[114:117], v[200:203], v[30:33]
	v_mfma_f32_16x16x32_bf16 v[30:33], v[126:129], v[204:207], v[30:33]
	v_mfma_f32_16x16x32_bf16 v[26:29], v[130:133], v[200:203], v[26:29]
	v_mfma_f32_16x16x32_bf16 v[26:29], v[142:145], v[204:207], v[26:29]
	v_mfma_f32_16x16x32_bf16 v[14:17], v[114:117], v[208:211], v[14:17]
	v_mfma_f32_16x16x32_bf16 v[14:17], v[126:129], v[212:215], v[14:17]
	v_mfma_f32_16x16x32_bf16 v[10:13], v[130:133], v[208:211], v[10:13]
	v_mfma_f32_16x16x32_bf16 v[10:13], v[142:145], v[212:215], v[10:13]
	v_mfma_f32_16x16x32_bf16 v[54:57], v[146:149], v[184:187], v[54:57]
	v_mfma_f32_16x16x32_bf16 v[54:57], v[150:153], v[188:191], v[54:57]
	v_mfma_f32_16x16x32_bf16 v[50:53], v[174:177], v[184:187], v[50:53]
	v_mfma_f32_16x16x32_bf16 v[50:53], v[178:181], v[188:191], v[50:53]
	v_mfma_f32_16x16x32_bf16 v[38:41], v[146:149], v[192:195], v[38:41]
	v_mfma_f32_16x16x32_bf16 v[38:41], v[150:153], v[196:199], v[38:41]
	v_mfma_f32_16x16x32_bf16 v[34:37], v[174:177], v[192:195], v[34:37]
	v_mfma_f32_16x16x32_bf16 v[34:37], v[178:181], v[196:199], v[34:37]
	v_mfma_f32_16x16x32_bf16 v[22:25], v[146:149], v[200:203], v[22:25]
	v_mfma_f32_16x16x32_bf16 v[22:25], v[150:153], v[204:207], v[22:25]
	v_mfma_f32_16x16x32_bf16 v[18:21], v[174:177], v[200:203], v[18:21]
	v_mfma_f32_16x16x32_bf16 v[18:21], v[178:181], v[204:207], v[18:21]
	s_barrier
	s_setprio 2
	v_mfma_f32_16x16x32_bf16 v[6:9], v[146:149], v[208:211], v[6:9]
	v_mfma_f32_16x16x32_bf16 v[6:9], v[150:153], v[212:215], v[6:9]
	v_mfma_f32_16x16x32_bf16 v[2:5], v[174:177], v[208:211], v[2:5]
	v_mfma_f32_16x16x32_bf16 v[2:5], v[178:181], v[212:215], v[2:5]
	s_setprio 0
	s_add_i32 s39, 0, 0x18000
	s_add_i32 s68, 0, 0x1c000
	v_add_u32_e32 v142, s39, v1
	v_add_u32_e32 v173, s68, v1
	ds_read_b128 v[114:117], v142
	ds_read_b128 v[126:129], v142 offset:1024
	ds_read_b128 v[130:133], v142 offset:2048
	ds_read_b128 v[142:145], v142 offset:3072
	ds_read_b128 v[146:149], v173
	ds_read_b128 v[150:153], v173 offset:1024
	ds_read_b128 v[174:177], v173 offset:2048
	ds_read_b128 v[178:181], v173 offset:3072
	s_mov_b32 m0, s58
	v_lshl_add_u64 v[218:219], v[216:217], 0, s[14:15]
	ds_read_b128 v[184:187], v169 offset:32768
	ds_read_b128 v[188:191], v169 offset:33792
	ds_read_b128 v[192:195], v169 offset:34816
	ds_read_b128 v[196:199], v169 offset:35840
	ds_read_b128 v[200:203], v169 offset:36864
	ds_read_b128 v[204:207], v169 offset:37888
	ds_read_b128 v[208:211], v169 offset:38912
	ds_read_b128 v[212:215], v169 offset:39936
	global_load_lds_dwordx4 v[218:219], off
	v_lshl_add_u64 v[218:219], v[216:217], 0, s[16:17]
	s_mov_b32 m0, s59
	s_nop 0
	global_load_lds_dwordx4 v[218:219], off
	s_waitcnt vmcnt(8)
	s_waitcnt lgkmcnt(0)
	s_barrier
	s_setprio 1
	s_waitcnt lgkmcnt(0)
	v_mfma_f32_16x16x32_bf16 v[138:141], v[114:117], v[184:187], v[138:141]
	v_mfma_f32_16x16x32_bf16 v[138:141], v[126:129], v[188:191], v[138:141]
	v_mfma_f32_16x16x32_bf16 v[134:137], v[130:133], v[184:187], v[134:137]
	v_mfma_f32_16x16x32_bf16 v[134:137], v[142:145], v[188:191], v[134:137]
	v_mfma_f32_16x16x32_bf16 v[110:113], v[114:117], v[192:195], v[110:113]
	v_mfma_f32_16x16x32_bf16 v[110:113], v[126:129], v[196:199], v[110:113]
	v_mfma_f32_16x16x32_bf16 v[106:109], v[130:133], v[192:195], v[106:109]
	v_mfma_f32_16x16x32_bf16 v[106:109], v[142:145], v[196:199], v[106:109]
	v_mfma_f32_16x16x32_bf16 v[94:97], v[114:117], v[200:203], v[94:97]
	v_mfma_f32_16x16x32_bf16 v[94:97], v[126:129], v[204:207], v[94:97]
	v_mfma_f32_16x16x32_bf16 v[90:93], v[130:133], v[200:203], v[90:93]
	v_mfma_f32_16x16x32_bf16 v[90:93], v[142:145], v[204:207], v[90:93]
	v_mfma_f32_16x16x32_bf16 v[78:81], v[114:117], v[208:211], v[78:81]
	v_mfma_f32_16x16x32_bf16 v[78:81], v[126:129], v[212:215], v[78:81]
	v_mfma_f32_16x16x32_bf16 v[74:77], v[130:133], v[208:211], v[74:77]
	v_mfma_f32_16x16x32_bf16 v[74:77], v[142:145], v[212:215], v[74:77]
	v_mfma_f32_16x16x32_bf16 v[122:125], v[146:149], v[184:187], v[122:125]
	v_mfma_f32_16x16x32_bf16 v[122:125], v[150:153], v[188:191], v[122:125]
	v_mfma_f32_16x16x32_bf16 v[118:121], v[174:177], v[184:187], v[118:121]
	v_mfma_f32_16x16x32_bf16 v[118:121], v[178:181], v[188:191], v[118:121]
	v_mfma_f32_16x16x32_bf16 v[102:105], v[146:149], v[192:195], v[102:105]
	v_mfma_f32_16x16x32_bf16 v[102:105], v[150:153], v[196:199], v[102:105]
	v_mfma_f32_16x16x32_bf16 v[98:101], v[174:177], v[192:195], v[98:101]
	v_mfma_f32_16x16x32_bf16 v[98:101], v[178:181], v[196:199], v[98:101]
	v_mfma_f32_16x16x32_bf16 v[86:89], v[146:149], v[200:203], v[86:89]
	v_mfma_f32_16x16x32_bf16 v[86:89], v[150:153], v[204:207], v[86:89]
	v_mfma_f32_16x16x32_bf16 v[82:85], v[174:177], v[200:203], v[82:85]
	v_mfma_f32_16x16x32_bf16 v[82:85], v[178:181], v[204:207], v[82:85]
	s_barrier
; #define PG8_STAGE(bufoff, gbase, voff) do { if constexpr (!pg8_noload<Epi>::value) { _Pragma("unroll") for (int _i = 0; _i < 2; ++_i) \
;         __builtin_amdgcn_global_load_lds((const unsigned*)((const char*)(gbase) + (size_t)_i * pstep + (voff)[0]), (PG8_LAS unsigned*)(lds + (bufoff) + ldsw + _i * 8192), 16, 0, 0); } } while (0)
; #define PG8_LDA(dst, b, h) do { _Pragma("unroll") for (int m = 0; m < 4; ++m) _Pragma("unroll") for (int k = 0; k < 2; ++k) dst[m][k] = *(const PG8_LAS bf16x8*)(lds + PG8_SA(b, h) + aoff + m * 2048 + k * 1024); } while (0)
; #define PG8_LDB(dst, b, h) do { _Pragma("unroll") for (int n = 0; n < 2; ++n) _Pragma("unroll") for (int k = 0; k < 2; ++k) dst[n][k] = *(const PG8_LAS bf16x8*)(lds + PG8_SB(b, h) + boff + n * 2048 + k * 1024); } while (0)
; #define PG8_MMA(ai, bj, At, Bt) do { __builtin_amdgcn_s_setprio(1); _Pragma("unroll") for (int m = 0; m < 4; ++m) _Pragma("unroll") for (int n = 0; n < 2; ++n) _Pragma("unroll") for (int k = 0; k < 2; ++k) \
;         acc[ai][bj][m][n] = __builtin_amdgcn_mfma_f32_16x16x32_bf16(Bt[n][k], At[m][k], acc[ai][bj][m][n], 0, 0, 0); __builtin_amdgcn_s_setprio(0); } while (0)
; #define PG8_WAIT_V(n) asm volatile("s_waitcnt vmcnt(" #n ")" ::: "memory")
; #define PG8_WAIT_L(n) asm volatile("s_waitcnt lgkmcnt(" #n ")" ::: "memory")
; #define PG8_BAR __builtin_amdgcn_s_barrier()
; #define PG8_SCHED __builtin_amdgcn_sched_barrier(0)
; template <class Epi, class Sched, bool ALIGN_EPI = false, bool SP2 = false, bool ABLK = false>
; __device__ __forceinline__ void gemm_phase(PG8_LAS unsigned char* lds, const Gemm g, const Sched& S, const Epi& E) {
;     ...
;             PG8_WAIT_V(8); PG8_WAIT_L(0); PG8_BAR; PG8_MMA(1, 0, At, B0); PG8_MMA(1, 1, At, B1); PG8_BAR; PG8_SCHED;
;             PG8_LDB(B0, 1, 0); PG8_LDB(B1, 1, 1); PG8_SCHED; PG8_LDA(At, 1, 0); PG8_STAGE(PG8_SA(0, 1), a2 + hstep, voffA);
;             PG8_WAIT_V(8); PG8_WAIT_L(0); PG8_BAR; PG8_MMA(0, 0, At, B0); PG8_MMA(0, 1, At, B1); PG8_BAR; PG8_SCHED;
;             PG8_LDA(At, 1, 1); PG8_STAGE(PG8_SB(1, 0), b3, voffB); PG8_STAGE(PG8_SB(1, 1), b3 + hstep, voffB); PG8_STAGE(PG8_SA(1, 0), a3, voffA);
;             PG8_WAIT_V(8); PG8_WAIT_L(0); PG8_BAR; PG8_MMA(1, 0, At, B0); PG8_MMA(1, 1, At, B1); PG8_BAR; PG8_SCHED;
	s_setprio 2
	v_mfma_f32_16x16x32_bf16 v[70:73], v[146:149], v[208:211], v[70:73]
	v_mfma_f32_16x16x32_bf16 v[70:73], v[150:153], v[212:215], v[70:73]
	v_mfma_f32_16x16x32_bf16 v[66:69], v[174:177], v[208:211], v[66:69]
	v_mfma_f32_16x16x32_bf16 v[66:69], v[178:181], v[212:215], v[66:69]
	s_setprio 0
	s_add_i32 s39, s39, s55
	v_lshl_add_u64 v[218:219], v[162:163], 0, s[24:25]
	s_mov_b32 m0, s39
	ds_read_b128 v[184:187], v169 offset:49152
	ds_read_b128 v[188:191], v169 offset:50176
	ds_read_b128 v[192:195], v169 offset:51200
	ds_read_b128 v[196:199], v169 offset:52224
	ds_read_b128 v[200:203], v169 offset:53248
	ds_read_b128 v[204:207], v169 offset:54272
	ds_read_b128 v[208:211], v169 offset:55296
	ds_read_b128 v[212:215], v169 offset:56320
	global_load_lds_dwordx4 v[218:219], off
	v_lshl_add_u64 v[218:219], v[162:163], 0, s[26:27]
	s_add_i32 m0, s39, 0x2000
	s_add_i32 s39, s68, s55
	global_load_lds_dwordx4 v[218:219], off
	v_lshl_add_u64 v[218:219], v[162:163], 0, s[28:29]
	s_mov_b32 m0, s39
	v_lshl_add_u64 v[162:163], v[162:163], 0, s[30:31]
	global_load_lds_dwordx4 v[218:219], off
	s_add_i32 m0, s39, 0x2000
	s_nop 0
	global_load_lds_dwordx4 v[162:163], off
	v_lshl_add_u64 v[162:163], v[216:217], 0, s[24:25]
	s_mov_b32 m0, s62
	s_nop 0
	global_load_lds_dwordx4 v[162:163], off
	v_lshl_add_u64 v[162:163], v[216:217], 0, s[26:27]
	s_mov_b32 m0, s63
	s_nop 0
	global_load_lds_dwordx4 v[162:163], off
	s_waitcnt vmcnt(8)
	s_waitcnt lgkmcnt(0)
	s_barrier
	s_setprio 1
	s_waitcnt lgkmcnt(0)
	v_mfma_f32_16x16x32_bf16 v[62:65], v[114:117], v[184:187], v[62:65]
	v_mfma_f32_16x16x32_bf16 v[62:65], v[126:129], v[188:191], v[62:65]
	v_mfma_f32_16x16x32_bf16 v[58:61], v[130:133], v[184:187], v[58:61]
	v_mfma_f32_16x16x32_bf16 v[58:61], v[142:145], v[188:191], v[58:61]
	v_mfma_f32_16x16x32_bf16 v[46:49], v[114:117], v[192:195], v[46:49]
	v_mfma_f32_16x16x32_bf16 v[46:49], v[126:129], v[196:199], v[46:49]
	v_mfma_f32_16x16x32_bf16 v[42:45], v[130:133], v[192:195], v[42:45]
	v_mfma_f32_16x16x32_bf16 v[42:45], v[142:145], v[196:199], v[42:45]
	v_mfma_f32_16x16x32_bf16 v[30:33], v[114:117], v[200:203], v[30:33]
	v_mfma_f32_16x16x32_bf16 v[30:33], v[126:129], v[204:207], v[30:33]
	v_mfma_f32_16x16x32_bf16 v[26:29], v[130:133], v[200:203], v[26:29]
	v_mfma_f32_16x16x32_bf16 v[26:29], v[142:145], v[204:207], v[26:29]
	v_mfma_f32_16x16x32_bf16 v[14:17], v[114:117], v[208:211], v[14:17]
	v_mfma_f32_16x16x32_bf16 v[14:17], v[126:129], v[212:215], v[14:17]
	v_mfma_f32_16x16x32_bf16 v[10:13], v[130:133], v[208:211], v[10:13]
	v_mfma_f32_16x16x32_bf16 v[10:13], v[142:145], v[212:215], v[10:13]
	v_mfma_f32_16x16x32_bf16 v[54:57], v[146:149], v[184:187], v[54:57]
	v_mfma_f32_16x16x32_bf16 v[54:57], v[150:153], v[188:191], v[54:57]
	v_mfma_f32_16x16x32_bf16 v[50:53], v[174:177], v[184:187], v[50:53]
	v_mfma_f32_16x16x32_bf16 v[50:53], v[178:181], v[188:191], v[50:53]
	v_mfma_f32_16x16x32_bf16 v[38:41], v[146:149], v[192:195], v[38:41]
	v_mfma_f32_16x16x32_bf16 v[38:41], v[150:153], v[196:199], v[38:41]
	v_mfma_f32_16x16x32_bf16 v[34:37], v[174:177], v[192:195], v[34:37]
	v_mfma_f32_16x16x32_bf16 v[34:37], v[178:181], v[196:199], v[34:37]
	v_mfma_f32_16x16x32_bf16 v[22:25], v[146:149], v[200:203], v[22:25]
	v_mfma_f32_16x16x32_bf16 v[22:25], v[150:153], v[204:207], v[22:25]
	v_mfma_f32_16x16x32_bf16 v[18:21], v[174:177], v[200:203], v[18:21]
	v_mfma_f32_16x16x32_bf16 v[18:21], v[178:181], v[204:207], v[18:21]
	s_barrier
	s_setprio 2
	v_mfma_f32_16x16x32_bf16 v[6:9], v[146:149], v[208:211], v[6:9]
	v_mfma_f32_16x16x32_bf16 v[6:9], v[150:153], v[212:215], v[6:9]
	v_mfma_f32_16x16x32_bf16 v[2:5], v[174:177], v[208:211], v[2:5]
	v_mfma_f32_16x16x32_bf16 v[2:5], v[178:181], v[212:215], v[2:5]
	s_setprio 0
	s_add_u32 s92, s92, 0x1000
	s_addc_u32 s93, s93, 0
	s_add_u32 s11, s11, 0x1000
	s_addc_u32 s37, s37, 0
	s_cmp_ge_i32 s65, s80
	s_mov_b32 s39, s65
	s_cbranch_scc0 .LBB0_487
	s_and_b64 vcc, exec, s[34:35]
	s_cbranch_vccnz .LBB0_492
	s_lshl_b32 s11, s2, 8
	s_cmp_gt_i32 s2, 63
	s_mov_b64 s[68:69], -1
	s_cbranch_scc1 .LBB0_493

; #define PG8_STAGE(bufoff, gbase, voff) do { if constexpr (!pg8_noload<Epi>::value) { _Pragma("unroll") for (int _i = 0; _i < 2; ++_i) \
;         __builtin_amdgcn_global_load_lds((const unsigned*)((const char*)(gbase) + (size_t)_i * pstep + (voff)[0]), (PG8_LAS unsigned*)(lds + (bufoff) + ldsw + _i * 8192), 16, 0, 0); } } while (0)
; #define PG8_LDA(dst, b, h) do { _Pragma("unroll") for (int m = 0; m < 4; ++m) _Pragma("unroll") for (int k = 0; k < 2; ++k) dst[m][k] = *(const PG8_LAS bf16x8*)(lds + PG8_SA(b, h) + aoff + m * 2048 + k * 1024); } while (0)
; #define PG8_LDB(dst, b, h) do { _Pragma("unroll") for (int n = 0; n < 2; ++n) _Pragma("unroll") for (int k = 0; k < 2; ++k) dst[n][k] = *(const PG8_LAS bf16x8*)(lds + PG8_SB(b, h) + boff + n * 2048 + k * 1024); } while (0)
; #define PG8_MMA(ai, bj, At, Bt) do { __builtin_amdgcn_s_setprio(1); _Pragma("unroll") for (int m = 0; m < 4; ++m) _Pragma("unroll") for (int n = 0; n < 2; ++n) _Pragma("unroll") for (int k = 0; k < 2; ++k) \
;         acc[ai][bj][m][n] = __builtin_amdgcn_mfma_f32_16x16x32_bf16(Bt[n][k], At[m][k], acc[ai][bj][m][n], 0, 0, 0); __builtin_amdgcn_s_setprio(0); } while (0)
; #define PG8_WAIT_V(n) asm volatile("s_waitcnt vmcnt(" #n ")" ::: "memory")
; #define PG8_WAIT_L(n) asm volatile("s_waitcnt lgkmcnt(" #n ")" ::: "memory")
; template <class Epi, class Sched, bool ALIGN_EPI = false, bool SP2 = false, bool ABLK = false>
; __device__ __forceinline__ void gemm_phase(PG8_LAS unsigned char* lds, const Gemm g, const Sched& S, const Epi& E) {
;     ...
;             const char* a1 = cA + (size_t)(t + 1) * kstep;
;             const char* a2 = last ? nA : cA + (size_t)(t + 2) * kstep; const char* b2 = last ? nB : cB + (size_t)(t + 2) * kstepB;
;             const char* a3 = a2 + kstep; const char* b3 = b2 + kstepB;
;             if (last && has_next) S.a_ready(nxt);
;             if constexpr (SP2) {
;             PG8_LDB(B0, 0, 0); PG8_LDB(B1, 0, 1); PG8_SCHED; PG8_LDA(At, 0, 0); PG8_STAGE(PG8_SA(1, 1), a1 + hstep, voffA);
;             PG8_WAIT_V(8); PG8_WAIT_L(0); PG8_BAR; PG8_MMA(0, 0, At, B0); PG8_MMA(0, 1, At, B1); PG8_BAR; PG8_SCHED;
;             PG8_LDA(At, 0, 1); PG8_STAGE(PG8_SB(0, 0), b2, voffB); PG8_STAGE(PG8_SB(0, 1), b2 + hstep, voffB); PG8_STAGE(PG8_SA(0, 0), a2, voffA);
;             PG8_WAIT_V(8); PG8_WAIT_L(0); PG8_BAR; PG8_MMA(1, 0, At, B0); PG8_MMA(1, 1, At, B1); PG8_BAR; PG8_SCHED;
.LBB0_619:
	s_or_b32 s28, s57, 1
	s_lshl_b64 s[58:59], s[28:29], 11
	s_add_u32 s58, s2, s58
	s_addc_u32 s59, s3, s59
	s_add_i32 s28, s57, 2
	v_add_u32_e32 v160, s78, v168
	v_add_u32_e32 v180, s79, v168
	s_lshl_b64 s[60:61], s[28:29], 11
	ds_read_b128 v[130:133], v160
	ds_read_b128 v[134:137], v160 offset:1024
	ds_read_b128 v[156:159], v160 offset:2048
	ds_read_b128 v[160:163], v160 offset:3072
	ds_read_b128 v[164:167], v180
	ds_read_b128 v[176:179], v180 offset:1024
	ds_read_b128 v[184:187], v180 offset:2048
	ds_read_b128 v[188:191], v180 offset:3072
	s_add_u32 s66, s2, s60
	s_addc_u32 s67, s3, s61
	s_and_b64 s[62:63], s[68:69], exec
	s_cselect_b32 s73, s67, s7
	s_cselect_b32 s72, s66, s15
	s_add_u32 s62, s16, s60
	s_addc_u32 s63, s17, s61
	s_and_b64 s[60:61], s[68:69], exec
	s_cselect_b32 s61, s63, s9
	s_cselect_b32 s60, s62, s56
	v_lshl_add_u64 v[180:181], s[58:59], 0, v[138:139]
	v_lshl_add_u64 v[224:225], v[180:181], 0, s[24:25]
	s_add_i32 m0, s70, 0xc000
	ds_read_b128 v[192:195], v173
	ds_read_b128 v[196:199], v173 offset:1024
	ds_read_b128 v[200:203], v173 offset:2048
	ds_read_b128 v[204:207], v173 offset:3072
	ds_read_b128 v[208:211], v173 offset:4096
	ds_read_b128 v[212:215], v173 offset:5120
	ds_read_b128 v[216:219], v173 offset:6144
	ds_read_b128 v[220:223], v173 offset:7168
	global_load_lds_dwordx4 v[224:225], off
	v_lshl_add_u64 v[180:181], v[180:181], 0, s[26:27]
	s_add_i32 m0, s70, 0xe000
	s_nop 0
	global_load_lds_dwordx4 v[180:181], off
	s_waitcnt vmcnt(8)
	s_waitcnt lgkmcnt(0)
	s_barrier
	s_setprio 1
	s_waitcnt lgkmcnt(0)
	v_mfma_f32_16x16x32_bf16 v[126:129], v[130:133], v[192:195], v[126:129]
	v_mfma_f32_16x16x32_bf16 v[126:129], v[134:137], v[196:199], v[126:129]
	v_mfma_f32_16x16x32_bf16 v[122:125], v[156:159], v[192:195], v[122:125]
	v_mfma_f32_16x16x32_bf16 v[122:125], v[160:163], v[196:199], v[122:125]
	v_mfma_f32_16x16x32_bf16 v[110:113], v[130:133], v[200:203], v[110:113]
	v_mfma_f32_16x16x32_bf16 v[110:113], v[134:137], v[204:207], v[110:113]
	v_mfma_f32_16x16x32_bf16 v[106:109], v[156:159], v[200:203], v[106:109]
	v_mfma_f32_16x16x32_bf16 v[106:109], v[160:163], v[204:207], v[106:109]
	v_mfma_f32_16x16x32_bf16 v[94:97], v[130:133], v[208:211], v[94:97]
	v_mfma_f32_16x16x32_bf16 v[94:97], v[134:137], v[212:215], v[94:97]
	v_mfma_f32_16x16x32_bf16 v[90:93], v[156:159], v[208:211], v[90:93]
	v_mfma_f32_16x16x32_bf16 v[90:93], v[160:163], v[212:215], v[90:93]
	v_mfma_f32_16x16x32_bf16 v[78:81], v[130:133], v[216:219], v[78:81]
	v_mfma_f32_16x16x32_bf16 v[78:81], v[134:137], v[220:223], v[78:81]
	v_mfma_f32_16x16x32_bf16 v[74:77], v[156:159], v[216:219], v[74:77]
	v_mfma_f32_16x16x32_bf16 v[74:77], v[160:163], v[220:223], v[74:77]
	v_mfma_f32_16x16x32_bf16 v[118:121], v[164:167], v[192:195], v[118:121]
	v_mfma_f32_16x16x32_bf16 v[118:121], v[176:179], v[196:199], v[118:121]
	v_mfma_f32_16x16x32_bf16 v[114:117], v[184:187], v[192:195], v[114:117]
	v_mfma_f32_16x16x32_bf16 v[114:117], v[188:191], v[196:199], v[114:117]
	v_mfma_f32_16x16x32_bf16 v[102:105], v[164:167], v[200:203], v[102:105]
	v_mfma_f32_16x16x32_bf16 v[102:105], v[176:179], v[204:207], v[102:105]
	v_mfma_f32_16x16x32_bf16 v[98:101], v[184:187], v[200:203], v[98:101]
	v_mfma_f32_16x16x32_bf16 v[98:101], v[188:191], v[204:207], v[98:101]
	v_mfma_f32_16x16x32_bf16 v[86:89], v[164:167], v[208:211], v[86:89]
	v_mfma_f32_16x16x32_bf16 v[86:89], v[176:179], v[212:215], v[86:89]
	v_mfma_f32_16x16x32_bf16 v[82:85], v[184:187], v[208:211], v[82:85]
	v_mfma_f32_16x16x32_bf16 v[82:85], v[188:191], v[212:215], v[82:85]
	s_barrier
	s_setprio 2
	v_mfma_f32_16x16x32_bf16 v[70:73], v[164:167], v[216:219], v[70:73]
	v_mfma_f32_16x16x32_bf16 v[70:73], v[176:179], v[220:223], v[70:73]
	v_mfma_f32_16x16x32_bf16 v[66:69], v[184:187], v[216:219], v[66:69]
	v_mfma_f32_16x16x32_bf16 v[66:69], v[188:191], v[220:223], v[66:69]
	s_setprio 0
	s_add_i32 s58, s78, s91
	v_lshl_add_u64 v[180:181], s[60:61], 0, v[138:139]
	s_mov_b32 m0, s58
	ds_read_b128 v[192:195], v173 offset:16384
	ds_read_b128 v[196:199], v173 offset:17408
	ds_read_b128 v[200:203], v173 offset:18432
	ds_read_b128 v[204:207], v173 offset:19456
	ds_read_b128 v[208:211], v173 offset:20480
	ds_read_b128 v[212:215], v173 offset:21504
	ds_read_b128 v[216:219], v173 offset:22528
	ds_read_b128 v[220:223], v173 offset:23552
	global_load_lds_dwordx4 v[180:181], off
	v_lshl_add_u64 v[224:225], v[180:181], 0, s[22:23]
	s_add_i32 m0, s58, 0x2000
	s_add_i32 s58, s79, s91
	global_load_lds_dwordx4 v[224:225], off
	v_lshl_add_u64 v[224:225], v[180:181], 0, s[24:25]
	s_mov_b32 m0, s58
	s_nop 0
	global_load_lds_dwordx4 v[224:225], off
	v_lshl_add_u64 v[224:225], v[180:181], 0, s[26:27]
	s_add_i32 m0, s58, 0x2000
	s_nop 0
	global_load_lds_dwordx4 v[224:225], off
	v_lshl_add_u64 v[224:225], s[72:73], 0, v[138:139]
	s_mov_b32 m0, s70
	v_lshl_add_u64 v[226:227], v[224:225], 0, s[22:23]
	global_load_lds_dwordx4 v[224:225], off
	s_mov_b32 m0, s71
	s_nop 0
	global_load_lds_dwordx4 v[226:227], off
	s_waitcnt vmcnt(8)
	s_waitcnt lgkmcnt(0)
	s_barrier
; #define PG8_STAGE(bufoff, gbase, voff) do { if constexpr (!pg8_noload<Epi>::value) { _Pragma("unroll") for (int _i = 0; _i < 2; ++_i) \
;         __builtin_amdgcn_global_load_lds((const unsigned*)((const char*)(gbase) + (size_t)_i * pstep + (voff)[0]), (PG8_LAS unsigned*)(lds + (bufoff) + ldsw + _i * 8192), 16, 0, 0); } } while (0)
; #define PG8_LDA(dst, b, h) do { _Pragma("unroll") for (int m = 0; m < 4; ++m) _Pragma("unroll") for (int k = 0; k < 2; ++k) dst[m][k] = *(const PG8_LAS bf16x8*)(lds + PG8_SA(b, h) + aoff + m * 2048 + k * 1024); } while (0)
; #define PG8_LDB(dst, b, h) do { _Pragma("unroll") for (int n = 0; n < 2; ++n) _Pragma("unroll") for (int k = 0; k < 2; ++k) dst[n][k] = *(const PG8_LAS bf16x8*)(lds + PG8_SB(b, h) + boff + n * 2048 + k * 1024); } while (0)
; #define PG8_MMA(ai, bj, At, Bt) do { __builtin_amdgcn_s_setprio(1); _Pragma("unroll") for (int m = 0; m < 4; ++m) _Pragma("unroll") for (int n = 0; n < 2; ++n) _Pragma("unroll") for (int k = 0; k < 2; ++k) \
;         acc[ai][bj][m][n] = __builtin_amdgcn_mfma_f32_16x16x32_bf16(Bt[n][k], At[m][k], acc[ai][bj][m][n], 0, 0, 0); __builtin_amdgcn_s_setprio(0); } while (0)
; #define PG8_WAIT_V(n) asm volatile("s_waitcnt vmcnt(" #n ")" ::: "memory")
; #define PG8_WAIT_L(n) asm volatile("s_waitcnt lgkmcnt(" #n ")" ::: "memory")
; #define PG8_BAR __builtin_amdgcn_s_barrier()
; #define PG8_SCHED __builtin_amdgcn_sched_barrier(0)
; template <class Epi, class Sched, bool ALIGN_EPI = false, bool SP2 = false, bool ABLK = false>
; __device__ __forceinline__ void gemm_phase(PG8_LAS unsigned char* lds, const Gemm g, const Sched& S, const Epi& E) {
;     ...
;             PG8_WAIT_V(8); PG8_WAIT_L(0); PG8_BAR; PG8_MMA(1, 0, At, B0); PG8_MMA(1, 1, At, B1); PG8_BAR; PG8_SCHED;
;             PG8_LDB(B0, 1, 0); PG8_LDB(B1, 1, 1); PG8_SCHED; PG8_LDA(At, 1, 0); PG8_STAGE(PG8_SA(0, 1), a2 + hstep, voffA);
;             PG8_WAIT_V(8); PG8_WAIT_L(0); PG8_BAR; PG8_MMA(0, 0, At, B0); PG8_MMA(0, 1, At, B1); PG8_BAR; PG8_SCHED;
;             PG8_LDA(At, 1, 1); PG8_STAGE(PG8_SB(1, 0), b3, voffB); PG8_STAGE(PG8_SB(1, 1), b3 + hstep, voffB); PG8_STAGE(PG8_SA(1, 0), a3, voffA);
	s_setprio 1
	s_waitcnt lgkmcnt(0)
	v_mfma_f32_16x16x32_bf16 v[62:65], v[130:133], v[192:195], v[62:65]
	v_mfma_f32_16x16x32_bf16 v[62:65], v[134:137], v[196:199], v[62:65]
	v_mfma_f32_16x16x32_bf16 v[58:61], v[156:159], v[192:195], v[58:61]
	v_mfma_f32_16x16x32_bf16 v[58:61], v[160:163], v[196:199], v[58:61]
	v_mfma_f32_16x16x32_bf16 v[46:49], v[130:133], v[200:203], v[46:49]
	v_mfma_f32_16x16x32_bf16 v[46:49], v[134:137], v[204:207], v[46:49]
	v_mfma_f32_16x16x32_bf16 v[42:45], v[156:159], v[200:203], v[42:45]
	v_mfma_f32_16x16x32_bf16 v[42:45], v[160:163], v[204:207], v[42:45]
	v_mfma_f32_16x16x32_bf16 v[30:33], v[130:133], v[208:211], v[30:33]
	v_mfma_f32_16x16x32_bf16 v[30:33], v[134:137], v[212:215], v[30:33]
	v_mfma_f32_16x16x32_bf16 v[26:29], v[156:159], v[208:211], v[26:29]
	v_mfma_f32_16x16x32_bf16 v[26:29], v[160:163], v[212:215], v[26:29]
	v_mfma_f32_16x16x32_bf16 v[14:17], v[130:133], v[216:219], v[14:17]
	v_mfma_f32_16x16x32_bf16 v[14:17], v[134:137], v[220:223], v[14:17]
	v_mfma_f32_16x16x32_bf16 v[10:13], v[156:159], v[216:219], v[10:13]
	v_mfma_f32_16x16x32_bf16 v[10:13], v[160:163], v[220:223], v[10:13]
	v_mfma_f32_16x16x32_bf16 v[54:57], v[164:167], v[192:195], v[54:57]
	v_mfma_f32_16x16x32_bf16 v[54:57], v[176:179], v[196:199], v[54:57]
	v_mfma_f32_16x16x32_bf16 v[50:53], v[184:187], v[192:195], v[50:53]
	v_mfma_f32_16x16x32_bf16 v[50:53], v[188:191], v[196:199], v[50:53]
	v_mfma_f32_16x16x32_bf16 v[38:41], v[164:167], v[200:203], v[38:41]
	v_mfma_f32_16x16x32_bf16 v[38:41], v[176:179], v[204:207], v[38:41]
	v_mfma_f32_16x16x32_bf16 v[34:37], v[184:187], v[200:203], v[34:37]
	v_mfma_f32_16x16x32_bf16 v[34:37], v[188:191], v[204:207], v[34:37]
	v_mfma_f32_16x16x32_bf16 v[22:25], v[164:167], v[208:211], v[22:25]
	v_mfma_f32_16x16x32_bf16 v[22:25], v[176:179], v[212:215], v[22:25]
	v_mfma_f32_16x16x32_bf16 v[18:21], v[184:187], v[208:211], v[18:21]
	v_mfma_f32_16x16x32_bf16 v[18:21], v[188:191], v[212:215], v[18:21]
	s_barrier
	s_setprio 2
	v_mfma_f32_16x16x32_bf16 v[6:9], v[164:167], v[216:219], v[6:9]
	v_mfma_f32_16x16x32_bf16 v[6:9], v[176:179], v[220:223], v[6:9]
	v_mfma_f32_16x16x32_bf16 v[2:5], v[184:187], v[216:219], v[2:5]
	v_mfma_f32_16x16x32_bf16 v[2:5], v[188:191], v[220:223], v[2:5]
	s_setprio 0
	s_add_i32 s58, 0, 0x18000
	s_add_i32 s59, 0, 0x1c000
	v_add_u32_e32 v160, s58, v168
	v_add_u32_e32 v188, s59, v168
	ds_read_b128 v[130:133], v160
	ds_read_b128 v[134:137], v160 offset:1024
	ds_read_b128 v[156:159], v160 offset:2048
	ds_read_b128 v[160:163], v160 offset:3072
	ds_read_b128 v[164:167], v188
	ds_read_b128 v[176:179], v188 offset:1024
	ds_read_b128 v[184:187], v188 offset:2048
	ds_read_b128 v[188:191], v188 offset:3072
	s_mov_b32 m0, s34
	v_lshl_add_u64 v[226:227], v[224:225], 0, s[24:25]
	ds_read_b128 v[192:195], v173 offset:32768
	ds_read_b128 v[196:199], v173 offset:33792
	ds_read_b128 v[200:203], v173 offset:34816
	ds_read_b128 v[204:207], v173 offset:35840
	ds_read_b128 v[208:211], v173 offset:36864
	ds_read_b128 v[212:215], v173 offset:37888
	ds_read_b128 v[216:219], v173 offset:38912
	ds_read_b128 v[220:223], v173 offset:39936
	global_load_lds_dwordx4 v[226:227], off
	v_lshl_add_u64 v[226:227], v[224:225], 0, s[26:27]
	s_mov_b32 m0, s35
	s_nop 0
	global_load_lds_dwordx4 v[226:227], off
	s_waitcnt vmcnt(8)
	s_waitcnt lgkmcnt(0)
	s_barrier
	s_setprio 1
	s_waitcnt lgkmcnt(0)
	v_mfma_f32_16x16x32_bf16 v[126:129], v[130:133], v[192:195], v[126:129]
	v_mfma_f32_16x16x32_bf16 v[126:129], v[134:137], v[196:199], v[126:129]
	v_mfma_f32_16x16x32_bf16 v[122:125], v[156:159], v[192:195], v[122:125]
	v_mfma_f32_16x16x32_bf16 v[122:125], v[160:163], v[196:199], v[122:125]
	v_mfma_f32_16x16x32_bf16 v[110:113], v[130:133], v[200:203], v[110:113]
	v_mfma_f32_16x16x32_bf16 v[110:113], v[134:137], v[204:207], v[110:113]
	v_mfma_f32_16x16x32_bf16 v[106:109], v[156:159], v[200:203], v[106:109]
	v_mfma_f32_16x16x32_bf16 v[106:109], v[160:163], v[204:207], v[106:109]
	v_mfma_f32_16x16x32_bf16 v[94:97], v[130:133], v[208:211], v[94:97]
	v_mfma_f32_16x16x32_bf16 v[94:97], v[134:137], v[212:215], v[94:97]
	v_mfma_f32_16x16x32_bf16 v[90:93], v[156:159], v[208:211], v[90:93]
	v_mfma_f32_16x16x32_bf16 v[90:93], v[160:163], v[212:215], v[90:93]
	v_mfma_f32_16x16x32_bf16 v[78:81], v[130:133], v[216:219], v[78:81]
	v_mfma_f32_16x16x32_bf16 v[78:81], v[134:137], v[220:223], v[78:81]
	v_mfma_f32_16x16x32_bf16 v[74:77], v[156:159], v[216:219], v[74:77]
	v_mfma_f32_16x16x32_bf16 v[74:77], v[160:163], v[220:223], v[74:77]
	v_mfma_f32_16x16x32_bf16 v[118:121], v[164:167], v[192:195], v[118:121]
	v_mfma_f32_16x16x32_bf16 v[118:121], v[176:179], v[196:199], v[118:121]
	v_mfma_f32_16x16x32_bf16 v[114:117], v[184:187], v[192:195], v[114:117]
	v_mfma_f32_16x16x32_bf16 v[114:117], v[188:191], v[196:199], v[114:117]
	v_mfma_f32_16x16x32_bf16 v[102:105], v[164:167], v[200:203], v[102:105]
	v_mfma_f32_16x16x32_bf16 v[102:105], v[176:179], v[204:207], v[102:105]
	v_mfma_f32_16x16x32_bf16 v[98:101], v[184:187], v[200:203], v[98:101]
	v_mfma_f32_16x16x32_bf16 v[98:101], v[188:191], v[204:207], v[98:101]
	v_mfma_f32_16x16x32_bf16 v[86:89], v[164:167], v[208:211], v[86:89]
	v_mfma_f32_16x16x32_bf16 v[86:89], v[176:179], v[212:215], v[86:89]
	v_mfma_f32_16x16x32_bf16 v[82:85], v[184:187], v[208:211], v[82:85]
	v_mfma_f32_16x16x32_bf16 v[82:85], v[188:191], v[212:215], v[82:85]
	s_barrier
; #define PG8_STAGE(bufoff, gbase, voff) do { if constexpr (!pg8_noload<Epi>::value) { _Pragma("unroll") for (int _i = 0; _i < 2; ++_i) \
;         __builtin_amdgcn_global_load_lds((const unsigned*)((const char*)(gbase) + (size_t)_i * pstep + (voff)[0]), (PG8_LAS unsigned*)(lds + (bufoff) + ldsw + _i * 8192), 16, 0, 0); } } while (0)
; #define PG8_LDA(dst, b, h) do { _Pragma("unroll") for (int m = 0; m < 4; ++m) _Pragma("unroll") for (int k = 0; k < 2; ++k) dst[m][k] = *(const PG8_LAS bf16x8*)(lds + PG8_SA(b, h) + aoff + m * 2048 + k * 1024); } while (0)
; #define PG8_LDB(dst, b, h) do { _Pragma("unroll") for (int n = 0; n < 2; ++n) _Pragma("unroll") for (int k = 0; k < 2; ++k) dst[n][k] = *(const PG8_LAS bf16x8*)(lds + PG8_SB(b, h) + boff + n * 2048 + k * 1024); } while (0)
; #define PG8_MMA(ai, bj, At, Bt) do { __builtin_amdgcn_s_setprio(1); _Pragma("unroll") for (int m = 0; m < 4; ++m) _Pragma("unroll") for (int n = 0; n < 2; ++n) _Pragma("unroll") for (int k = 0; k < 2; ++k) \
;         acc[ai][bj][m][n] = __builtin_amdgcn_mfma_f32_16x16x32_bf16(Bt[n][k], At[m][k], acc[ai][bj][m][n], 0, 0, 0); __builtin_amdgcn_s_setprio(0); } while (0)
; #define PG8_WAIT_V(n) asm volatile("s_waitcnt vmcnt(" #n ")" ::: "memory")
; #define PG8_WAIT_L(n) asm volatile("s_waitcnt lgkmcnt(" #n ")" ::: "memory")
; #define PG8_BAR __builtin_amdgcn_s_barrier()
; #define PG8_SCHED __builtin_amdgcn_sched_barrier(0)
; template <class Epi, class Sched, bool ALIGN_EPI = false, bool SP2 = false, bool ABLK = false>
; __device__ __forceinline__ void gemm_phase(PG8_LAS unsigned char* lds, const Gemm g, const Sched& S, const Epi& E) {
;     ...
;             PG8_WAIT_V(8); PG8_WAIT_L(0); PG8_BAR; PG8_MMA(1, 0, At, B0); PG8_MMA(1, 1, At, B1); PG8_BAR; PG8_SCHED;
;             PG8_LDB(B0, 1, 0); PG8_LDB(B1, 1, 1); PG8_SCHED; PG8_LDA(At, 1, 0); PG8_STAGE(PG8_SA(0, 1), a2 + hstep, voffA);
;             PG8_WAIT_V(8); PG8_WAIT_L(0); PG8_BAR; PG8_MMA(0, 0, At, B0); PG8_MMA(0, 1, At, B1); PG8_BAR; PG8_SCHED;
;             PG8_LDA(At, 1, 1); PG8_STAGE(PG8_SB(1, 0), b3, voffB); PG8_STAGE(PG8_SB(1, 1), b3 + hstep, voffB); PG8_STAGE(PG8_SA(1, 0), a3, voffA);
;             PG8_WAIT_V(8); PG8_WAIT_L(0); PG8_BAR; PG8_MMA(1, 0, At, B0); PG8_MMA(1, 1, At, B1); PG8_BAR; PG8_SCHED;
	s_setprio 2
	v_mfma_f32_16x16x32_bf16 v[70:73], v[164:167], v[216:219], v[70:73]
	v_mfma_f32_16x16x32_bf16 v[70:73], v[176:179], v[220:223], v[70:73]
	v_mfma_f32_16x16x32_bf16 v[66:69], v[184:187], v[216:219], v[66:69]
	v_mfma_f32_16x16x32_bf16 v[66:69], v[188:191], v[220:223], v[66:69]
	s_setprio 0
	s_add_i32 s58, s58, s91
	v_lshl_add_u64 v[226:227], v[180:181], 0, s[92:93]
	s_mov_b32 m0, s58
	ds_read_b128 v[192:195], v173 offset:49152
	ds_read_b128 v[196:199], v173 offset:50176
	ds_read_b128 v[200:203], v173 offset:51200
	ds_read_b128 v[204:207], v173 offset:52224
	ds_read_b128 v[208:211], v173 offset:53248
	ds_read_b128 v[212:215], v173 offset:54272
	ds_read_b128 v[216:219], v173 offset:55296
	ds_read_b128 v[220:223], v173 offset:56320
	global_load_lds_dwordx4 v[226:227], off
	v_lshl_add_u64 v[226:227], v[180:181], 0, s[94:95]
	s_add_i32 m0, s58, 0x2000
	s_add_i32 s58, s59, s91
	global_load_lds_dwordx4 v[226:227], off
	v_lshl_add_u64 v[226:227], v[180:181], 0, s[96:97]
	s_mov_b32 m0, s58
	v_lshl_add_u64 v[180:181], v[180:181], 0, s[88:89]
	global_load_lds_dwordx4 v[226:227], off
	s_add_i32 m0, s58, 0x2000
	s_nop 0
	global_load_lds_dwordx4 v[180:181], off
	v_lshl_add_u64 v[180:181], v[224:225], 0, s[92:93]
	s_mov_b32 m0, s10
	s_nop 0
	global_load_lds_dwordx4 v[180:181], off
	v_lshl_add_u64 v[180:181], v[224:225], 0, s[94:95]
	s_mov_b32 m0, s11
	s_nop 0
	global_load_lds_dwordx4 v[180:181], off
	s_waitcnt vmcnt(8)
	s_waitcnt lgkmcnt(0)
	s_barrier
	s_setprio 1
	s_waitcnt lgkmcnt(0)
	v_mfma_f32_16x16x32_bf16 v[62:65], v[130:133], v[192:195], v[62:65]
	v_mfma_f32_16x16x32_bf16 v[62:65], v[134:137], v[196:199], v[62:65]
	v_mfma_f32_16x16x32_bf16 v[58:61], v[156:159], v[192:195], v[58:61]
	v_mfma_f32_16x16x32_bf16 v[58:61], v[160:163], v[196:199], v[58:61]
	v_mfma_f32_16x16x32_bf16 v[46:49], v[130:133], v[200:203], v[46:49]
	v_mfma_f32_16x16x32_bf16 v[46:49], v[134:137], v[204:207], v[46:49]
	v_mfma_f32_16x16x32_bf16 v[42:45], v[156:159], v[200:203], v[42:45]
	v_mfma_f32_16x16x32_bf16 v[42:45], v[160:163], v[204:207], v[42:45]
	v_mfma_f32_16x16x32_bf16 v[30:33], v[130:133], v[208:211], v[30:33]
	v_mfma_f32_16x16x32_bf16 v[30:33], v[134:137], v[212:215], v[30:33]
	v_mfma_f32_16x16x32_bf16 v[26:29], v[156:159], v[208:211], v[26:29]
	v_mfma_f32_16x16x32_bf16 v[26:29], v[160:163], v[212:215], v[26:29]
	v_mfma_f32_16x16x32_bf16 v[14:17], v[130:133], v[216:219], v[14:17]
	v_mfma_f32_16x16x32_bf16 v[14:17], v[134:137], v[220:223], v[14:17]
	v_mfma_f32_16x16x32_bf16 v[10:13], v[156:159], v[216:219], v[10:13]
	v_mfma_f32_16x16x32_bf16 v[10:13], v[160:163], v[220:223], v[10:13]
	v_mfma_f32_16x16x32_bf16 v[54:57], v[164:167], v[192:195], v[54:57]
	v_mfma_f32_16x16x32_bf16 v[54:57], v[176:179], v[196:199], v[54:57]
	v_mfma_f32_16x16x32_bf16 v[50:53], v[184:187], v[192:195], v[50:53]
	v_mfma_f32_16x16x32_bf16 v[50:53], v[188:191], v[196:199], v[50:53]
	v_mfma_f32_16x16x32_bf16 v[38:41], v[164:167], v[200:203], v[38:41]
	v_mfma_f32_16x16x32_bf16 v[38:41], v[176:179], v[204:207], v[38:41]
	v_mfma_f32_16x16x32_bf16 v[34:37], v[184:187], v[200:203], v[34:37]
	v_mfma_f32_16x16x32_bf16 v[34:37], v[188:191], v[204:207], v[34:37]
	v_mfma_f32_16x16x32_bf16 v[22:25], v[164:167], v[208:211], v[22:25]
	v_mfma_f32_16x16x32_bf16 v[22:25], v[176:179], v[212:215], v[22:25]
	v_mfma_f32_16x16x32_bf16 v[18:21], v[184:187], v[208:211], v[18:21]
	v_mfma_f32_16x16x32_bf16 v[18:21], v[188:191], v[212:215], v[18:21]
	s_barrier
	s_setprio 2
	v_mfma_f32_16x16x32_bf16 v[6:9], v[164:167], v[216:219], v[6:9]
	v_mfma_f32_16x16x32_bf16 v[6:9], v[176:179], v[220:223], v[6:9]
	v_mfma_f32_16x16x32_bf16 v[2:5], v[184:187], v[216:219], v[2:5]
	v_mfma_f32_16x16x32_bf16 v[2:5], v[188:191], v[220:223], v[2:5]
	s_setprio 0
	s_cmp_gt_u32 s57, 29
	s_mov_b32 s57, s28
	s_cbranch_scc1 .LBB0_631

; #define PG8_STAGE(bufoff, gbase, voff) do { if constexpr (!pg8_noload<Epi>::value) { _Pragma("unroll") for (int _i = 0; _i < 2; ++_i) \
;         __builtin_amdgcn_global_load_lds((const unsigned*)((const char*)(gbase) + (size_t)_i * pstep + (voff)[0]), (PG8_LAS unsigned*)(lds + (bufoff) + ldsw + _i * 8192), 16, 0, 0); } } while (0)
; #define PG8_LDA(dst, b, h) do { _Pragma("unroll") for (int m = 0; m < 4; ++m) _Pragma("unroll") for (int k = 0; k < 2; ++k) dst[m][k] = *(const PG8_LAS bf16x8*)(lds + PG8_SA(b, h) + aoff + m * 2048 + k * 1024); } while (0)
; #define PG8_LDB(dst, b, h) do { _Pragma("unroll") for (int n = 0; n < 2; ++n) _Pragma("unroll") for (int k = 0; k < 2; ++k) dst[n][k] = *(const PG8_LAS bf16x8*)(lds + PG8_SB(b, h) + boff + n * 2048 + k * 1024); } while (0)
; #define PG8_MMA(ai, bj, At, Bt) do { __builtin_amdgcn_s_setprio(1); _Pragma("unroll") for (int m = 0; m < 4; ++m) _Pragma("unroll") for (int n = 0; n < 2; ++n) _Pragma("unroll") for (int k = 0; k < 2; ++k) \
;         acc[ai][bj][m][n] = __builtin_amdgcn_mfma_f32_16x16x32_bf16(Bt[n][k], At[m][k], acc[ai][bj][m][n], 0, 0, 0); __builtin_amdgcn_s_setprio(0); } while (0)
; #define PG8_WAIT_V(n) asm volatile("s_waitcnt vmcnt(" #n ")" ::: "memory")
; #define PG8_WAIT_L(n) asm volatile("s_waitcnt lgkmcnt(" #n ")" ::: "memory")
; template <class Epi, class Sched, bool ALIGN_EPI = false, bool SP2 = false, bool ABLK = false>
; __device__ __forceinline__ void gemm_phase(PG8_LAS unsigned char* lds, const Gemm g, const Sched& S, const Epi& E) {
;     ...
;             const char* a1 = cA + (size_t)(t + 1) * kstep;
;             const char* a2 = last ? nA : cA + (size_t)(t + 2) * kstep; const char* b2 = last ? nB : cB + (size_t)(t + 2) * kstepB;
;             const char* a3 = a2 + kstep; const char* b3 = b2 + kstepB;
;             if (last && has_next) S.a_ready(nxt);
;             if constexpr (SP2) {
;             PG8_LDB(B0, 0, 0); PG8_LDB(B1, 0, 1); PG8_SCHED; PG8_LDA(At, 0, 0); PG8_STAGE(PG8_SA(1, 1), a1 + hstep, voffA);
;             PG8_WAIT_V(8); PG8_WAIT_L(0); PG8_BAR; PG8_MMA(0, 0, At, B0); PG8_MMA(0, 1, At, B1); PG8_BAR; PG8_SCHED;
;             PG8_LDA(At, 0, 1); PG8_STAGE(PG8_SB(0, 0), b2, voffB); PG8_STAGE(PG8_SB(0, 1), b2 + hstep, voffB); PG8_STAGE(PG8_SA(0, 0), a2, voffA);
;             PG8_WAIT_V(8); PG8_WAIT_L(0); PG8_BAR; PG8_MMA(1, 0, At, B0); PG8_MMA(1, 1, At, B1); PG8_BAR; PG8_SCHED;
.LBB0_1533:
	ds_read_b128 v[114:117], v167
	ds_read_b128 v[126:129], v167 offset:1024
	ds_read_b128 v[130:133], v167 offset:2048
	ds_read_b128 v[142:145], v167 offset:3072
	ds_read_b128 v[146:149], v168
	ds_read_b128 v[150:153], v168 offset:1024
	ds_read_b128 v[174:177], v168 offset:2048
	ds_read_b128 v[178:181], v168 offset:3072
	s_add_i32 s41, s39, 2
	s_add_u32 s70, s68, 0xfff00800
	s_addc_u32 s71, s69, -1
	s_cmp_eq_u32 s3, s39
	s_cselect_b32 s71, s43, s71
	s_cselect_b32 s70, s42, s70
	s_cselect_b32 s81, s65, s37
	s_cselect_b32 s80, s64, s11
	v_lshl_add_u64 v[162:163], s[68:69], 0, v[158:159]
	s_add_i32 m0, s56, 0xc000
	ds_read_b128 v[184:187], v169
	ds_read_b128 v[188:191], v169 offset:1024
	ds_read_b128 v[192:195], v169 offset:2048
	ds_read_b128 v[196:199], v169 offset:3072
	ds_read_b128 v[200:203], v169 offset:4096
	ds_read_b128 v[204:207], v169 offset:5120
	ds_read_b128 v[208:211], v169 offset:6144
	ds_read_b128 v[212:215], v169 offset:7168
	global_load_lds_dwordx4 v[162:163], off
	v_lshl_add_u64 v[162:163], v[162:163], 0, s[12:13]
	s_add_i32 m0, s56, 0xe000
	s_nop 0
	global_load_lds_dwordx4 v[162:163], off
	s_waitcnt vmcnt(8)
	s_waitcnt lgkmcnt(0)
	s_barrier
	s_setprio 1
	s_waitcnt lgkmcnt(0)
	v_mfma_f32_16x16x32_bf16 v[138:141], v[114:117], v[184:187], v[138:141]
	v_mfma_f32_16x16x32_bf16 v[138:141], v[126:129], v[188:191], v[138:141]
	v_mfma_f32_16x16x32_bf16 v[134:137], v[130:133], v[184:187], v[134:137]
	v_mfma_f32_16x16x32_bf16 v[134:137], v[142:145], v[188:191], v[134:137]
	v_mfma_f32_16x16x32_bf16 v[110:113], v[114:117], v[192:195], v[110:113]
	v_mfma_f32_16x16x32_bf16 v[110:113], v[126:129], v[196:199], v[110:113]
	v_mfma_f32_16x16x32_bf16 v[106:109], v[130:133], v[192:195], v[106:109]
	v_mfma_f32_16x16x32_bf16 v[106:109], v[142:145], v[196:199], v[106:109]
	v_mfma_f32_16x16x32_bf16 v[94:97], v[114:117], v[200:203], v[94:97]
	v_mfma_f32_16x16x32_bf16 v[94:97], v[126:129], v[204:207], v[94:97]
	v_mfma_f32_16x16x32_bf16 v[90:93], v[130:133], v[200:203], v[90:93]
	v_mfma_f32_16x16x32_bf16 v[90:93], v[142:145], v[204:207], v[90:93]
	v_mfma_f32_16x16x32_bf16 v[78:81], v[114:117], v[208:211], v[78:81]
	v_mfma_f32_16x16x32_bf16 v[78:81], v[126:129], v[212:215], v[78:81]
	v_mfma_f32_16x16x32_bf16 v[74:77], v[130:133], v[208:211], v[74:77]
	v_mfma_f32_16x16x32_bf16 v[74:77], v[142:145], v[212:215], v[74:77]
	v_mfma_f32_16x16x32_bf16 v[122:125], v[146:149], v[184:187], v[122:125]
	v_mfma_f32_16x16x32_bf16 v[122:125], v[150:153], v[188:191], v[122:125]
	v_mfma_f32_16x16x32_bf16 v[118:121], v[174:177], v[184:187], v[118:121]
	v_mfma_f32_16x16x32_bf16 v[118:121], v[178:181], v[188:191], v[118:121]
	v_mfma_f32_16x16x32_bf16 v[102:105], v[146:149], v[192:195], v[102:105]
	v_mfma_f32_16x16x32_bf16 v[102:105], v[150:153], v[196:199], v[102:105]
	v_mfma_f32_16x16x32_bf16 v[98:101], v[174:177], v[192:195], v[98:101]
	v_mfma_f32_16x16x32_bf16 v[98:101], v[178:181], v[196:199], v[98:101]
	v_mfma_f32_16x16x32_bf16 v[86:89], v[146:149], v[200:203], v[86:89]
	v_mfma_f32_16x16x32_bf16 v[86:89], v[150:153], v[204:207], v[86:89]
	v_mfma_f32_16x16x32_bf16 v[82:85], v[174:177], v[200:203], v[82:85]
	v_mfma_f32_16x16x32_bf16 v[82:85], v[178:181], v[204:207], v[82:85]
	s_barrier
	s_setprio 2
	v_mfma_f32_16x16x32_bf16 v[70:73], v[146:149], v[208:211], v[70:73]
	v_mfma_f32_16x16x32_bf16 v[70:73], v[150:153], v[212:215], v[70:73]
	v_mfma_f32_16x16x32_bf16 v[66:69], v[174:177], v[208:211], v[66:69]
	v_mfma_f32_16x16x32_bf16 v[66:69], v[178:181], v[212:215], v[66:69]
	s_setprio 0
	s_add_i32 s39, s74, s55
	v_lshl_add_u64 v[162:163], s[80:81], 0, v[154:155]
	s_mov_b32 m0, s39
	ds_read_b128 v[184:187], v169 offset:16384
	ds_read_b128 v[188:191], v169 offset:17408
	ds_read_b128 v[192:195], v169 offset:18432
	ds_read_b128 v[196:199], v169 offset:19456
	ds_read_b128 v[200:203], v169 offset:20480
	ds_read_b128 v[204:207], v169 offset:21504
	ds_read_b128 v[208:211], v169 offset:22528
	ds_read_b128 v[212:215], v169 offset:23552
	global_load_lds_dwordx4 v[162:163], off
	v_lshl_add_u64 v[216:217], v[162:163], 0, s[12:13]
	s_add_i32 m0, s39, 0x2000
	s_add_i32 s39, s75, s55
	global_load_lds_dwordx4 v[216:217], off
	v_lshl_add_u64 v[216:217], v[162:163], 0, s[14:15]
	s_mov_b32 m0, s39
	s_nop 0
	global_load_lds_dwordx4 v[216:217], off
	v_lshl_add_u64 v[216:217], v[162:163], 0, s[16:17]
	s_add_i32 m0, s39, 0x2000
	s_nop 0
	global_load_lds_dwordx4 v[216:217], off
	v_lshl_add_u64 v[216:217], s[70:71], 0, v[154:155]
	s_mov_b32 m0, s56
	v_lshl_add_u64 v[218:219], v[216:217], 0, s[12:13]
	global_load_lds_dwordx4 v[216:217], off
	s_mov_b32 m0, s57
	s_nop 0
	global_load_lds_dwordx4 v[218:219], off
	s_waitcnt vmcnt(8)
	s_waitcnt lgkmcnt(0)
	s_barrier
; #define PG8_STAGE(bufoff, gbase, voff) do { if constexpr (!pg8_noload<Epi>::value) { _Pragma("unroll") for (int _i = 0; _i < 2; ++_i) \
;         __builtin_amdgcn_global_load_lds((const unsigned*)((const char*)(gbase) + (size_t)_i * pstep + (voff)[0]), (PG8_LAS unsigned*)(lds + (bufoff) + ldsw + _i * 8192), 16, 0, 0); } } while (0)
; #define PG8_LDA(dst, b, h) do { _Pragma("unroll") for (int m = 0; m < 4; ++m) _Pragma("unroll") for (int k = 0; k < 2; ++k) dst[m][k] = *(const PG8_LAS bf16x8*)(lds + PG8_SA(b, h) + aoff + m * 2048 + k * 1024); } while (0)
; #define PG8_LDB(dst, b, h) do { _Pragma("unroll") for (int n = 0; n < 2; ++n) _Pragma("unroll") for (int k = 0; k < 2; ++k) dst[n][k] = *(const PG8_LAS bf16x8*)(lds + PG8_SB(b, h) + boff + n * 2048 + k * 1024); } while (0)
; #define PG8_MMA(ai, bj, At, Bt) do { __builtin_amdgcn_s_setprio(1); _Pragma("unroll") for (int m = 0; m < 4; ++m) _Pragma("unroll") for (int n = 0; n < 2; ++n) _Pragma("unroll") for (int k = 0; k < 2; ++k) \
;         acc[ai][bj][m][n] = __builtin_amdgcn_mfma_f32_16x16x32_bf16(Bt[n][k], At[m][k], acc[ai][bj][m][n], 0, 0, 0); __builtin_amdgcn_s_setprio(0); } while (0)
; #define PG8_WAIT_V(n) asm volatile("s_waitcnt vmcnt(" #n ")" ::: "memory")
; #define PG8_WAIT_L(n) asm volatile("s_waitcnt lgkmcnt(" #n ")" ::: "memory")
; #define PG8_BAR __builtin_amdgcn_s_barrier()
; #define PG8_SCHED __builtin_amdgcn_sched_barrier(0)
; template <class Epi, class Sched, bool ALIGN_EPI = false, bool SP2 = false, bool ABLK = false>
; __device__ __forceinline__ void gemm_phase(PG8_LAS unsigned char* lds, const Gemm g, const Sched& S, const Epi& E) {
;     ...
;             PG8_WAIT_V(8); PG8_WAIT_L(0); PG8_BAR; PG8_MMA(1, 0, At, B0); PG8_MMA(1, 1, At, B1); PG8_BAR; PG8_SCHED;
;             PG8_LDB(B0, 1, 0); PG8_LDB(B1, 1, 1); PG8_SCHED; PG8_LDA(At, 1, 0); PG8_STAGE(PG8_SA(0, 1), a2 + hstep, voffA);
;             PG8_WAIT_V(8); PG8_WAIT_L(0); PG8_BAR; PG8_MMA(0, 0, At, B0); PG8_MMA(0, 1, At, B1); PG8_BAR; PG8_SCHED;
;             PG8_LDA(At, 1, 1); PG8_STAGE(PG8_SB(1, 0), b3, voffB); PG8_STAGE(PG8_SB(1, 1), b3 + hstep, voffB); PG8_STAGE(PG8_SA(1, 0), a3, voffA);
	s_setprio 1
	s_waitcnt lgkmcnt(0)
	v_mfma_f32_16x16x32_bf16 v[62:65], v[114:117], v[184:187], v[62:65]
	v_mfma_f32_16x16x32_bf16 v[62:65], v[126:129], v[188:191], v[62:65]
	v_mfma_f32_16x16x32_bf16 v[58:61], v[130:133], v[184:187], v[58:61]
	v_mfma_f32_16x16x32_bf16 v[58:61], v[142:145], v[188:191], v[58:61]
	v_mfma_f32_16x16x32_bf16 v[46:49], v[114:117], v[192:195], v[46:49]
	v_mfma_f32_16x16x32_bf16 v[46:49], v[126:129], v[196:199], v[46:49]
	v_mfma_f32_16x16x32_bf16 v[42:45], v[130:133], v[192:195], v[42:45]
	v_mfma_f32_16x16x32_bf16 v[42:45], v[142:145], v[196:199], v[42:45]
	v_mfma_f32_16x16x32_bf16 v[30:33], v[114:117], v[200:203], v[30:33]
	v_mfma_f32_16x16x32_bf16 v[30:33], v[126:129], v[204:207], v[30:33]
	v_mfma_f32_16x16x32_bf16 v[26:29], v[130:133], v[200:203], v[26:29]
	v_mfma_f32_16x16x32_bf16 v[26:29], v[142:145], v[204:207], v[26:29]
	v_mfma_f32_16x16x32_bf16 v[14:17], v[114:117], v[208:211], v[14:17]
	v_mfma_f32_16x16x32_bf16 v[14:17], v[126:129], v[212:215], v[14:17]
	v_mfma_f32_16x16x32_bf16 v[10:13], v[130:133], v[208:211], v[10:13]
	v_mfma_f32_16x16x32_bf16 v[10:13], v[142:145], v[212:215], v[10:13]
	v_mfma_f32_16x16x32_bf16 v[54:57], v[146:149], v[184:187], v[54:57]
	v_mfma_f32_16x16x32_bf16 v[54:57], v[150:153], v[188:191], v[54:57]
	v_mfma_f32_16x16x32_bf16 v[50:53], v[174:177], v[184:187], v[50:53]
	v_mfma_f32_16x16x32_bf16 v[50:53], v[178:181], v[188:191], v[50:53]
	v_mfma_f32_16x16x32_bf16 v[38:41], v[146:149], v[192:195], v[38:41]
	v_mfma_f32_16x16x32_bf16 v[38:41], v[150:153], v[196:199], v[38:41]
	v_mfma_f32_16x16x32_bf16 v[34:37], v[174:177], v[192:195], v[34:37]
	v_mfma_f32_16x16x32_bf16 v[34:37], v[178:181], v[196:199], v[34:37]
	v_mfma_f32_16x16x32_bf16 v[22:25], v[146:149], v[200:203], v[22:25]
	v_mfma_f32_16x16x32_bf16 v[22:25], v[150:153], v[204:207], v[22:25]
	v_mfma_f32_16x16x32_bf16 v[18:21], v[174:177], v[200:203], v[18:21]
	v_mfma_f32_16x16x32_bf16 v[18:21], v[178:181], v[204:207], v[18:21]
	s_barrier
	s_setprio 2
	v_mfma_f32_16x16x32_bf16 v[6:9], v[146:149], v[208:211], v[6:9]
	v_mfma_f32_16x16x32_bf16 v[6:9], v[150:153], v[212:215], v[6:9]
	v_mfma_f32_16x16x32_bf16 v[2:5], v[174:177], v[208:211], v[2:5]
	v_mfma_f32_16x16x32_bf16 v[2:5], v[178:181], v[212:215], v[2:5]
	s_setprio 0
	s_add_i32 s39, 0, 0x18000
	s_add_i32 s70, 0, 0x1c000
	v_add_u32_e32 v142, s39, v1
	v_add_u32_e32 v173, s70, v1
	ds_read_b128 v[114:117], v142
	ds_read_b128 v[126:129], v142 offset:1024
	ds_read_b128 v[130:133], v142 offset:2048
	ds_read_b128 v[142:145], v142 offset:3072
	ds_read_b128 v[146:149], v173
	ds_read_b128 v[150:153], v173 offset:1024
	ds_read_b128 v[174:177], v173 offset:2048
	ds_read_b128 v[178:181], v173 offset:3072
	s_mov_b32 m0, s58
	v_lshl_add_u64 v[218:219], v[216:217], 0, s[14:15]
	ds_read_b128 v[184:187], v169 offset:32768
	ds_read_b128 v[188:191], v169 offset:33792
	ds_read_b128 v[192:195], v169 offset:34816
	ds_read_b128 v[196:199], v169 offset:35840
	ds_read_b128 v[200:203], v169 offset:36864
	ds_read_b128 v[204:207], v169 offset:37888
	ds_read_b128 v[208:211], v169 offset:38912
	ds_read_b128 v[212:215], v169 offset:39936
	global_load_lds_dwordx4 v[218:219], off
	v_lshl_add_u64 v[218:219], v[216:217], 0, s[16:17]
	s_mov_b32 m0, s59
	s_nop 0
	global_load_lds_dwordx4 v[218:219], off
	s_waitcnt vmcnt(8)
	s_waitcnt lgkmcnt(0)
	s_barrier
	s_setprio 1
	s_waitcnt lgkmcnt(0)
	v_mfma_f32_16x16x32_bf16 v[138:141], v[114:117], v[184:187], v[138:141]
	v_mfma_f32_16x16x32_bf16 v[138:141], v[126:129], v[188:191], v[138:141]
	v_mfma_f32_16x16x32_bf16 v[134:137], v[130:133], v[184:187], v[134:137]
	v_mfma_f32_16x16x32_bf16 v[134:137], v[142:145], v[188:191], v[134:137]
	v_mfma_f32_16x16x32_bf16 v[110:113], v[114:117], v[192:195], v[110:113]
	v_mfma_f32_16x16x32_bf16 v[110:113], v[126:129], v[196:199], v[110:113]
	v_mfma_f32_16x16x32_bf16 v[106:109], v[130:133], v[192:195], v[106:109]
	v_mfma_f32_16x16x32_bf16 v[106:109], v[142:145], v[196:199], v[106:109]
	v_mfma_f32_16x16x32_bf16 v[94:97], v[114:117], v[200:203], v[94:97]
	v_mfma_f32_16x16x32_bf16 v[94:97], v[126:129], v[204:207], v[94:97]
	v_mfma_f32_16x16x32_bf16 v[90:93], v[130:133], v[200:203], v[90:93]
	v_mfma_f32_16x16x32_bf16 v[90:93], v[142:145], v[204:207], v[90:93]
	v_mfma_f32_16x16x32_bf16 v[78:81], v[114:117], v[208:211], v[78:81]
	v_mfma_f32_16x16x32_bf16 v[78:81], v[126:129], v[212:215], v[78:81]
	v_mfma_f32_16x16x32_bf16 v[74:77], v[130:133], v[208:211], v[74:77]
	v_mfma_f32_16x16x32_bf16 v[74:77], v[142:145], v[212:215], v[74:77]
	v_mfma_f32_16x16x32_bf16 v[122:125], v[146:149], v[184:187], v[122:125]
	v_mfma_f32_16x16x32_bf16 v[122:125], v[150:153], v[188:191], v[122:125]
	v_mfma_f32_16x16x32_bf16 v[118:121], v[174:177], v[184:187], v[118:121]
	v_mfma_f32_16x16x32_bf16 v[118:121], v[178:181], v[188:191], v[118:121]
	v_mfma_f32_16x16x32_bf16 v[102:105], v[146:149], v[192:195], v[102:105]
	v_mfma_f32_16x16x32_bf16 v[102:105], v[150:153], v[196:199], v[102:105]
	v_mfma_f32_16x16x32_bf16 v[98:101], v[174:177], v[192:195], v[98:101]
	v_mfma_f32_16x16x32_bf16 v[98:101], v[178:181], v[196:199], v[98:101]
	v_mfma_f32_16x16x32_bf16 v[86:89], v[146:149], v[200:203], v[86:89]
	v_mfma_f32_16x16x32_bf16 v[86:89], v[150:153], v[204:207], v[86:89]
	v_mfma_f32_16x16x32_bf16 v[82:85], v[174:177], v[200:203], v[82:85]
	v_mfma_f32_16x16x32_bf16 v[82:85], v[178:181], v[204:207], v[82:85]
	s_barrier
; #define PG8_STAGE(bufoff, gbase, voff) do { if constexpr (!pg8_noload<Epi>::value) { _Pragma("unroll") for (int _i = 0; _i < 2; ++_i) \
;         __builtin_amdgcn_global_load_lds((const unsigned*)((const char*)(gbase) + (size_t)_i * pstep + (voff)[0]), (PG8_LAS unsigned*)(lds + (bufoff) + ldsw + _i * 8192), 16, 0, 0); } } while (0)
; #define PG8_LDA(dst, b, h) do { _Pragma("unroll") for (int m = 0; m < 4; ++m) _Pragma("unroll") for (int k = 0; k < 2; ++k) dst[m][k] = *(const PG8_LAS bf16x8*)(lds + PG8_SA(b, h) + aoff + m * 2048 + k * 1024); } while (0)
; #define PG8_LDB(dst, b, h) do { _Pragma("unroll") for (int n = 0; n < 2; ++n) _Pragma("unroll") for (int k = 0; k < 2; ++k) dst[n][k] = *(const PG8_LAS bf16x8*)(lds + PG8_SB(b, h) + boff + n * 2048 + k * 1024); } while (0)
; #define PG8_MMA(ai, bj, At, Bt) do { __builtin_amdgcn_s_setprio(1); _Pragma("unroll") for (int m = 0; m < 4; ++m) _Pragma("unroll") for (int n = 0; n < 2; ++n) _Pragma("unroll") for (int k = 0; k < 2; ++k) \
;         acc[ai][bj][m][n] = __builtin_amdgcn_mfma_f32_16x16x32_bf16(Bt[n][k], At[m][k], acc[ai][bj][m][n], 0, 0, 0); __builtin_amdgcn_s_setprio(0); } while (0)
; #define PG8_WAIT_V(n) asm volatile("s_waitcnt vmcnt(" #n ")" ::: "memory")
; #define PG8_WAIT_L(n) asm volatile("s_waitcnt lgkmcnt(" #n ")" ::: "memory")
; #define PG8_BAR __builtin_amdgcn_s_barrier()
; #define PG8_SCHED __builtin_amdgcn_sched_barrier(0)
; template <class Epi, class Sched, bool ALIGN_EPI = false, bool SP2 = false, bool ABLK = false>
; __device__ __forceinline__ void gemm_phase(PG8_LAS unsigned char* lds, const Gemm g, const Sched& S, const Epi& E) {
;     ...
;             PG8_WAIT_V(8); PG8_WAIT_L(0); PG8_BAR; PG8_MMA(1, 0, At, B0); PG8_MMA(1, 1, At, B1); PG8_BAR; PG8_SCHED;
;             PG8_LDB(B0, 1, 0); PG8_LDB(B1, 1, 1); PG8_SCHED; PG8_LDA(At, 1, 0); PG8_STAGE(PG8_SA(0, 1), a2 + hstep, voffA);
;             PG8_WAIT_V(8); PG8_WAIT_L(0); PG8_BAR; PG8_MMA(0, 0, At, B0); PG8_MMA(0, 1, At, B1); PG8_BAR; PG8_SCHED;
;             PG8_LDA(At, 1, 1); PG8_STAGE(PG8_SB(1, 0), b3, voffB); PG8_STAGE(PG8_SB(1, 1), b3 + hstep, voffB); PG8_STAGE(PG8_SA(1, 0), a3, voffA);
;             PG8_WAIT_V(8); PG8_WAIT_L(0); PG8_BAR; PG8_MMA(1, 0, At, B0); PG8_MMA(1, 1, At, B1); PG8_BAR; PG8_SCHED;
	s_setprio 2
	v_mfma_f32_16x16x32_bf16 v[70:73], v[146:149], v[208:211], v[70:73]
	v_mfma_f32_16x16x32_bf16 v[70:73], v[150:153], v[212:215], v[70:73]
	v_mfma_f32_16x16x32_bf16 v[66:69], v[174:177], v[208:211], v[66:69]
	v_mfma_f32_16x16x32_bf16 v[66:69], v[178:181], v[212:215], v[66:69]
	s_setprio 0
	s_add_i32 s39, s39, s55
	v_lshl_add_u64 v[218:219], v[162:163], 0, s[24:25]
	s_mov_b32 m0, s39
	ds_read_b128 v[184:187], v169 offset:49152
	ds_read_b128 v[188:191], v169 offset:50176
	ds_read_b128 v[192:195], v169 offset:51200
	ds_read_b128 v[196:199], v169 offset:52224
	ds_read_b128 v[200:203], v169 offset:53248
	ds_read_b128 v[204:207], v169 offset:54272
	ds_read_b128 v[208:211], v169 offset:55296
	ds_read_b128 v[212:215], v169 offset:56320
	global_load_lds_dwordx4 v[218:219], off
	v_lshl_add_u64 v[218:219], v[162:163], 0, s[26:27]
	s_add_i32 m0, s39, 0x2000
	s_add_i32 s39, s70, s55
	global_load_lds_dwordx4 v[218:219], off
	v_lshl_add_u64 v[218:219], v[162:163], 0, s[28:29]
	s_mov_b32 m0, s39
	v_lshl_add_u64 v[162:163], v[162:163], 0, s[30:31]
	global_load_lds_dwordx4 v[218:219], off
	s_add_i32 m0, s39, 0x2000
	s_nop 0
	global_load_lds_dwordx4 v[162:163], off
	v_lshl_add_u64 v[162:163], v[216:217], 0, s[24:25]
	s_mov_b32 m0, s62
	s_nop 0
	global_load_lds_dwordx4 v[162:163], off
	v_lshl_add_u64 v[162:163], v[216:217], 0, s[26:27]
	s_mov_b32 m0, s63
	s_nop 0
	global_load_lds_dwordx4 v[162:163], off
	s_waitcnt vmcnt(8)
	s_waitcnt lgkmcnt(0)
	s_barrier
	s_setprio 1
	s_waitcnt lgkmcnt(0)
	v_mfma_f32_16x16x32_bf16 v[62:65], v[114:117], v[184:187], v[62:65]
	v_mfma_f32_16x16x32_bf16 v[62:65], v[126:129], v[188:191], v[62:65]
	v_mfma_f32_16x16x32_bf16 v[58:61], v[130:133], v[184:187], v[58:61]
	v_mfma_f32_16x16x32_bf16 v[58:61], v[142:145], v[188:191], v[58:61]
	v_mfma_f32_16x16x32_bf16 v[46:49], v[114:117], v[192:195], v[46:49]
	v_mfma_f32_16x16x32_bf16 v[46:49], v[126:129], v[196:199], v[46:49]
	v_mfma_f32_16x16x32_bf16 v[42:45], v[130:133], v[192:195], v[42:45]
	v_mfma_f32_16x16x32_bf16 v[42:45], v[142:145], v[196:199], v[42:45]
	v_mfma_f32_16x16x32_bf16 v[30:33], v[114:117], v[200:203], v[30:33]
	v_mfma_f32_16x16x32_bf16 v[30:33], v[126:129], v[204:207], v[30:33]
	v_mfma_f32_16x16x32_bf16 v[26:29], v[130:133], v[200:203], v[26:29]
	v_mfma_f32_16x16x32_bf16 v[26:29], v[142:145], v[204:207], v[26:29]
	v_mfma_f32_16x16x32_bf16 v[14:17], v[114:117], v[208:211], v[14:17]
	v_mfma_f32_16x16x32_bf16 v[14:17], v[126:129], v[212:215], v[14:17]
	v_mfma_f32_16x16x32_bf16 v[10:13], v[130:133], v[208:211], v[10:13]
	v_mfma_f32_16x16x32_bf16 v[10:13], v[142:145], v[212:215], v[10:13]
	v_mfma_f32_16x16x32_bf16 v[54:57], v[146:149], v[184:187], v[54:57]
	v_mfma_f32_16x16x32_bf16 v[54:57], v[150:153], v[188:191], v[54:57]
	v_mfma_f32_16x16x32_bf16 v[50:53], v[174:177], v[184:187], v[50:53]
	v_mfma_f32_16x16x32_bf16 v[50:53], v[178:181], v[188:191], v[50:53]
	v_mfma_f32_16x16x32_bf16 v[38:41], v[146:149], v[192:195], v[38:41]
	v_mfma_f32_16x16x32_bf16 v[38:41], v[150:153], v[196:199], v[38:41]
	v_mfma_f32_16x16x32_bf16 v[34:37], v[174:177], v[192:195], v[34:37]
	v_mfma_f32_16x16x32_bf16 v[34:37], v[178:181], v[196:199], v[34:37]
	v_mfma_f32_16x16x32_bf16 v[22:25], v[146:149], v[200:203], v[22:25]
	v_mfma_f32_16x16x32_bf16 v[22:25], v[150:153], v[204:207], v[22:25]
	v_mfma_f32_16x16x32_bf16 v[18:21], v[174:177], v[200:203], v[18:21]
	v_mfma_f32_16x16x32_bf16 v[18:21], v[178:181], v[204:207], v[18:21]
	s_barrier
	s_setprio 2
	v_mfma_f32_16x16x32_bf16 v[6:9], v[146:149], v[208:211], v[6:9]
	v_mfma_f32_16x16x32_bf16 v[6:9], v[150:153], v[212:215], v[6:9]
	v_mfma_f32_16x16x32_bf16 v[2:5], v[174:177], v[208:211], v[2:5]
	v_mfma_f32_16x16x32_bf16 v[2:5], v[178:181], v[212:215], v[2:5]
	s_setprio 0
	s_add_u32 s68, s68, 0x1000
	s_addc_u32 s69, s69, 0
	s_add_u32 s11, s11, 0x1000
	s_addc_u32 s37, s37, 0
	s_cmp_ge_i32 s41, s79
	s_mov_b32 s39, s41
	s_cbranch_scc0 .LBB0_1533
	s_and_b64 vcc, exec, s[34:35]
	s_cbranch_vccnz .LBB0_1538
	s_lshl_b32 s11, s2, 8
	s_cmp_gt_i32 s2, 63
	s_mov_b64 s[68:69], -1
	s_cbranch_scc1 .LBB0_1539

; #define PG8_STAGE(bufoff, gbase, voff) do { if constexpr (!pg8_noload<Epi>::value) { _Pragma("unroll") for (int _i = 0; _i < 2; ++_i) \
;         __builtin_amdgcn_global_load_lds((const unsigned*)((const char*)(gbase) + (size_t)_i * pstep + (voff)[0]), (PG8_LAS unsigned*)(lds + (bufoff) + ldsw + _i * 8192), 16, 0, 0); } } while (0)
; #define PG8_LDA(dst, b, h) do { _Pragma("unroll") for (int m = 0; m < 4; ++m) _Pragma("unroll") for (int k = 0; k < 2; ++k) dst[m][k] = *(const PG8_LAS bf16x8*)(lds + PG8_SA(b, h) + aoff + m * 2048 + k * 1024); } while (0)
; #define PG8_LDB(dst, b, h) do { _Pragma("unroll") for (int n = 0; n < 2; ++n) _Pragma("unroll") for (int k = 0; k < 2; ++k) dst[n][k] = *(const PG8_LAS bf16x8*)(lds + PG8_SB(b, h) + boff + n * 2048 + k * 1024); } while (0)
; #define PG8_MMA(ai, bj, At, Bt) do { __builtin_amdgcn_s_setprio(1); _Pragma("unroll") for (int m = 0; m < 4; ++m) _Pragma("unroll") for (int n = 0; n < 2; ++n) _Pragma("unroll") for (int k = 0; k < 2; ++k) \
;         acc[ai][bj][m][n] = __builtin_amdgcn_mfma_f32_16x16x32_bf16(Bt[n][k], At[m][k], acc[ai][bj][m][n], 0, 0, 0); __builtin_amdgcn_s_setprio(0); } while (0)
; #define PG8_WAIT_V(n) asm volatile("s_waitcnt vmcnt(" #n ")" ::: "memory")
; #define PG8_WAIT_L(n) asm volatile("s_waitcnt lgkmcnt(" #n ")" ::: "memory")
; template <class Epi, class Sched, bool ALIGN_EPI = false, bool SP2 = false, bool ABLK = false>
; __device__ __forceinline__ void gemm_phase(PG8_LAS unsigned char* lds, const Gemm g, const Sched& S, const Epi& E) {
;     ...
;             const char* a1 = cA + (size_t)(t + 1) * kstep;
;             const char* a2 = last ? nA : cA + (size_t)(t + 2) * kstep; const char* b2 = last ? nB : cB + (size_t)(t + 2) * kstepB;
;             const char* a3 = a2 + kstep; const char* b3 = b2 + kstepB;
;             if (last && has_next) S.a_ready(nxt);
;             if constexpr (SP2) {
;             PG8_LDB(B0, 0, 0); PG8_LDB(B1, 0, 1); PG8_SCHED; PG8_LDA(At, 0, 0); PG8_STAGE(PG8_SA(1, 1), a1 + hstep, voffA);
;             PG8_WAIT_V(8); PG8_WAIT_L(0); PG8_BAR; PG8_MMA(0, 0, At, B0); PG8_MMA(0, 1, At, B1); PG8_BAR; PG8_SCHED;
;             PG8_LDA(At, 0, 1); PG8_STAGE(PG8_SB(0, 0), b2, voffB); PG8_STAGE(PG8_SB(0, 1), b2 + hstep, voffB); PG8_STAGE(PG8_SA(0, 0), a2, voffA);
;             PG8_WAIT_V(8); PG8_WAIT_L(0); PG8_BAR; PG8_MMA(1, 0, At, B0); PG8_MMA(1, 1, At, B1); PG8_BAR; PG8_SCHED;
.LBB0_1657:
	s_or_b32 s26, s94, 1
	s_lshl_b64 s[82:83], s[26:27], 11
	s_add_u32 s88, s74, s82
	v_add_u32_e32 v140, s12, v173
	s_addc_u32 s89, s75, s83
	s_add_i32 s26, s94, 2
	ds_read_b128 v[130:133], v140
	ds_read_b128 v[134:137], v140 offset:1024
	ds_read_b128 v[154:157], v140 offset:2048
	ds_read_b128 v[158:161], v140 offset:3072
	v_add_u32_e32 v140, s13, v173
	s_lshl_b64 s[90:91], s[26:27], 11
	ds_read_b128 v[162:165], v140
	ds_read_b128 v[166:169], v140 offset:1024
	ds_read_b128 v[184:187], v140 offset:2048
	ds_read_b128 v[188:191], v140 offset:3072
	s_add_u32 s92, s74, s90
	s_addc_u32 s93, s75, s91
	s_and_b64 s[82:83], s[80:81], exec
	s_cselect_b32 s83, s93, s3
	s_cselect_b32 s82, s92, s25
	s_add_u32 s90, s76, s90
	s_addc_u32 s91, s77, s91
	s_and_b64 s[80:81], s[80:81], exec
	s_cselect_b32 s81, s91, s65
	s_cselect_b32 s80, s90, s67
	v_lshl_add_u64 v[170:171], s[88:89], 0, v[138:139]
	v_lshl_add_u64 v[224:225], v[170:171], 0, s[20:21]
	s_add_i32 m0, s56, 0xc000
	ds_read_b128 v[192:195], v178
	ds_read_b128 v[196:199], v178 offset:1024
	ds_read_b128 v[200:203], v178 offset:2048
	ds_read_b128 v[204:207], v178 offset:3072
	ds_read_b128 v[208:211], v178 offset:4096
	ds_read_b128 v[212:215], v178 offset:5120
	ds_read_b128 v[216:219], v178 offset:6144
	ds_read_b128 v[220:223], v178 offset:7168
	global_load_lds_dwordx4 v[224:225], off
	v_lshl_add_u64 v[170:171], v[170:171], 0, s[22:23]
	s_add_i32 m0, s56, 0xe000
	s_nop 0
	global_load_lds_dwordx4 v[170:171], off
	s_waitcnt vmcnt(8)
	s_waitcnt lgkmcnt(0)
	s_barrier
	s_setprio 1
	s_waitcnt lgkmcnt(0)
	v_mfma_f32_16x16x32_bf16 v[126:129], v[130:133], v[192:195], v[126:129]
	v_mfma_f32_16x16x32_bf16 v[126:129], v[134:137], v[196:199], v[126:129]
	v_mfma_f32_16x16x32_bf16 v[122:125], v[154:157], v[192:195], v[122:125]
	v_mfma_f32_16x16x32_bf16 v[122:125], v[158:161], v[196:199], v[122:125]
	v_mfma_f32_16x16x32_bf16 v[110:113], v[130:133], v[200:203], v[110:113]
	v_mfma_f32_16x16x32_bf16 v[110:113], v[134:137], v[204:207], v[110:113]
	v_mfma_f32_16x16x32_bf16 v[106:109], v[154:157], v[200:203], v[106:109]
	v_mfma_f32_16x16x32_bf16 v[106:109], v[158:161], v[204:207], v[106:109]
	v_mfma_f32_16x16x32_bf16 v[94:97], v[130:133], v[208:211], v[94:97]
	v_mfma_f32_16x16x32_bf16 v[94:97], v[134:137], v[212:215], v[94:97]
	v_mfma_f32_16x16x32_bf16 v[90:93], v[154:157], v[208:211], v[90:93]
	v_mfma_f32_16x16x32_bf16 v[90:93], v[158:161], v[212:215], v[90:93]
	v_mfma_f32_16x16x32_bf16 v[78:81], v[130:133], v[216:219], v[78:81]
	v_mfma_f32_16x16x32_bf16 v[78:81], v[134:137], v[220:223], v[78:81]
	v_mfma_f32_16x16x32_bf16 v[74:77], v[154:157], v[216:219], v[74:77]
	v_mfma_f32_16x16x32_bf16 v[74:77], v[158:161], v[220:223], v[74:77]
	v_mfma_f32_16x16x32_bf16 v[118:121], v[162:165], v[192:195], v[118:121]
	v_mfma_f32_16x16x32_bf16 v[118:121], v[166:169], v[196:199], v[118:121]
	v_mfma_f32_16x16x32_bf16 v[114:117], v[184:187], v[192:195], v[114:117]
	v_mfma_f32_16x16x32_bf16 v[114:117], v[188:191], v[196:199], v[114:117]
	v_mfma_f32_16x16x32_bf16 v[102:105], v[162:165], v[200:203], v[102:105]
	v_mfma_f32_16x16x32_bf16 v[102:105], v[166:169], v[204:207], v[102:105]
	v_mfma_f32_16x16x32_bf16 v[98:101], v[184:187], v[200:203], v[98:101]
	v_mfma_f32_16x16x32_bf16 v[98:101], v[188:191], v[204:207], v[98:101]
	v_mfma_f32_16x16x32_bf16 v[86:89], v[162:165], v[208:211], v[86:89]
	v_mfma_f32_16x16x32_bf16 v[86:89], v[166:169], v[212:215], v[86:89]
	v_mfma_f32_16x16x32_bf16 v[82:85], v[184:187], v[208:211], v[82:85]
	v_mfma_f32_16x16x32_bf16 v[82:85], v[188:191], v[212:215], v[82:85]
	s_barrier
	s_setprio 2
	v_mfma_f32_16x16x32_bf16 v[70:73], v[162:165], v[216:219], v[70:73]
	v_mfma_f32_16x16x32_bf16 v[70:73], v[166:169], v[220:223], v[70:73]
	v_mfma_f32_16x16x32_bf16 v[66:69], v[184:187], v[216:219], v[66:69]
	v_mfma_f32_16x16x32_bf16 v[66:69], v[188:191], v[220:223], v[66:69]
	s_setprio 0
	v_lshl_add_u64 v[170:171], s[80:81], 0, v[138:139]
	s_add_i32 s80, s12, s55
	s_mov_b32 m0, s80
	ds_read_b128 v[192:195], v178 offset:16384
	ds_read_b128 v[196:199], v178 offset:17408
	ds_read_b128 v[200:203], v178 offset:18432
	ds_read_b128 v[204:207], v178 offset:19456
	ds_read_b128 v[208:211], v178 offset:20480
	ds_read_b128 v[212:215], v178 offset:21504
	ds_read_b128 v[216:219], v178 offset:22528
	ds_read_b128 v[220:223], v178 offset:23552
	global_load_lds_dwordx4 v[170:171], off
	v_lshl_add_u64 v[224:225], v[170:171], 0, s[18:19]
	s_add_i32 m0, s80, 0x2000
	s_add_i32 s80, s13, s55
	global_load_lds_dwordx4 v[224:225], off
	v_lshl_add_u64 v[224:225], v[170:171], 0, s[20:21]
	s_mov_b32 m0, s80
	s_nop 0
	global_load_lds_dwordx4 v[224:225], off
	v_lshl_add_u64 v[224:225], v[170:171], 0, s[22:23]
	s_add_i32 m0, s80, 0x2000
	s_nop 0
	global_load_lds_dwordx4 v[224:225], off
	v_lshl_add_u64 v[224:225], s[82:83], 0, v[138:139]
	s_mov_b32 m0, s56
	v_lshl_add_u64 v[226:227], v[224:225], 0, s[18:19]
	global_load_lds_dwordx4 v[224:225], off
	s_mov_b32 m0, s57
	s_nop 0
	global_load_lds_dwordx4 v[226:227], off
	s_waitcnt vmcnt(8)
	s_waitcnt lgkmcnt(0)
	s_barrier
; #define PG8_STAGE(bufoff, gbase, voff) do { if constexpr (!pg8_noload<Epi>::value) { _Pragma("unroll") for (int _i = 0; _i < 2; ++_i) \
;         __builtin_amdgcn_global_load_lds((const unsigned*)((const char*)(gbase) + (size_t)_i * pstep + (voff)[0]), (PG8_LAS unsigned*)(lds + (bufoff) + ldsw + _i * 8192), 16, 0, 0); } } while (0)
; #define PG8_LDA(dst, b, h) do { _Pragma("unroll") for (int m = 0; m < 4; ++m) _Pragma("unroll") for (int k = 0; k < 2; ++k) dst[m][k] = *(const PG8_LAS bf16x8*)(lds + PG8_SA(b, h) + aoff + m * 2048 + k * 1024); } while (0)
; #define PG8_LDB(dst, b, h) do { _Pragma("unroll") for (int n = 0; n < 2; ++n) _Pragma("unroll") for (int k = 0; k < 2; ++k) dst[n][k] = *(const PG8_LAS bf16x8*)(lds + PG8_SB(b, h) + boff + n * 2048 + k * 1024); } while (0)
; #define PG8_MMA(ai, bj, At, Bt) do { __builtin_amdgcn_s_setprio(1); _Pragma("unroll") for (int m = 0; m < 4; ++m) _Pragma("unroll") for (int n = 0; n < 2; ++n) _Pragma("unroll") for (int k = 0; k < 2; ++k) \
;         acc[ai][bj][m][n] = __builtin_amdgcn_mfma_f32_16x16x32_bf16(Bt[n][k], At[m][k], acc[ai][bj][m][n], 0, 0, 0); __builtin_amdgcn_s_setprio(0); } while (0)
; #define PG8_WAIT_V(n) asm volatile("s_waitcnt vmcnt(" #n ")" ::: "memory")
; #define PG8_WAIT_L(n) asm volatile("s_waitcnt lgkmcnt(" #n ")" ::: "memory")
; #define PG8_BAR __builtin_amdgcn_s_barrier()
; #define PG8_SCHED __builtin_amdgcn_sched_barrier(0)
; template <class Epi, class Sched, bool ALIGN_EPI = false, bool SP2 = false, bool ABLK = false>
; __device__ __forceinline__ void gemm_phase(PG8_LAS unsigned char* lds, const Gemm g, const Sched& S, const Epi& E) {
;     ...
;             PG8_WAIT_V(8); PG8_WAIT_L(0); PG8_BAR; PG8_MMA(1, 0, At, B0); PG8_MMA(1, 1, At, B1); PG8_BAR; PG8_SCHED;
;             PG8_LDB(B0, 1, 0); PG8_LDB(B1, 1, 1); PG8_SCHED; PG8_LDA(At, 1, 0); PG8_STAGE(PG8_SA(0, 1), a2 + hstep, voffA);
;             PG8_WAIT_V(8); PG8_WAIT_L(0); PG8_BAR; PG8_MMA(0, 0, At, B0); PG8_MMA(0, 1, At, B1); PG8_BAR; PG8_SCHED;
;             PG8_LDA(At, 1, 1); PG8_STAGE(PG8_SB(1, 0), b3, voffB); PG8_STAGE(PG8_SB(1, 1), b3 + hstep, voffB); PG8_STAGE(PG8_SA(1, 0), a3, voffA);
	s_setprio 1
	s_waitcnt lgkmcnt(0)
	v_mfma_f32_16x16x32_bf16 v[62:65], v[130:133], v[192:195], v[62:65]
	v_mfma_f32_16x16x32_bf16 v[62:65], v[134:137], v[196:199], v[62:65]
	v_mfma_f32_16x16x32_bf16 v[58:61], v[154:157], v[192:195], v[58:61]
	v_mfma_f32_16x16x32_bf16 v[58:61], v[158:161], v[196:199], v[58:61]
	v_mfma_f32_16x16x32_bf16 v[46:49], v[130:133], v[200:203], v[46:49]
	v_mfma_f32_16x16x32_bf16 v[46:49], v[134:137], v[204:207], v[46:49]
	v_mfma_f32_16x16x32_bf16 v[42:45], v[154:157], v[200:203], v[42:45]
	v_mfma_f32_16x16x32_bf16 v[42:45], v[158:161], v[204:207], v[42:45]
	v_mfma_f32_16x16x32_bf16 v[30:33], v[130:133], v[208:211], v[30:33]
	v_mfma_f32_16x16x32_bf16 v[30:33], v[134:137], v[212:215], v[30:33]
	v_mfma_f32_16x16x32_bf16 v[26:29], v[154:157], v[208:211], v[26:29]
	v_mfma_f32_16x16x32_bf16 v[26:29], v[158:161], v[212:215], v[26:29]
	v_mfma_f32_16x16x32_bf16 v[14:17], v[130:133], v[216:219], v[14:17]
	v_mfma_f32_16x16x32_bf16 v[14:17], v[134:137], v[220:223], v[14:17]
	v_mfma_f32_16x16x32_bf16 v[10:13], v[154:157], v[216:219], v[10:13]
	v_mfma_f32_16x16x32_bf16 v[10:13], v[158:161], v[220:223], v[10:13]
	v_mfma_f32_16x16x32_bf16 v[54:57], v[162:165], v[192:195], v[54:57]
	v_mfma_f32_16x16x32_bf16 v[54:57], v[166:169], v[196:199], v[54:57]
	v_mfma_f32_16x16x32_bf16 v[50:53], v[184:187], v[192:195], v[50:53]
	v_mfma_f32_16x16x32_bf16 v[50:53], v[188:191], v[196:199], v[50:53]
	v_mfma_f32_16x16x32_bf16 v[38:41], v[162:165], v[200:203], v[38:41]
	v_mfma_f32_16x16x32_bf16 v[38:41], v[166:169], v[204:207], v[38:41]
	v_mfma_f32_16x16x32_bf16 v[34:37], v[184:187], v[200:203], v[34:37]
	v_mfma_f32_16x16x32_bf16 v[34:37], v[188:191], v[204:207], v[34:37]
	v_mfma_f32_16x16x32_bf16 v[22:25], v[162:165], v[208:211], v[22:25]
	v_mfma_f32_16x16x32_bf16 v[22:25], v[166:169], v[212:215], v[22:25]
	v_mfma_f32_16x16x32_bf16 v[18:21], v[184:187], v[208:211], v[18:21]
	v_mfma_f32_16x16x32_bf16 v[18:21], v[188:191], v[212:215], v[18:21]
	s_barrier
	s_setprio 2
	v_mfma_f32_16x16x32_bf16 v[6:9], v[162:165], v[216:219], v[6:9]
	v_mfma_f32_16x16x32_bf16 v[6:9], v[166:169], v[220:223], v[6:9]
	v_mfma_f32_16x16x32_bf16 v[2:5], v[184:187], v[216:219], v[2:5]
	v_mfma_f32_16x16x32_bf16 v[2:5], v[188:191], v[220:223], v[2:5]
	s_setprio 0
	s_add_i32 s80, 0, 0x18000
	v_add_u32_e32 v140, s80, v173
	s_add_i32 s81, 0, 0x1c000
	ds_read_b128 v[130:133], v140
	ds_read_b128 v[134:137], v140 offset:1024
	ds_read_b128 v[154:157], v140 offset:2048
	ds_read_b128 v[158:161], v140 offset:3072
	v_add_u32_e32 v140, s81, v173
	ds_read_b128 v[162:165], v140
	ds_read_b128 v[166:169], v140 offset:1024
	ds_read_b128 v[184:187], v140 offset:2048
	ds_read_b128 v[188:191], v140 offset:3072
	s_mov_b32 m0, s58
	v_lshl_add_u64 v[226:227], v[224:225], 0, s[20:21]
	ds_read_b128 v[192:195], v178 offset:32768
	ds_read_b128 v[196:199], v178 offset:33792
	ds_read_b128 v[200:203], v178 offset:34816
	ds_read_b128 v[204:207], v178 offset:35840
	ds_read_b128 v[208:211], v178 offset:36864
	ds_read_b128 v[212:215], v178 offset:37888
	ds_read_b128 v[216:219], v178 offset:38912
	ds_read_b128 v[220:223], v178 offset:39936
	global_load_lds_dwordx4 v[226:227], off
	v_lshl_add_u64 v[226:227], v[224:225], 0, s[22:23]
	s_mov_b32 m0, s59
	s_nop 0
	global_load_lds_dwordx4 v[226:227], off
	s_waitcnt vmcnt(8)
	s_waitcnt lgkmcnt(0)
	s_barrier
	s_setprio 1
	s_waitcnt lgkmcnt(0)
	v_mfma_f32_16x16x32_bf16 v[126:129], v[130:133], v[192:195], v[126:129]
	v_mfma_f32_16x16x32_bf16 v[126:129], v[134:137], v[196:199], v[126:129]
	v_mfma_f32_16x16x32_bf16 v[122:125], v[154:157], v[192:195], v[122:125]
	v_mfma_f32_16x16x32_bf16 v[122:125], v[158:161], v[196:199], v[122:125]
	v_mfma_f32_16x16x32_bf16 v[110:113], v[130:133], v[200:203], v[110:113]
	v_mfma_f32_16x16x32_bf16 v[110:113], v[134:137], v[204:207], v[110:113]
	v_mfma_f32_16x16x32_bf16 v[106:109], v[154:157], v[200:203], v[106:109]
	v_mfma_f32_16x16x32_bf16 v[106:109], v[158:161], v[204:207], v[106:109]
	v_mfma_f32_16x16x32_bf16 v[94:97], v[130:133], v[208:211], v[94:97]
	v_mfma_f32_16x16x32_bf16 v[94:97], v[134:137], v[212:215], v[94:97]
	v_mfma_f32_16x16x32_bf16 v[90:93], v[154:157], v[208:211], v[90:93]
	v_mfma_f32_16x16x32_bf16 v[90:93], v[158:161], v[212:215], v[90:93]
	v_mfma_f32_16x16x32_bf16 v[78:81], v[130:133], v[216:219], v[78:81]
	v_mfma_f32_16x16x32_bf16 v[78:81], v[134:137], v[220:223], v[78:81]
	v_mfma_f32_16x16x32_bf16 v[74:77], v[154:157], v[216:219], v[74:77]
	v_mfma_f32_16x16x32_bf16 v[74:77], v[158:161], v[220:223], v[74:77]
	v_mfma_f32_16x16x32_bf16 v[118:121], v[162:165], v[192:195], v[118:121]
	v_mfma_f32_16x16x32_bf16 v[118:121], v[166:169], v[196:199], v[118:121]
	v_mfma_f32_16x16x32_bf16 v[114:117], v[184:187], v[192:195], v[114:117]
	v_mfma_f32_16x16x32_bf16 v[114:117], v[188:191], v[196:199], v[114:117]
	v_mfma_f32_16x16x32_bf16 v[102:105], v[162:165], v[200:203], v[102:105]
	v_mfma_f32_16x16x32_bf16 v[102:105], v[166:169], v[204:207], v[102:105]
	v_mfma_f32_16x16x32_bf16 v[98:101], v[184:187], v[200:203], v[98:101]
	v_mfma_f32_16x16x32_bf16 v[98:101], v[188:191], v[204:207], v[98:101]
	v_mfma_f32_16x16x32_bf16 v[86:89], v[162:165], v[208:211], v[86:89]
	v_mfma_f32_16x16x32_bf16 v[86:89], v[166:169], v[212:215], v[86:89]
	v_mfma_f32_16x16x32_bf16 v[82:85], v[184:187], v[208:211], v[82:85]
	v_mfma_f32_16x16x32_bf16 v[82:85], v[188:191], v[212:215], v[82:85]
	s_barrier
; #define PG8_STAGE(bufoff, gbase, voff) do { if constexpr (!pg8_noload<Epi>::value) { _Pragma("unroll") for (int _i = 0; _i < 2; ++_i) \
;         __builtin_amdgcn_global_load_lds((const unsigned*)((const char*)(gbase) + (size_t)_i * pstep + (voff)[0]), (PG8_LAS unsigned*)(lds + (bufoff) + ldsw + _i * 8192), 16, 0, 0); } } while (0)
; #define PG8_LDA(dst, b, h) do { _Pragma("unroll") for (int m = 0; m < 4; ++m) _Pragma("unroll") for (int k = 0; k < 2; ++k) dst[m][k] = *(const PG8_LAS bf16x8*)(lds + PG8_SA(b, h) + aoff + m * 2048 + k * 1024); } while (0)
; #define PG8_LDB(dst, b, h) do { _Pragma("unroll") for (int n = 0; n < 2; ++n) _Pragma("unroll") for (int k = 0; k < 2; ++k) dst[n][k] = *(const PG8_LAS bf16x8*)(lds + PG8_SB(b, h) + boff + n * 2048 + k * 1024); } while (0)
; #define PG8_MMA(ai, bj, At, Bt) do { __builtin_amdgcn_s_setprio(1); _Pragma("unroll") for (int m = 0; m < 4; ++m) _Pragma("unroll") for (int n = 0; n < 2; ++n) _Pragma("unroll") for (int k = 0; k < 2; ++k) \
;         acc[ai][bj][m][n] = __builtin_amdgcn_mfma_f32_16x16x32_bf16(Bt[n][k], At[m][k], acc[ai][bj][m][n], 0, 0, 0); __builtin_amdgcn_s_setprio(0); } while (0)
; #define PG8_WAIT_V(n) asm volatile("s_waitcnt vmcnt(" #n ")" ::: "memory")
; #define PG8_WAIT_L(n) asm volatile("s_waitcnt lgkmcnt(" #n ")" ::: "memory")
; #define PG8_BAR __builtin_amdgcn_s_barrier()
; #define PG8_SCHED __builtin_amdgcn_sched_barrier(0)
; template <class Epi, class Sched, bool ALIGN_EPI = false, bool SP2 = false, bool ABLK = false>
; __device__ __forceinline__ void gemm_phase(PG8_LAS unsigned char* lds, const Gemm g, const Sched& S, const Epi& E) {
;     ...
;             PG8_WAIT_V(8); PG8_WAIT_L(0); PG8_BAR; PG8_MMA(1, 0, At, B0); PG8_MMA(1, 1, At, B1); PG8_BAR; PG8_SCHED;
;             PG8_LDB(B0, 1, 0); PG8_LDB(B1, 1, 1); PG8_SCHED; PG8_LDA(At, 1, 0); PG8_STAGE(PG8_SA(0, 1), a2 + hstep, voffA);
;             PG8_WAIT_V(8); PG8_WAIT_L(0); PG8_BAR; PG8_MMA(0, 0, At, B0); PG8_MMA(0, 1, At, B1); PG8_BAR; PG8_SCHED;
;             PG8_LDA(At, 1, 1); PG8_STAGE(PG8_SB(1, 0), b3, voffB); PG8_STAGE(PG8_SB(1, 1), b3 + hstep, voffB); PG8_STAGE(PG8_SA(1, 0), a3, voffA);
;             PG8_WAIT_V(8); PG8_WAIT_L(0); PG8_BAR; PG8_MMA(1, 0, At, B0); PG8_MMA(1, 1, At, B1); PG8_BAR; PG8_SCHED;
	s_setprio 2
	v_mfma_f32_16x16x32_bf16 v[70:73], v[162:165], v[216:219], v[70:73]
	v_mfma_f32_16x16x32_bf16 v[70:73], v[166:169], v[220:223], v[70:73]
	v_mfma_f32_16x16x32_bf16 v[66:69], v[184:187], v[216:219], v[66:69]
	v_mfma_f32_16x16x32_bf16 v[66:69], v[188:191], v[220:223], v[66:69]
	s_setprio 0
	s_add_i32 s80, s80, s55
	v_lshl_add_u64 v[226:227], v[170:171], 0, s[30:31]
	s_mov_b32 m0, s80
	ds_read_b128 v[192:195], v178 offset:49152
	ds_read_b128 v[196:199], v178 offset:50176
	ds_read_b128 v[200:203], v178 offset:51200
	ds_read_b128 v[204:207], v178 offset:52224
	ds_read_b128 v[208:211], v178 offset:53248
	ds_read_b128 v[212:215], v178 offset:54272
	ds_read_b128 v[216:219], v178 offset:55296
	ds_read_b128 v[220:223], v178 offset:56320
	global_load_lds_dwordx4 v[226:227], off
	v_lshl_add_u64 v[226:227], v[170:171], 0, s[34:35]
	s_add_i32 m0, s80, 0x2000
	s_add_i32 s80, s81, s55
	global_load_lds_dwordx4 v[226:227], off
	v_lshl_add_u64 v[226:227], v[170:171], 0, s[36:37]
	s_mov_b32 m0, s80
	v_lshl_add_u64 v[170:171], v[170:171], 0, s[38:39]
	global_load_lds_dwordx4 v[226:227], off
	s_add_i32 m0, s80, 0x2000
	s_nop 0
	global_load_lds_dwordx4 v[170:171], off
	v_lshl_add_u64 v[170:171], v[224:225], 0, s[30:31]
	s_mov_b32 m0, s63
	s_nop 0
	global_load_lds_dwordx4 v[170:171], off
	v_lshl_add_u64 v[170:171], v[224:225], 0, s[34:35]
	s_mov_b32 m0, s73
	s_nop 0
	global_load_lds_dwordx4 v[170:171], off
	s_waitcnt vmcnt(8)
	s_waitcnt lgkmcnt(0)
	s_barrier
	s_setprio 1
	s_waitcnt lgkmcnt(0)
	v_mfma_f32_16x16x32_bf16 v[62:65], v[130:133], v[192:195], v[62:65]
	v_mfma_f32_16x16x32_bf16 v[62:65], v[134:137], v[196:199], v[62:65]
	v_mfma_f32_16x16x32_bf16 v[58:61], v[154:157], v[192:195], v[58:61]
	v_mfma_f32_16x16x32_bf16 v[58:61], v[158:161], v[196:199], v[58:61]
	v_mfma_f32_16x16x32_bf16 v[46:49], v[130:133], v[200:203], v[46:49]
	v_mfma_f32_16x16x32_bf16 v[46:49], v[134:137], v[204:207], v[46:49]
	v_mfma_f32_16x16x32_bf16 v[42:45], v[154:157], v[200:203], v[42:45]
	v_mfma_f32_16x16x32_bf16 v[42:45], v[158:161], v[204:207], v[42:45]
	v_mfma_f32_16x16x32_bf16 v[30:33], v[130:133], v[208:211], v[30:33]
	v_mfma_f32_16x16x32_bf16 v[30:33], v[134:137], v[212:215], v[30:33]
	v_mfma_f32_16x16x32_bf16 v[26:29], v[154:157], v[208:211], v[26:29]
	v_mfma_f32_16x16x32_bf16 v[26:29], v[158:161], v[212:215], v[26:29]
	v_mfma_f32_16x16x32_bf16 v[14:17], v[130:133], v[216:219], v[14:17]
	v_mfma_f32_16x16x32_bf16 v[14:17], v[134:137], v[220:223], v[14:17]
	v_mfma_f32_16x16x32_bf16 v[10:13], v[154:157], v[216:219], v[10:13]
	v_mfma_f32_16x16x32_bf16 v[10:13], v[158:161], v[220:223], v[10:13]
	v_mfma_f32_16x16x32_bf16 v[54:57], v[162:165], v[192:195], v[54:57]
	v_mfma_f32_16x16x32_bf16 v[54:57], v[166:169], v[196:199], v[54:57]
	v_mfma_f32_16x16x32_bf16 v[50:53], v[184:187], v[192:195], v[50:53]
	v_mfma_f32_16x16x32_bf16 v[50:53], v[188:191], v[196:199], v[50:53]
	v_mfma_f32_16x16x32_bf16 v[38:41], v[162:165], v[200:203], v[38:41]
	v_mfma_f32_16x16x32_bf16 v[38:41], v[166:169], v[204:207], v[38:41]
	v_mfma_f32_16x16x32_bf16 v[34:37], v[184:187], v[200:203], v[34:37]
	v_mfma_f32_16x16x32_bf16 v[34:37], v[188:191], v[204:207], v[34:37]
	v_mfma_f32_16x16x32_bf16 v[22:25], v[162:165], v[208:211], v[22:25]
	v_mfma_f32_16x16x32_bf16 v[22:25], v[166:169], v[212:215], v[22:25]
	v_mfma_f32_16x16x32_bf16 v[18:21], v[184:187], v[208:211], v[18:21]
	v_mfma_f32_16x16x32_bf16 v[18:21], v[188:191], v[212:215], v[18:21]
	s_barrier
	s_setprio 2
	v_mfma_f32_16x16x32_bf16 v[6:9], v[162:165], v[216:219], v[6:9]
	v_mfma_f32_16x16x32_bf16 v[6:9], v[166:169], v[220:223], v[6:9]
	v_mfma_f32_16x16x32_bf16 v[2:5], v[184:187], v[216:219], v[2:5]
	v_mfma_f32_16x16x32_bf16 v[2:5], v[188:191], v[220:223], v[2:5]
	s_setprio 0
	s_cmp_gt_u32 s94, 29
	s_mov_b32 s94, s26
	s_cbranch_scc1 .LBB0_1669

; #define PG8_STAGE(bufoff, gbase, voff) do { if constexpr (!pg8_noload<Epi>::value) { _Pragma("unroll") for (int _i = 0; _i < 2; ++_i) \
;         __builtin_amdgcn_global_load_lds((const unsigned*)((const char*)(gbase) + (size_t)_i * pstep + (voff)[0]), (PG8_LAS unsigned*)(lds + (bufoff) + ldsw + _i * 8192), 16, 0, 0); } } while (0)
; #define PG8_LDA(dst, b, h) do { _Pragma("unroll") for (int m = 0; m < 4; ++m) _Pragma("unroll") for (int k = 0; k < 2; ++k) dst[m][k] = *(const PG8_LAS bf16x8*)(lds + PG8_SA(b, h) + aoff + m * 2048 + k * 1024); } while (0)
; #define PG8_LDB(dst, b, h) do { _Pragma("unroll") for (int n = 0; n < 2; ++n) _Pragma("unroll") for (int k = 0; k < 2; ++k) dst[n][k] = *(const PG8_LAS bf16x8*)(lds + PG8_SB(b, h) + boff + n * 2048 + k * 1024); } while (0)
; #define PG8_MMA(ai, bj, At, Bt) do { __builtin_amdgcn_s_setprio(1); _Pragma("unroll") for (int m = 0; m < 4; ++m) _Pragma("unroll") for (int n = 0; n < 2; ++n) _Pragma("unroll") for (int k = 0; k < 2; ++k) \
;         acc[ai][bj][m][n] = __builtin_amdgcn_mfma_f32_16x16x32_bf16(Bt[n][k], At[m][k], acc[ai][bj][m][n], 0, 0, 0); __builtin_amdgcn_s_setprio(0); } while (0)
; #define PG8_WAIT_V(n) asm volatile("s_waitcnt vmcnt(" #n ")" ::: "memory")
; #define PG8_WAIT_L(n) asm volatile("s_waitcnt lgkmcnt(" #n ")" ::: "memory")
; template <class Epi, class Sched, bool ALIGN_EPI = false, bool SP2 = false, bool ABLK = false>
; __device__ __forceinline__ void gemm_phase(PG8_LAS unsigned char* lds, const Gemm g, const Sched& S, const Epi& E) {
;     ...
;             const char* a1 = cA + (size_t)(t + 1) * kstep;
;             const char* a2 = last ? nA : cA + (size_t)(t + 2) * kstep; const char* b2 = last ? nB : cB + (size_t)(t + 2) * kstepB;
;             const char* a3 = a2 + kstep; const char* b3 = b2 + kstepB;
;             if (last && has_next) S.a_ready(nxt);
;             if constexpr (SP2) {
;             PG8_LDB(B0, 0, 0); PG8_LDB(B1, 0, 1); PG8_SCHED; PG8_LDA(At, 0, 0); PG8_STAGE(PG8_SA(1, 1), a1 + hstep, voffA);
;             PG8_WAIT_V(8); PG8_WAIT_L(0); PG8_BAR; PG8_MMA(0, 0, At, B0); PG8_MMA(0, 1, At, B1); PG8_BAR; PG8_SCHED;
;             PG8_LDA(At, 0, 1); PG8_STAGE(PG8_SB(0, 0), b2, voffB); PG8_STAGE(PG8_SB(0, 1), b2 + hstep, voffB); PG8_STAGE(PG8_SA(0, 0), a2, voffA);
;             PG8_WAIT_V(8); PG8_WAIT_L(0); PG8_BAR; PG8_MMA(1, 0, At, B0); PG8_MMA(1, 1, At, B1); PG8_BAR; PG8_SCHED;
.LBB0_1997:
	ds_read_b128 v[130:133], v175
	ds_read_b128 v[134:137], v175 offset:1024
	ds_read_b128 v[138:141], v175 offset:2048
	ds_read_b128 v[142:145], v175 offset:3072
	ds_read_b128 v[146:149], v176
	ds_read_b128 v[150:153], v176 offset:1024
	ds_read_b128 v[154:157], v176 offset:2048
	ds_read_b128 v[158:161], v176 offset:3072
	s_add_i32 s43, s41, 2
	s_add_u32 s62, s52, 0xfff80800
	s_addc_u32 s63, s53, -1
	s_cmp_eq_u32 s3, s41
	s_cselect_b32 s63, s45, s63
	s_cselect_b32 s62, s44, s62
	s_cselect_b32 s77, s47, s39
	s_cselect_b32 s76, s46, s11
	v_lshl_add_u64 v[170:171], s[52:53], 0, v[166:167]
	s_add_i32 m0, s49, 0xc000
	ds_read_b128 v[184:187], v177
	ds_read_b128 v[188:191], v177 offset:1024
	ds_read_b128 v[192:195], v177 offset:2048
	ds_read_b128 v[196:199], v177 offset:3072
	ds_read_b128 v[200:203], v177 offset:4096
	ds_read_b128 v[204:207], v177 offset:5120
	ds_read_b128 v[208:211], v177 offset:6144
	ds_read_b128 v[212:215], v177 offset:7168
	global_load_lds_dwordx4 v[170:171], off
	v_lshl_add_u64 v[170:171], v[170:171], 0, s[12:13]
	s_add_i32 m0, s49, 0xe000
	s_nop 0
	global_load_lds_dwordx4 v[170:171], off
	s_waitcnt vmcnt(8)
	s_waitcnt lgkmcnt(0)
	s_barrier
	s_setprio 1
	s_waitcnt lgkmcnt(0)
	v_mfma_f32_16x16x32_bf16 v[126:129], v[130:133], v[184:187], v[126:129]
	v_mfma_f32_16x16x32_bf16 v[126:129], v[134:137], v[188:191], v[126:129]
	v_mfma_f32_16x16x32_bf16 v[122:125], v[138:141], v[184:187], v[122:125]
	v_mfma_f32_16x16x32_bf16 v[122:125], v[142:145], v[188:191], v[122:125]
	v_mfma_f32_16x16x32_bf16 v[110:113], v[130:133], v[192:195], v[110:113]
	v_mfma_f32_16x16x32_bf16 v[110:113], v[134:137], v[196:199], v[110:113]
	v_mfma_f32_16x16x32_bf16 v[106:109], v[138:141], v[192:195], v[106:109]
	v_mfma_f32_16x16x32_bf16 v[106:109], v[142:145], v[196:199], v[106:109]
	v_mfma_f32_16x16x32_bf16 v[94:97], v[130:133], v[200:203], v[94:97]
	v_mfma_f32_16x16x32_bf16 v[94:97], v[134:137], v[204:207], v[94:97]
	v_mfma_f32_16x16x32_bf16 v[90:93], v[138:141], v[200:203], v[90:93]
	v_mfma_f32_16x16x32_bf16 v[90:93], v[142:145], v[204:207], v[90:93]
	v_mfma_f32_16x16x32_bf16 v[78:81], v[130:133], v[208:211], v[78:81]
	v_mfma_f32_16x16x32_bf16 v[78:81], v[134:137], v[212:215], v[78:81]
	v_mfma_f32_16x16x32_bf16 v[74:77], v[138:141], v[208:211], v[74:77]
	v_mfma_f32_16x16x32_bf16 v[74:77], v[142:145], v[212:215], v[74:77]
	v_mfma_f32_16x16x32_bf16 v[118:121], v[146:149], v[184:187], v[118:121]
	v_mfma_f32_16x16x32_bf16 v[118:121], v[150:153], v[188:191], v[118:121]
	v_mfma_f32_16x16x32_bf16 v[114:117], v[154:157], v[184:187], v[114:117]
	v_mfma_f32_16x16x32_bf16 v[114:117], v[158:161], v[188:191], v[114:117]
	v_mfma_f32_16x16x32_bf16 v[102:105], v[146:149], v[192:195], v[102:105]
	v_mfma_f32_16x16x32_bf16 v[102:105], v[150:153], v[196:199], v[102:105]
	v_mfma_f32_16x16x32_bf16 v[98:101], v[154:157], v[192:195], v[98:101]
	v_mfma_f32_16x16x32_bf16 v[98:101], v[158:161], v[196:199], v[98:101]
	v_mfma_f32_16x16x32_bf16 v[86:89], v[146:149], v[200:203], v[86:89]
	v_mfma_f32_16x16x32_bf16 v[86:89], v[150:153], v[204:207], v[86:89]
	v_mfma_f32_16x16x32_bf16 v[82:85], v[154:157], v[200:203], v[82:85]
	v_mfma_f32_16x16x32_bf16 v[82:85], v[158:161], v[204:207], v[82:85]
	s_barrier
	s_setprio 2
	v_mfma_f32_16x16x32_bf16 v[70:73], v[146:149], v[208:211], v[70:73]
	v_mfma_f32_16x16x32_bf16 v[70:73], v[150:153], v[212:215], v[70:73]
	v_mfma_f32_16x16x32_bf16 v[66:69], v[154:157], v[208:211], v[66:69]
	v_mfma_f32_16x16x32_bf16 v[66:69], v[158:161], v[212:215], v[66:69]
	s_setprio 0
	s_add_i32 s41, s70, s57
	v_lshl_add_u64 v[170:171], s[76:77], 0, v[162:163]
	s_mov_b32 m0, s41
	ds_read_b128 v[184:187], v177 offset:16384
	ds_read_b128 v[188:191], v177 offset:17408
	ds_read_b128 v[192:195], v177 offset:18432
	ds_read_b128 v[196:199], v177 offset:19456
	ds_read_b128 v[200:203], v177 offset:20480
	ds_read_b128 v[204:207], v177 offset:21504
	ds_read_b128 v[208:211], v177 offset:22528
	ds_read_b128 v[212:215], v177 offset:23552
	global_load_lds_dwordx4 v[170:171], off
	v_lshl_add_u64 v[216:217], v[170:171], 0, s[12:13]
	s_add_i32 m0, s41, 0x2000
	s_add_i32 s41, s71, s57
	global_load_lds_dwordx4 v[216:217], off
	v_lshl_add_u64 v[216:217], v[170:171], 0, s[14:15]
	s_mov_b32 m0, s41
	s_nop 0
	global_load_lds_dwordx4 v[216:217], off
	v_lshl_add_u64 v[216:217], v[170:171], 0, s[16:17]
	s_add_i32 m0, s41, 0x2000
	s_nop 0
	global_load_lds_dwordx4 v[216:217], off
	v_lshl_add_u64 v[216:217], s[62:63], 0, v[162:163]
	s_mov_b32 m0, s49
	v_lshl_add_u64 v[218:219], v[216:217], 0, s[12:13]
	global_load_lds_dwordx4 v[216:217], off
	s_mov_b32 m0, s58
	s_nop 0
	global_load_lds_dwordx4 v[218:219], off
	s_waitcnt vmcnt(8)
	s_waitcnt lgkmcnt(0)
	s_barrier
; #define PG8_STAGE(bufoff, gbase, voff) do { if constexpr (!pg8_noload<Epi>::value) { _Pragma("unroll") for (int _i = 0; _i < 2; ++_i) \
;         __builtin_amdgcn_global_load_lds((const unsigned*)((const char*)(gbase) + (size_t)_i * pstep + (voff)[0]), (PG8_LAS unsigned*)(lds + (bufoff) + ldsw + _i * 8192), 16, 0, 0); } } while (0)
; #define PG8_LDA(dst, b, h) do { _Pragma("unroll") for (int m = 0; m < 4; ++m) _Pragma("unroll") for (int k = 0; k < 2; ++k) dst[m][k] = *(const PG8_LAS bf16x8*)(lds + PG8_SA(b, h) + aoff + m * 2048 + k * 1024); } while (0)
; #define PG8_LDB(dst, b, h) do { _Pragma("unroll") for (int n = 0; n < 2; ++n) _Pragma("unroll") for (int k = 0; k < 2; ++k) dst[n][k] = *(const PG8_LAS bf16x8*)(lds + PG8_SB(b, h) + boff + n * 2048 + k * 1024); } while (0)
; #define PG8_MMA(ai, bj, At, Bt) do { __builtin_amdgcn_s_setprio(1); _Pragma("unroll") for (int m = 0; m < 4; ++m) _Pragma("unroll") for (int n = 0; n < 2; ++n) _Pragma("unroll") for (int k = 0; k < 2; ++k) \
;         acc[ai][bj][m][n] = __builtin_amdgcn_mfma_f32_16x16x32_bf16(Bt[n][k], At[m][k], acc[ai][bj][m][n], 0, 0, 0); __builtin_amdgcn_s_setprio(0); } while (0)
; #define PG8_WAIT_V(n) asm volatile("s_waitcnt vmcnt(" #n ")" ::: "memory")
; #define PG8_WAIT_L(n) asm volatile("s_waitcnt lgkmcnt(" #n ")" ::: "memory")
; #define PG8_BAR __builtin_amdgcn_s_barrier()
; #define PG8_SCHED __builtin_amdgcn_sched_barrier(0)
; template <class Epi, class Sched, bool ALIGN_EPI = false, bool SP2 = false, bool ABLK = false>
; __device__ __forceinline__ void gemm_phase(PG8_LAS unsigned char* lds, const Gemm g, const Sched& S, const Epi& E) {
;     ...
;             PG8_WAIT_V(8); PG8_WAIT_L(0); PG8_BAR; PG8_MMA(1, 0, At, B0); PG8_MMA(1, 1, At, B1); PG8_BAR; PG8_SCHED;
;             PG8_LDB(B0, 1, 0); PG8_LDB(B1, 1, 1); PG8_SCHED; PG8_LDA(At, 1, 0); PG8_STAGE(PG8_SA(0, 1), a2 + hstep, voffA);
;             PG8_WAIT_V(8); PG8_WAIT_L(0); PG8_BAR; PG8_MMA(0, 0, At, B0); PG8_MMA(0, 1, At, B1); PG8_BAR; PG8_SCHED;
;             PG8_LDA(At, 1, 1); PG8_STAGE(PG8_SB(1, 0), b3, voffB); PG8_STAGE(PG8_SB(1, 1), b3 + hstep, voffB); PG8_STAGE(PG8_SA(1, 0), a3, voffA);
	s_setprio 1
	s_waitcnt lgkmcnt(0)
	v_mfma_f32_16x16x32_bf16 v[62:65], v[130:133], v[184:187], v[62:65]
	v_mfma_f32_16x16x32_bf16 v[62:65], v[134:137], v[188:191], v[62:65]
	v_mfma_f32_16x16x32_bf16 v[58:61], v[138:141], v[184:187], v[58:61]
	v_mfma_f32_16x16x32_bf16 v[58:61], v[142:145], v[188:191], v[58:61]
	v_mfma_f32_16x16x32_bf16 v[46:49], v[130:133], v[192:195], v[46:49]
	v_mfma_f32_16x16x32_bf16 v[46:49], v[134:137], v[196:199], v[46:49]
	v_mfma_f32_16x16x32_bf16 v[42:45], v[138:141], v[192:195], v[42:45]
	v_mfma_f32_16x16x32_bf16 v[42:45], v[142:145], v[196:199], v[42:45]
	v_mfma_f32_16x16x32_bf16 v[30:33], v[130:133], v[200:203], v[30:33]
	v_mfma_f32_16x16x32_bf16 v[30:33], v[134:137], v[204:207], v[30:33]
	v_mfma_f32_16x16x32_bf16 v[26:29], v[138:141], v[200:203], v[26:29]
	v_mfma_f32_16x16x32_bf16 v[26:29], v[142:145], v[204:207], v[26:29]
	v_mfma_f32_16x16x32_bf16 v[14:17], v[130:133], v[208:211], v[14:17]
	v_mfma_f32_16x16x32_bf16 v[14:17], v[134:137], v[212:215], v[14:17]
	v_mfma_f32_16x16x32_bf16 v[10:13], v[138:141], v[208:211], v[10:13]
	v_mfma_f32_16x16x32_bf16 v[10:13], v[142:145], v[212:215], v[10:13]
	v_mfma_f32_16x16x32_bf16 v[54:57], v[146:149], v[184:187], v[54:57]
	v_mfma_f32_16x16x32_bf16 v[54:57], v[150:153], v[188:191], v[54:57]
	v_mfma_f32_16x16x32_bf16 v[50:53], v[154:157], v[184:187], v[50:53]
	v_mfma_f32_16x16x32_bf16 v[50:53], v[158:161], v[188:191], v[50:53]
	v_mfma_f32_16x16x32_bf16 v[38:41], v[146:149], v[192:195], v[38:41]
	v_mfma_f32_16x16x32_bf16 v[38:41], v[150:153], v[196:199], v[38:41]
	v_mfma_f32_16x16x32_bf16 v[34:37], v[154:157], v[192:195], v[34:37]
	v_mfma_f32_16x16x32_bf16 v[34:37], v[158:161], v[196:199], v[34:37]
	v_mfma_f32_16x16x32_bf16 v[22:25], v[146:149], v[200:203], v[22:25]
	v_mfma_f32_16x16x32_bf16 v[22:25], v[150:153], v[204:207], v[22:25]
	v_mfma_f32_16x16x32_bf16 v[18:21], v[154:157], v[200:203], v[18:21]
	v_mfma_f32_16x16x32_bf16 v[18:21], v[158:161], v[204:207], v[18:21]
	s_barrier
	s_setprio 2
	v_mfma_f32_16x16x32_bf16 v[6:9], v[146:149], v[208:211], v[6:9]
	v_mfma_f32_16x16x32_bf16 v[6:9], v[150:153], v[212:215], v[6:9]
	v_mfma_f32_16x16x32_bf16 v[2:5], v[154:157], v[208:211], v[2:5]
	v_mfma_f32_16x16x32_bf16 v[2:5], v[158:161], v[212:215], v[2:5]
	s_setprio 0
	s_add_i32 s41, 0, 0x18000
	s_add_i32 s62, 0, 0x1c000
	v_add_u32_e32 v142, s41, v1
	v_add_u32_e32 v158, s62, v1
	ds_read_b128 v[130:133], v142
	ds_read_b128 v[134:137], v142 offset:1024
	ds_read_b128 v[138:141], v142 offset:2048
	ds_read_b128 v[142:145], v142 offset:3072
	ds_read_b128 v[146:149], v158
	ds_read_b128 v[150:153], v158 offset:1024
	ds_read_b128 v[154:157], v158 offset:2048
	ds_read_b128 v[158:161], v158 offset:3072
	s_mov_b32 m0, s59
	v_lshl_add_u64 v[218:219], v[216:217], 0, s[14:15]
	ds_read_b128 v[184:187], v177 offset:32768
	ds_read_b128 v[188:191], v177 offset:33792
	ds_read_b128 v[192:195], v177 offset:34816
	ds_read_b128 v[196:199], v177 offset:35840
	ds_read_b128 v[200:203], v177 offset:36864
	ds_read_b128 v[204:207], v177 offset:37888
	ds_read_b128 v[208:211], v177 offset:38912
	ds_read_b128 v[212:215], v177 offset:39936
	global_load_lds_dwordx4 v[218:219], off
	v_lshl_add_u64 v[218:219], v[216:217], 0, s[16:17]
	s_mov_b32 m0, s60
	s_nop 0
	global_load_lds_dwordx4 v[218:219], off
	s_waitcnt vmcnt(8)
	s_waitcnt lgkmcnt(0)
	s_barrier
	s_setprio 1
	s_waitcnt lgkmcnt(0)
	v_mfma_f32_16x16x32_bf16 v[126:129], v[130:133], v[184:187], v[126:129]
	v_mfma_f32_16x16x32_bf16 v[126:129], v[134:137], v[188:191], v[126:129]
	v_mfma_f32_16x16x32_bf16 v[122:125], v[138:141], v[184:187], v[122:125]
	v_mfma_f32_16x16x32_bf16 v[122:125], v[142:145], v[188:191], v[122:125]
	v_mfma_f32_16x16x32_bf16 v[110:113], v[130:133], v[192:195], v[110:113]
	v_mfma_f32_16x16x32_bf16 v[110:113], v[134:137], v[196:199], v[110:113]
	v_mfma_f32_16x16x32_bf16 v[106:109], v[138:141], v[192:195], v[106:109]
	v_mfma_f32_16x16x32_bf16 v[106:109], v[142:145], v[196:199], v[106:109]
	v_mfma_f32_16x16x32_bf16 v[94:97], v[130:133], v[200:203], v[94:97]
	v_mfma_f32_16x16x32_bf16 v[94:97], v[134:137], v[204:207], v[94:97]
	v_mfma_f32_16x16x32_bf16 v[90:93], v[138:141], v[200:203], v[90:93]
	v_mfma_f32_16x16x32_bf16 v[90:93], v[142:145], v[204:207], v[90:93]
	v_mfma_f32_16x16x32_bf16 v[78:81], v[130:133], v[208:211], v[78:81]
	v_mfma_f32_16x16x32_bf16 v[78:81], v[134:137], v[212:215], v[78:81]
	v_mfma_f32_16x16x32_bf16 v[74:77], v[138:141], v[208:211], v[74:77]
	v_mfma_f32_16x16x32_bf16 v[74:77], v[142:145], v[212:215], v[74:77]
	v_mfma_f32_16x16x32_bf16 v[118:121], v[146:149], v[184:187], v[118:121]
	v_mfma_f32_16x16x32_bf16 v[118:121], v[150:153], v[188:191], v[118:121]
	v_mfma_f32_16x16x32_bf16 v[114:117], v[154:157], v[184:187], v[114:117]
	v_mfma_f32_16x16x32_bf16 v[114:117], v[158:161], v[188:191], v[114:117]
	v_mfma_f32_16x16x32_bf16 v[102:105], v[146:149], v[192:195], v[102:105]
	v_mfma_f32_16x16x32_bf16 v[102:105], v[150:153], v[196:199], v[102:105]
	v_mfma_f32_16x16x32_bf16 v[98:101], v[154:157], v[192:195], v[98:101]
	v_mfma_f32_16x16x32_bf16 v[98:101], v[158:161], v[196:199], v[98:101]
	v_mfma_f32_16x16x32_bf16 v[86:89], v[146:149], v[200:203], v[86:89]
	v_mfma_f32_16x16x32_bf16 v[86:89], v[150:153], v[204:207], v[86:89]
	v_mfma_f32_16x16x32_bf16 v[82:85], v[154:157], v[200:203], v[82:85]
	v_mfma_f32_16x16x32_bf16 v[82:85], v[158:161], v[204:207], v[82:85]
	s_barrier
; #define PG8_STAGE(bufoff, gbase, voff) do { if constexpr (!pg8_noload<Epi>::value) { _Pragma("unroll") for (int _i = 0; _i < 2; ++_i) \
;         __builtin_amdgcn_global_load_lds((const unsigned*)((const char*)(gbase) + (size_t)_i * pstep + (voff)[0]), (PG8_LAS unsigned*)(lds + (bufoff) + ldsw + _i * 8192), 16, 0, 0); } } while (0)
; #define PG8_LDA(dst, b, h) do { _Pragma("unroll") for (int m = 0; m < 4; ++m) _Pragma("unroll") for (int k = 0; k < 2; ++k) dst[m][k] = *(const PG8_LAS bf16x8*)(lds + PG8_SA(b, h) + aoff + m * 2048 + k * 1024); } while (0)
; #define PG8_LDB(dst, b, h) do { _Pragma("unroll") for (int n = 0; n < 2; ++n) _Pragma("unroll") for (int k = 0; k < 2; ++k) dst[n][k] = *(const PG8_LAS bf16x8*)(lds + PG8_SB(b, h) + boff + n * 2048 + k * 1024); } while (0)
; #define PG8_MMA(ai, bj, At, Bt) do { __builtin_amdgcn_s_setprio(1); _Pragma("unroll") for (int m = 0; m < 4; ++m) _Pragma("unroll") for (int n = 0; n < 2; ++n) _Pragma("unroll") for (int k = 0; k < 2; ++k) \
;         acc[ai][bj][m][n] = __builtin_amdgcn_mfma_f32_16x16x32_bf16(Bt[n][k], At[m][k], acc[ai][bj][m][n], 0, 0, 0); __builtin_amdgcn_s_setprio(0); } while (0)
; #define PG8_WAIT_V(n) asm volatile("s_waitcnt vmcnt(" #n ")" ::: "memory")
; #define PG8_WAIT_L(n) asm volatile("s_waitcnt lgkmcnt(" #n ")" ::: "memory")
; #define PG8_BAR __builtin_amdgcn_s_barrier()
; #define PG8_SCHED __builtin_amdgcn_sched_barrier(0)
; template <class Epi, class Sched, bool ALIGN_EPI = false, bool SP2 = false, bool ABLK = false>
; __device__ __forceinline__ void gemm_phase(PG8_LAS unsigned char* lds, const Gemm g, const Sched& S, const Epi& E) {
;     ...
;             PG8_WAIT_V(8); PG8_WAIT_L(0); PG8_BAR; PG8_MMA(1, 0, At, B0); PG8_MMA(1, 1, At, B1); PG8_BAR; PG8_SCHED;
;             PG8_LDB(B0, 1, 0); PG8_LDB(B1, 1, 1); PG8_SCHED; PG8_LDA(At, 1, 0); PG8_STAGE(PG8_SA(0, 1), a2 + hstep, voffA);
;             PG8_WAIT_V(8); PG8_WAIT_L(0); PG8_BAR; PG8_MMA(0, 0, At, B0); PG8_MMA(0, 1, At, B1); PG8_BAR; PG8_SCHED;
;             PG8_LDA(At, 1, 1); PG8_STAGE(PG8_SB(1, 0), b3, voffB); PG8_STAGE(PG8_SB(1, 1), b3 + hstep, voffB); PG8_STAGE(PG8_SA(1, 0), a3, voffA);
;             PG8_WAIT_V(8); PG8_WAIT_L(0); PG8_BAR; PG8_MMA(1, 0, At, B0); PG8_MMA(1, 1, At, B1); PG8_BAR; PG8_SCHED;
	s_setprio 2
	v_mfma_f32_16x16x32_bf16 v[70:73], v[146:149], v[208:211], v[70:73]
	v_mfma_f32_16x16x32_bf16 v[70:73], v[150:153], v[212:215], v[70:73]
	v_mfma_f32_16x16x32_bf16 v[66:69], v[154:157], v[208:211], v[66:69]
	v_mfma_f32_16x16x32_bf16 v[66:69], v[158:161], v[212:215], v[66:69]
	s_setprio 0
	s_add_i32 s41, s41, s57
	v_lshl_add_u64 v[218:219], v[170:171], 0, s[24:25]
	s_mov_b32 m0, s41
	ds_read_b128 v[184:187], v177 offset:49152
	ds_read_b128 v[188:191], v177 offset:50176
	ds_read_b128 v[192:195], v177 offset:51200
	ds_read_b128 v[196:199], v177 offset:52224
	ds_read_b128 v[200:203], v177 offset:53248
	ds_read_b128 v[204:207], v177 offset:54272
	ds_read_b128 v[208:211], v177 offset:55296
	ds_read_b128 v[212:215], v177 offset:56320
	global_load_lds_dwordx4 v[218:219], off
	v_lshl_add_u64 v[218:219], v[170:171], 0, s[26:27]
	s_add_i32 m0, s41, 0x2000
	s_add_i32 s41, s62, s57
	global_load_lds_dwordx4 v[218:219], off
	v_lshl_add_u64 v[218:219], v[170:171], 0, s[28:29]
	s_mov_b32 m0, s41
	v_lshl_add_u64 v[170:171], v[170:171], 0, s[30:31]
	global_load_lds_dwordx4 v[218:219], off
	s_add_i32 m0, s41, 0x2000
	s_nop 0
	global_load_lds_dwordx4 v[170:171], off
	v_lshl_add_u64 v[170:171], v[216:217], 0, s[24:25]
	s_mov_b32 m0, s65
	s_nop 0
	global_load_lds_dwordx4 v[170:171], off
	v_lshl_add_u64 v[170:171], v[216:217], 0, s[26:27]
	s_mov_b32 m0, s66
	s_nop 0
	global_load_lds_dwordx4 v[170:171], off
	s_waitcnt vmcnt(8)
	s_waitcnt lgkmcnt(0)
	s_barrier
	s_setprio 1
	s_waitcnt lgkmcnt(0)
	v_mfma_f32_16x16x32_bf16 v[62:65], v[130:133], v[184:187], v[62:65]
	v_mfma_f32_16x16x32_bf16 v[62:65], v[134:137], v[188:191], v[62:65]
	v_mfma_f32_16x16x32_bf16 v[58:61], v[138:141], v[184:187], v[58:61]
	v_mfma_f32_16x16x32_bf16 v[58:61], v[142:145], v[188:191], v[58:61]
	v_mfma_f32_16x16x32_bf16 v[46:49], v[130:133], v[192:195], v[46:49]
	v_mfma_f32_16x16x32_bf16 v[46:49], v[134:137], v[196:199], v[46:49]
	v_mfma_f32_16x16x32_bf16 v[42:45], v[138:141], v[192:195], v[42:45]
	v_mfma_f32_16x16x32_bf16 v[42:45], v[142:145], v[196:199], v[42:45]
	v_mfma_f32_16x16x32_bf16 v[30:33], v[130:133], v[200:203], v[30:33]
	v_mfma_f32_16x16x32_bf16 v[30:33], v[134:137], v[204:207], v[30:33]
	v_mfma_f32_16x16x32_bf16 v[26:29], v[138:141], v[200:203], v[26:29]
	v_mfma_f32_16x16x32_bf16 v[26:29], v[142:145], v[204:207], v[26:29]
	v_mfma_f32_16x16x32_bf16 v[14:17], v[130:133], v[208:211], v[14:17]
	v_mfma_f32_16x16x32_bf16 v[14:17], v[134:137], v[212:215], v[14:17]
	v_mfma_f32_16x16x32_bf16 v[10:13], v[138:141], v[208:211], v[10:13]
	v_mfma_f32_16x16x32_bf16 v[10:13], v[142:145], v[212:215], v[10:13]
	v_mfma_f32_16x16x32_bf16 v[54:57], v[146:149], v[184:187], v[54:57]
	v_mfma_f32_16x16x32_bf16 v[54:57], v[150:153], v[188:191], v[54:57]
	v_mfma_f32_16x16x32_bf16 v[50:53], v[154:157], v[184:187], v[50:53]
	v_mfma_f32_16x16x32_bf16 v[50:53], v[158:161], v[188:191], v[50:53]
	v_mfma_f32_16x16x32_bf16 v[38:41], v[146:149], v[192:195], v[38:41]
	v_mfma_f32_16x16x32_bf16 v[38:41], v[150:153], v[196:199], v[38:41]
	v_mfma_f32_16x16x32_bf16 v[34:37], v[154:157], v[192:195], v[34:37]
	v_mfma_f32_16x16x32_bf16 v[34:37], v[158:161], v[196:199], v[34:37]
	v_mfma_f32_16x16x32_bf16 v[22:25], v[146:149], v[200:203], v[22:25]
	v_mfma_f32_16x16x32_bf16 v[22:25], v[150:153], v[204:207], v[22:25]
	v_mfma_f32_16x16x32_bf16 v[18:21], v[154:157], v[200:203], v[18:21]
	v_mfma_f32_16x16x32_bf16 v[18:21], v[158:161], v[204:207], v[18:21]
	s_barrier
	s_setprio 2
	v_mfma_f32_16x16x32_bf16 v[6:9], v[146:149], v[208:211], v[6:9]
	v_mfma_f32_16x16x32_bf16 v[6:9], v[150:153], v[212:215], v[6:9]
	v_mfma_f32_16x16x32_bf16 v[2:5], v[154:157], v[208:211], v[2:5]
	v_mfma_f32_16x16x32_bf16 v[2:5], v[158:161], v[212:215], v[2:5]
	s_setprio 0
	s_add_u32 s52, s52, 0x1000
	s_addc_u32 s53, s53, 0
	s_add_u32 s11, s11, 0x1000
	s_addc_u32 s39, s39, 0
	s_cmp_ge_i32 s43, s75
	s_mov_b32 s41, s43
	s_cbranch_scc0 .LBB0_1997
	s_and_b64 vcc, exec, s[34:35]
	s_cbranch_vccnz .LBB0_2002
	s_lshl_b32 s11, s2, 8
	s_cmp_gt_i32 s2, 63
	s_mov_b64 s[52:53], -1
	s_cbranch_scc1 .LBB0_2003

; #define PG8_STAGE(bufoff, gbase, voff) do { if constexpr (!pg8_noload<Epi>::value) { _Pragma("unroll") for (int _i = 0; _i < 2; ++_i) \
;         __builtin_amdgcn_global_load_lds((const unsigned*)((const char*)(gbase) + (size_t)_i * pstep + (voff)[0]), (PG8_LAS unsigned*)(lds + (bufoff) + ldsw + _i * 8192), 16, 0, 0); } } while (0)
; #define PG8_LDA(dst, b, h) do { _Pragma("unroll") for (int m = 0; m < 4; ++m) _Pragma("unroll") for (int k = 0; k < 2; ++k) dst[m][k] = *(const PG8_LAS bf16x8*)(lds + PG8_SA(b, h) + aoff + m * 2048 + k * 1024); } while (0)
; #define PG8_LDB(dst, b, h) do { _Pragma("unroll") for (int n = 0; n < 2; ++n) _Pragma("unroll") for (int k = 0; k < 2; ++k) dst[n][k] = *(const PG8_LAS bf16x8*)(lds + PG8_SB(b, h) + boff + n * 2048 + k * 1024); } while (0)
; #define PG8_MMA(ai, bj, At, Bt) do { __builtin_amdgcn_s_setprio(1); _Pragma("unroll") for (int m = 0; m < 4; ++m) _Pragma("unroll") for (int n = 0; n < 2; ++n) _Pragma("unroll") for (int k = 0; k < 2; ++k) \
;         acc[ai][bj][m][n] = __builtin_amdgcn_mfma_f32_16x16x32_bf16(Bt[n][k], At[m][k], acc[ai][bj][m][n], 0, 0, 0); __builtin_amdgcn_s_setprio(0); } while (0)
; #define PG8_WAIT_V(n) asm volatile("s_waitcnt vmcnt(" #n ")" ::: "memory")
; #define PG8_WAIT_L(n) asm volatile("s_waitcnt lgkmcnt(" #n ")" ::: "memory")
; template <class Epi, class Sched, bool ALIGN_EPI = false, bool SP2 = false, bool ABLK = false>
; __device__ __forceinline__ void gemm_phase(PG8_LAS unsigned char* lds, const Gemm g, const Sched& S, const Epi& E) {
;     ...
;             const char* a1 = cA + (size_t)(t + 1) * kstep;
;             const char* a2 = last ? nA : cA + (size_t)(t + 2) * kstep; const char* b2 = last ? nB : cB + (size_t)(t + 2) * kstepB;
;             const char* a3 = a2 + kstep; const char* b3 = b2 + kstepB;
;             if (last && has_next) S.a_ready(nxt);
;             if constexpr (SP2) {
;             PG8_LDB(B0, 0, 0); PG8_LDB(B1, 0, 1); PG8_SCHED; PG8_LDA(At, 0, 0); PG8_STAGE(PG8_SA(1, 1), a1 + hstep, voffA);
;             PG8_WAIT_V(8); PG8_WAIT_L(0); PG8_BAR; PG8_MMA(0, 0, At, B0); PG8_MMA(0, 1, At, B1); PG8_BAR; PG8_SCHED;
;             PG8_LDA(At, 0, 1); PG8_STAGE(PG8_SB(0, 0), b2, voffB); PG8_STAGE(PG8_SB(0, 1), b2 + hstep, voffB); PG8_STAGE(PG8_SA(0, 0), a2, voffA);
;             PG8_WAIT_V(8); PG8_WAIT_L(0); PG8_BAR; PG8_MMA(1, 0, At, B0); PG8_MMA(1, 1, At, B1); PG8_BAR; PG8_SCHED;
.LBB0_2119:
	s_or_b32 s30, s59, 1
	s_lshl_b64 s[14:15], s[30:31], 11
	s_add_u32 s14, s82, s14
	v_add_u32_e32 v133, s71, v148
	s_addc_u32 s15, s83, s15
	s_add_i32 s30, s59, 2
	ds_read_b128 v[144:147], v133
	ds_read_b128 v[184:187], v133 offset:1024
	ds_read_b128 v[188:191], v133 offset:2048
	ds_read_b128 v[192:195], v133 offset:3072
	v_add_u32_e32 v133, s73, v148
	s_lshl_b64 s[34:35], s[30:31], 11
	ds_read_b128 v[196:199], v133
	ds_read_b128 v[200:203], v133 offset:1024
	ds_read_b128 v[204:207], v133 offset:2048
	ds_read_b128 v[208:211], v133 offset:3072
	s_add_u32 s96, s82, s34
	s_addc_u32 s97, s83, s35
	s_and_b64 s[94:95], s[92:93], exec
	s_cselect_b32 s95, s97, s77
	s_cselect_b32 s94, s96, s28
	s_add_u32 s96, s88, s34
	s_addc_u32 s97, s89, s35
	s_and_b64 s[34:35], s[92:93], exec
	s_cselect_b32 s35, s97, s29
	s_cselect_b32 s34, s96, s75
	v_lshl_add_u64 v[180:181], s[14:15], 0, v[130:131]
	v_lshl_add_u64 v[244:245], v[180:181], 0, s[24:25]
	s_add_i32 m0, s17, 0xc000
	ds_read_b128 v[212:215], v168
	ds_read_b128 v[216:219], v168 offset:1024
	ds_read_b128 v[220:223], v168 offset:2048
	ds_read_b128 v[224:227], v168 offset:3072
	ds_read_b128 v[228:231], v168 offset:4096
	ds_read_b128 v[232:235], v168 offset:5120
	ds_read_b128 v[236:239], v168 offset:6144
	ds_read_b128 v[240:243], v168 offset:7168
	global_load_lds_dwordx4 v[244:245], off
	v_lshl_add_u64 v[180:181], v[180:181], 0, s[26:27]
	s_add_i32 m0, s17, 0xe000
	s_nop 0
	global_load_lds_dwordx4 v[180:181], off
	s_waitcnt vmcnt(8)
	s_waitcnt lgkmcnt(0)
	s_barrier
	s_setprio 1
	s_waitcnt lgkmcnt(0)
	v_mfma_f32_16x16x32_bf16 v[126:129], v[144:147], v[212:215], v[126:129]
	v_mfma_f32_16x16x32_bf16 v[126:129], v[184:187], v[216:219], v[126:129]
	v_mfma_f32_16x16x32_bf16 v[122:125], v[188:191], v[212:215], v[122:125]
	v_mfma_f32_16x16x32_bf16 v[122:125], v[192:195], v[216:219], v[122:125]
	v_mfma_f32_16x16x32_bf16 v[110:113], v[144:147], v[220:223], v[110:113]
	v_mfma_f32_16x16x32_bf16 v[110:113], v[184:187], v[224:227], v[110:113]
	v_mfma_f32_16x16x32_bf16 v[106:109], v[188:191], v[220:223], v[106:109]
	v_mfma_f32_16x16x32_bf16 v[106:109], v[192:195], v[224:227], v[106:109]
	v_mfma_f32_16x16x32_bf16 v[94:97], v[144:147], v[228:231], v[94:97]
	v_mfma_f32_16x16x32_bf16 v[94:97], v[184:187], v[232:235], v[94:97]
	v_mfma_f32_16x16x32_bf16 v[90:93], v[188:191], v[228:231], v[90:93]
	v_mfma_f32_16x16x32_bf16 v[90:93], v[192:195], v[232:235], v[90:93]
	v_mfma_f32_16x16x32_bf16 v[78:81], v[144:147], v[236:239], v[78:81]
	v_mfma_f32_16x16x32_bf16 v[78:81], v[184:187], v[240:243], v[78:81]
	v_mfma_f32_16x16x32_bf16 v[74:77], v[188:191], v[236:239], v[74:77]
	v_mfma_f32_16x16x32_bf16 v[74:77], v[192:195], v[240:243], v[74:77]
	v_mfma_f32_16x16x32_bf16 v[118:121], v[196:199], v[212:215], v[118:121]
	v_mfma_f32_16x16x32_bf16 v[118:121], v[200:203], v[216:219], v[118:121]
	v_mfma_f32_16x16x32_bf16 v[114:117], v[204:207], v[212:215], v[114:117]
	v_mfma_f32_16x16x32_bf16 v[114:117], v[208:211], v[216:219], v[114:117]
	v_mfma_f32_16x16x32_bf16 v[102:105], v[196:199], v[220:223], v[102:105]
	v_mfma_f32_16x16x32_bf16 v[102:105], v[200:203], v[224:227], v[102:105]
	v_mfma_f32_16x16x32_bf16 v[98:101], v[204:207], v[220:223], v[98:101]
	v_mfma_f32_16x16x32_bf16 v[98:101], v[208:211], v[224:227], v[98:101]
	v_mfma_f32_16x16x32_bf16 v[86:89], v[196:199], v[228:231], v[86:89]
	v_mfma_f32_16x16x32_bf16 v[86:89], v[200:203], v[232:235], v[86:89]
	v_mfma_f32_16x16x32_bf16 v[82:85], v[204:207], v[228:231], v[82:85]
	v_mfma_f32_16x16x32_bf16 v[82:85], v[208:211], v[232:235], v[82:85]
	s_barrier
	s_setprio 2
	v_mfma_f32_16x16x32_bf16 v[70:73], v[196:199], v[236:239], v[70:73]
	v_mfma_f32_16x16x32_bf16 v[70:73], v[200:203], v[240:243], v[70:73]
	v_mfma_f32_16x16x32_bf16 v[66:69], v[204:207], v[236:239], v[66:69]
	v_mfma_f32_16x16x32_bf16 v[66:69], v[208:211], v[240:243], v[66:69]
	s_setprio 0
	s_add_i32 s14, s71, s3
	v_lshl_add_u64 v[180:181], s[34:35], 0, v[130:131]
	s_mov_b32 m0, s14
	ds_read_b128 v[212:215], v168 offset:16384
	ds_read_b128 v[216:219], v168 offset:17408
	ds_read_b128 v[220:223], v168 offset:18432
	ds_read_b128 v[224:227], v168 offset:19456
	ds_read_b128 v[228:231], v168 offset:20480
	ds_read_b128 v[232:235], v168 offset:21504
	ds_read_b128 v[236:239], v168 offset:22528
	ds_read_b128 v[240:243], v168 offset:23552
	global_load_lds_dwordx4 v[180:181], off
	v_lshl_add_u64 v[244:245], v[180:181], 0, s[22:23]
	s_add_i32 m0, s14, 0x2000
	s_add_i32 s14, s73, s3
	global_load_lds_dwordx4 v[244:245], off
	v_lshl_add_u64 v[244:245], v[180:181], 0, s[24:25]
	s_mov_b32 m0, s14
	s_nop 0
	global_load_lds_dwordx4 v[244:245], off
	v_lshl_add_u64 v[244:245], v[180:181], 0, s[26:27]
	s_add_i32 m0, s14, 0x2000
	s_nop 0
	global_load_lds_dwordx4 v[244:245], off
	v_lshl_add_u64 v[244:245], s[94:95], 0, v[130:131]
	s_mov_b32 m0, s17
	v_lshl_add_u64 v[246:247], v[244:245], 0, s[22:23]
	global_load_lds_dwordx4 v[244:245], off
	s_mov_b32 m0, s56
	s_nop 0
	global_load_lds_dwordx4 v[246:247], off
	s_waitcnt vmcnt(8)
	s_waitcnt lgkmcnt(0)
	s_barrier
; #define PG8_STAGE(bufoff, gbase, voff) do { if constexpr (!pg8_noload<Epi>::value) { _Pragma("unroll") for (int _i = 0; _i < 2; ++_i) \
;         __builtin_amdgcn_global_load_lds((const unsigned*)((const char*)(gbase) + (size_t)_i * pstep + (voff)[0]), (PG8_LAS unsigned*)(lds + (bufoff) + ldsw + _i * 8192), 16, 0, 0); } } while (0)
; #define PG8_LDA(dst, b, h) do { _Pragma("unroll") for (int m = 0; m < 4; ++m) _Pragma("unroll") for (int k = 0; k < 2; ++k) dst[m][k] = *(const PG8_LAS bf16x8*)(lds + PG8_SA(b, h) + aoff + m * 2048 + k * 1024); } while (0)
; #define PG8_LDB(dst, b, h) do { _Pragma("unroll") for (int n = 0; n < 2; ++n) _Pragma("unroll") for (int k = 0; k < 2; ++k) dst[n][k] = *(const PG8_LAS bf16x8*)(lds + PG8_SB(b, h) + boff + n * 2048 + k * 1024); } while (0)
; #define PG8_MMA(ai, bj, At, Bt) do { __builtin_amdgcn_s_setprio(1); _Pragma("unroll") for (int m = 0; m < 4; ++m) _Pragma("unroll") for (int n = 0; n < 2; ++n) _Pragma("unroll") for (int k = 0; k < 2; ++k) \
;         acc[ai][bj][m][n] = __builtin_amdgcn_mfma_f32_16x16x32_bf16(Bt[n][k], At[m][k], acc[ai][bj][m][n], 0, 0, 0); __builtin_amdgcn_s_setprio(0); } while (0)
; #define PG8_WAIT_V(n) asm volatile("s_waitcnt vmcnt(" #n ")" ::: "memory")
; #define PG8_WAIT_L(n) asm volatile("s_waitcnt lgkmcnt(" #n ")" ::: "memory")
; #define PG8_BAR __builtin_amdgcn_s_barrier()
; #define PG8_SCHED __builtin_amdgcn_sched_barrier(0)
; template <class Epi, class Sched, bool ALIGN_EPI = false, bool SP2 = false, bool ABLK = false>
; __device__ __forceinline__ void gemm_phase(PG8_LAS unsigned char* lds, const Gemm g, const Sched& S, const Epi& E) {
;     ...
;             PG8_WAIT_V(8); PG8_WAIT_L(0); PG8_BAR; PG8_MMA(1, 0, At, B0); PG8_MMA(1, 1, At, B1); PG8_BAR; PG8_SCHED;
;             PG8_LDB(B0, 1, 0); PG8_LDB(B1, 1, 1); PG8_SCHED; PG8_LDA(At, 1, 0); PG8_STAGE(PG8_SA(0, 1), a2 + hstep, voffA);
;             PG8_WAIT_V(8); PG8_WAIT_L(0); PG8_BAR; PG8_MMA(0, 0, At, B0); PG8_MMA(0, 1, At, B1); PG8_BAR; PG8_SCHED;
;             PG8_LDA(At, 1, 1); PG8_STAGE(PG8_SB(1, 0), b3, voffB); PG8_STAGE(PG8_SB(1, 1), b3 + hstep, voffB); PG8_STAGE(PG8_SA(1, 0), a3, voffA);
	s_setprio 1
	s_waitcnt lgkmcnt(0)
	v_mfma_f32_16x16x32_bf16 v[62:65], v[144:147], v[212:215], v[62:65]
	v_mfma_f32_16x16x32_bf16 v[62:65], v[184:187], v[216:219], v[62:65]
	v_mfma_f32_16x16x32_bf16 v[58:61], v[188:191], v[212:215], v[58:61]
	v_mfma_f32_16x16x32_bf16 v[58:61], v[192:195], v[216:219], v[58:61]
	v_mfma_f32_16x16x32_bf16 v[46:49], v[144:147], v[220:223], v[46:49]
	v_mfma_f32_16x16x32_bf16 v[46:49], v[184:187], v[224:227], v[46:49]
	v_mfma_f32_16x16x32_bf16 v[42:45], v[188:191], v[220:223], v[42:45]
	v_mfma_f32_16x16x32_bf16 v[42:45], v[192:195], v[224:227], v[42:45]
	v_mfma_f32_16x16x32_bf16 v[30:33], v[144:147], v[228:231], v[30:33]
	v_mfma_f32_16x16x32_bf16 v[30:33], v[184:187], v[232:235], v[30:33]
	v_mfma_f32_16x16x32_bf16 v[26:29], v[188:191], v[228:231], v[26:29]
	v_mfma_f32_16x16x32_bf16 v[26:29], v[192:195], v[232:235], v[26:29]
	v_mfma_f32_16x16x32_bf16 v[14:17], v[144:147], v[236:239], v[14:17]
	v_mfma_f32_16x16x32_bf16 v[14:17], v[184:187], v[240:243], v[14:17]
	v_mfma_f32_16x16x32_bf16 v[10:13], v[188:191], v[236:239], v[10:13]
	v_mfma_f32_16x16x32_bf16 v[10:13], v[192:195], v[240:243], v[10:13]
	v_mfma_f32_16x16x32_bf16 v[54:57], v[196:199], v[212:215], v[54:57]
	v_mfma_f32_16x16x32_bf16 v[54:57], v[200:203], v[216:219], v[54:57]
	v_mfma_f32_16x16x32_bf16 v[50:53], v[204:207], v[212:215], v[50:53]
	v_mfma_f32_16x16x32_bf16 v[50:53], v[208:211], v[216:219], v[50:53]
	v_mfma_f32_16x16x32_bf16 v[38:41], v[196:199], v[220:223], v[38:41]
	v_mfma_f32_16x16x32_bf16 v[38:41], v[200:203], v[224:227], v[38:41]
	v_mfma_f32_16x16x32_bf16 v[34:37], v[204:207], v[220:223], v[34:37]
	v_mfma_f32_16x16x32_bf16 v[34:37], v[208:211], v[224:227], v[34:37]
	v_mfma_f32_16x16x32_bf16 v[22:25], v[196:199], v[228:231], v[22:25]
	v_mfma_f32_16x16x32_bf16 v[22:25], v[200:203], v[232:235], v[22:25]
	v_mfma_f32_16x16x32_bf16 v[18:21], v[204:207], v[228:231], v[18:21]
	v_mfma_f32_16x16x32_bf16 v[18:21], v[208:211], v[232:235], v[18:21]
	s_barrier
	s_setprio 2
	v_mfma_f32_16x16x32_bf16 v[6:9], v[196:199], v[236:239], v[6:9]
	v_mfma_f32_16x16x32_bf16 v[6:9], v[200:203], v[240:243], v[6:9]
	v_mfma_f32_16x16x32_bf16 v[2:5], v[204:207], v[236:239], v[2:5]
	v_mfma_f32_16x16x32_bf16 v[2:5], v[208:211], v[240:243], v[2:5]
	s_setprio 0
	s_add_i32 s14, 0, 0x18000
	v_add_u32_e32 v133, s14, v148
	s_add_i32 s15, 0, 0x1c000
	ds_read_b128 v[144:147], v133
	ds_read_b128 v[184:187], v133 offset:1024
	ds_read_b128 v[188:191], v133 offset:2048
	ds_read_b128 v[192:195], v133 offset:3072
	v_add_u32_e32 v133, s15, v148
	ds_read_b128 v[196:199], v133
	ds_read_b128 v[200:203], v133 offset:1024
	ds_read_b128 v[204:207], v133 offset:2048
	ds_read_b128 v[208:211], v133 offset:3072
	s_mov_b32 m0, s57
	v_lshl_add_u64 v[246:247], v[244:245], 0, s[24:25]
	ds_read_b128 v[212:215], v168 offset:32768
	ds_read_b128 v[216:219], v168 offset:33792
	ds_read_b128 v[220:223], v168 offset:34816
	ds_read_b128 v[224:227], v168 offset:35840
	ds_read_b128 v[228:231], v168 offset:36864
	ds_read_b128 v[232:235], v168 offset:37888
	ds_read_b128 v[236:239], v168 offset:38912
	ds_read_b128 v[240:243], v168 offset:39936
	global_load_lds_dwordx4 v[246:247], off
	v_lshl_add_u64 v[246:247], v[244:245], 0, s[26:27]
	s_mov_b32 m0, s58
	s_nop 0
	global_load_lds_dwordx4 v[246:247], off
	s_waitcnt vmcnt(8)
	s_waitcnt lgkmcnt(0)
	s_barrier
	s_setprio 1
	s_waitcnt lgkmcnt(0)
	v_mfma_f32_16x16x32_bf16 v[126:129], v[144:147], v[212:215], v[126:129]
	v_mfma_f32_16x16x32_bf16 v[126:129], v[184:187], v[216:219], v[126:129]
	v_mfma_f32_16x16x32_bf16 v[122:125], v[188:191], v[212:215], v[122:125]
	v_mfma_f32_16x16x32_bf16 v[122:125], v[192:195], v[216:219], v[122:125]
	v_mfma_f32_16x16x32_bf16 v[110:113], v[144:147], v[220:223], v[110:113]
	v_mfma_f32_16x16x32_bf16 v[110:113], v[184:187], v[224:227], v[110:113]
	v_mfma_f32_16x16x32_bf16 v[106:109], v[188:191], v[220:223], v[106:109]
	v_mfma_f32_16x16x32_bf16 v[106:109], v[192:195], v[224:227], v[106:109]
	v_mfma_f32_16x16x32_bf16 v[94:97], v[144:147], v[228:231], v[94:97]
	v_mfma_f32_16x16x32_bf16 v[94:97], v[184:187], v[232:235], v[94:97]
	v_mfma_f32_16x16x32_bf16 v[90:93], v[188:191], v[228:231], v[90:93]
	v_mfma_f32_16x16x32_bf16 v[90:93], v[192:195], v[232:235], v[90:93]
	v_mfma_f32_16x16x32_bf16 v[78:81], v[144:147], v[236:239], v[78:81]
	v_mfma_f32_16x16x32_bf16 v[78:81], v[184:187], v[240:243], v[78:81]
	v_mfma_f32_16x16x32_bf16 v[74:77], v[188:191], v[236:239], v[74:77]
	v_mfma_f32_16x16x32_bf16 v[74:77], v[192:195], v[240:243], v[74:77]
	v_mfma_f32_16x16x32_bf16 v[118:121], v[196:199], v[212:215], v[118:121]
	v_mfma_f32_16x16x32_bf16 v[118:121], v[200:203], v[216:219], v[118:121]
	v_mfma_f32_16x16x32_bf16 v[114:117], v[204:207], v[212:215], v[114:117]
	v_mfma_f32_16x16x32_bf16 v[114:117], v[208:211], v[216:219], v[114:117]
	v_mfma_f32_16x16x32_bf16 v[102:105], v[196:199], v[220:223], v[102:105]
	v_mfma_f32_16x16x32_bf16 v[102:105], v[200:203], v[224:227], v[102:105]
	v_mfma_f32_16x16x32_bf16 v[98:101], v[204:207], v[220:223], v[98:101]
	v_mfma_f32_16x16x32_bf16 v[98:101], v[208:211], v[224:227], v[98:101]
	v_mfma_f32_16x16x32_bf16 v[86:89], v[196:199], v[228:231], v[86:89]
	v_mfma_f32_16x16x32_bf16 v[86:89], v[200:203], v[232:235], v[86:89]
	v_mfma_f32_16x16x32_bf16 v[82:85], v[204:207], v[228:231], v[82:85]
	v_mfma_f32_16x16x32_bf16 v[82:85], v[208:211], v[232:235], v[82:85]
	s_barrier
; #define PG8_STAGE(bufoff, gbase, voff) do { if constexpr (!pg8_noload<Epi>::value) { _Pragma("unroll") for (int _i = 0; _i < 2; ++_i) \
;         __builtin_amdgcn_global_load_lds((const unsigned*)((const char*)(gbase) + (size_t)_i * pstep + (voff)[0]), (PG8_LAS unsigned*)(lds + (bufoff) + ldsw + _i * 8192), 16, 0, 0); } } while (0)
; #define PG8_LDA(dst, b, h) do { _Pragma("unroll") for (int m = 0; m < 4; ++m) _Pragma("unroll") for (int k = 0; k < 2; ++k) dst[m][k] = *(const PG8_LAS bf16x8*)(lds + PG8_SA(b, h) + aoff + m * 2048 + k * 1024); } while (0)
; #define PG8_LDB(dst, b, h) do { _Pragma("unroll") for (int n = 0; n < 2; ++n) _Pragma("unroll") for (int k = 0; k < 2; ++k) dst[n][k] = *(const PG8_LAS bf16x8*)(lds + PG8_SB(b, h) + boff + n * 2048 + k * 1024); } while (0)
; #define PG8_MMA(ai, bj, At, Bt) do { __builtin_amdgcn_s_setprio(1); _Pragma("unroll") for (int m = 0; m < 4; ++m) _Pragma("unroll") for (int n = 0; n < 2; ++n) _Pragma("unroll") for (int k = 0; k < 2; ++k) \
;         acc[ai][bj][m][n] = __builtin_amdgcn_mfma_f32_16x16x32_bf16(Bt[n][k], At[m][k], acc[ai][bj][m][n], 0, 0, 0); __builtin_amdgcn_s_setprio(0); } while (0)
; #define PG8_WAIT_V(n) asm volatile("s_waitcnt vmcnt(" #n ")" ::: "memory")
; #define PG8_WAIT_L(n) asm volatile("s_waitcnt lgkmcnt(" #n ")" ::: "memory")
; #define PG8_BAR __builtin_amdgcn_s_barrier()
; #define PG8_SCHED __builtin_amdgcn_sched_barrier(0)
; template <class Epi, class Sched, bool ALIGN_EPI = false, bool SP2 = false, bool ABLK = false>
; __device__ __forceinline__ void gemm_phase(PG8_LAS unsigned char* lds, const Gemm g, const Sched& S, const Epi& E) {
;     ...
;             PG8_WAIT_V(8); PG8_WAIT_L(0); PG8_BAR; PG8_MMA(1, 0, At, B0); PG8_MMA(1, 1, At, B1); PG8_BAR; PG8_SCHED;
;             PG8_LDB(B0, 1, 0); PG8_LDB(B1, 1, 1); PG8_SCHED; PG8_LDA(At, 1, 0); PG8_STAGE(PG8_SA(0, 1), a2 + hstep, voffA);
;             PG8_WAIT_V(8); PG8_WAIT_L(0); PG8_BAR; PG8_MMA(0, 0, At, B0); PG8_MMA(0, 1, At, B1); PG8_BAR; PG8_SCHED;
;             PG8_LDA(At, 1, 1); PG8_STAGE(PG8_SB(1, 0), b3, voffB); PG8_STAGE(PG8_SB(1, 1), b3 + hstep, voffB); PG8_STAGE(PG8_SA(1, 0), a3, voffA);
;             PG8_WAIT_V(8); PG8_WAIT_L(0); PG8_BAR; PG8_MMA(1, 0, At, B0); PG8_MMA(1, 1, At, B1); PG8_BAR; PG8_SCHED;
	s_setprio 2
	v_mfma_f32_16x16x32_bf16 v[70:73], v[196:199], v[236:239], v[70:73]
	v_mfma_f32_16x16x32_bf16 v[70:73], v[200:203], v[240:243], v[70:73]
	v_mfma_f32_16x16x32_bf16 v[66:69], v[204:207], v[236:239], v[66:69]
	v_mfma_f32_16x16x32_bf16 v[66:69], v[208:211], v[240:243], v[66:69]
	s_setprio 0
	s_add_i32 s14, s14, s3
	v_lshl_add_u64 v[246:247], v[180:181], 0, s[38:39]
	s_mov_b32 m0, s14
	ds_read_b128 v[212:215], v168 offset:49152
	ds_read_b128 v[216:219], v168 offset:50176
	ds_read_b128 v[220:223], v168 offset:51200
	ds_read_b128 v[224:227], v168 offset:52224
	ds_read_b128 v[228:231], v168 offset:53248
	ds_read_b128 v[232:235], v168 offset:54272
	ds_read_b128 v[236:239], v168 offset:55296
	ds_read_b128 v[240:243], v168 offset:56320
	global_load_lds_dwordx4 v[246:247], off
	v_lshl_add_u64 v[246:247], v[180:181], 0, s[40:41]
	s_add_i32 m0, s14, 0x2000
	s_add_i32 s14, s15, s3
	global_load_lds_dwordx4 v[246:247], off
	v_lshl_add_u64 v[246:247], v[180:181], 0, s[42:43]
	s_mov_b32 m0, s14
	v_lshl_add_u64 v[180:181], v[180:181], 0, s[44:45]
	global_load_lds_dwordx4 v[246:247], off
	s_add_i32 m0, s14, 0x2000
	s_nop 0
	global_load_lds_dwordx4 v[180:181], off
	v_lshl_add_u64 v[180:181], v[244:245], 0, s[38:39]
	s_mov_b32 m0, s61
	s_nop 0
	global_load_lds_dwordx4 v[180:181], off
	v_lshl_add_u64 v[180:181], v[244:245], 0, s[40:41]
	s_mov_b32 m0, s63
	s_nop 0
	global_load_lds_dwordx4 v[180:181], off
	s_waitcnt vmcnt(8)
	s_waitcnt lgkmcnt(0)
	s_barrier
	s_setprio 1
	s_waitcnt lgkmcnt(0)
	v_mfma_f32_16x16x32_bf16 v[62:65], v[144:147], v[212:215], v[62:65]
	v_mfma_f32_16x16x32_bf16 v[62:65], v[184:187], v[216:219], v[62:65]
	v_mfma_f32_16x16x32_bf16 v[58:61], v[188:191], v[212:215], v[58:61]
	v_mfma_f32_16x16x32_bf16 v[58:61], v[192:195], v[216:219], v[58:61]
	v_mfma_f32_16x16x32_bf16 v[46:49], v[144:147], v[220:223], v[46:49]
	v_mfma_f32_16x16x32_bf16 v[46:49], v[184:187], v[224:227], v[46:49]
	v_mfma_f32_16x16x32_bf16 v[42:45], v[188:191], v[220:223], v[42:45]
	v_mfma_f32_16x16x32_bf16 v[42:45], v[192:195], v[224:227], v[42:45]
	v_mfma_f32_16x16x32_bf16 v[30:33], v[144:147], v[228:231], v[30:33]
	v_mfma_f32_16x16x32_bf16 v[30:33], v[184:187], v[232:235], v[30:33]
	v_mfma_f32_16x16x32_bf16 v[26:29], v[188:191], v[228:231], v[26:29]
	v_mfma_f32_16x16x32_bf16 v[26:29], v[192:195], v[232:235], v[26:29]
	v_mfma_f32_16x16x32_bf16 v[14:17], v[144:147], v[236:239], v[14:17]
	v_mfma_f32_16x16x32_bf16 v[14:17], v[184:187], v[240:243], v[14:17]
	v_mfma_f32_16x16x32_bf16 v[10:13], v[188:191], v[236:239], v[10:13]
	v_mfma_f32_16x16x32_bf16 v[10:13], v[192:195], v[240:243], v[10:13]
	v_mfma_f32_16x16x32_bf16 v[54:57], v[196:199], v[212:215], v[54:57]
	v_mfma_f32_16x16x32_bf16 v[54:57], v[200:203], v[216:219], v[54:57]
	v_mfma_f32_16x16x32_bf16 v[50:53], v[204:207], v[212:215], v[50:53]
	v_mfma_f32_16x16x32_bf16 v[50:53], v[208:211], v[216:219], v[50:53]
	v_mfma_f32_16x16x32_bf16 v[38:41], v[196:199], v[220:223], v[38:41]
	v_mfma_f32_16x16x32_bf16 v[38:41], v[200:203], v[224:227], v[38:41]
	v_mfma_f32_16x16x32_bf16 v[34:37], v[204:207], v[220:223], v[34:37]
	v_mfma_f32_16x16x32_bf16 v[34:37], v[208:211], v[224:227], v[34:37]
	v_mfma_f32_16x16x32_bf16 v[22:25], v[196:199], v[228:231], v[22:25]
	v_mfma_f32_16x16x32_bf16 v[22:25], v[200:203], v[232:235], v[22:25]
	v_mfma_f32_16x16x32_bf16 v[18:21], v[204:207], v[228:231], v[18:21]
	v_mfma_f32_16x16x32_bf16 v[18:21], v[208:211], v[232:235], v[18:21]
	s_barrier
	s_setprio 2
	v_mfma_f32_16x16x32_bf16 v[6:9], v[196:199], v[236:239], v[6:9]
	v_mfma_f32_16x16x32_bf16 v[6:9], v[200:203], v[240:243], v[6:9]
	v_mfma_f32_16x16x32_bf16 v[2:5], v[204:207], v[236:239], v[2:5]
	v_mfma_f32_16x16x32_bf16 v[2:5], v[208:211], v[240:243], v[2:5]
	s_setprio 0
	s_cmp_gt_u32 s59, 29
	s_mov_b32 s59, s30
	s_cbranch_scc1 .LBB0_2131

; #define PG8_STAGE(bufoff, gbase, voff) do { if constexpr (!pg8_noload<Epi>::value) { _Pragma("unroll") for (int _i = 0; _i < 2; ++_i) \
;         __builtin_amdgcn_global_load_lds((const unsigned*)((const char*)(gbase) + (size_t)_i * pstep + (voff)[0]), (PG8_LAS unsigned*)(lds + (bufoff) + ldsw + _i * 8192), 16, 0, 0); } } while (0)
; #define PG8_LDA(dst, b, h) do { _Pragma("unroll") for (int m = 0; m < 4; ++m) _Pragma("unroll") for (int k = 0; k < 2; ++k) dst[m][k] = *(const PG8_LAS bf16x8*)(lds + PG8_SA(b, h) + aoff + m * 2048 + k * 1024); } while (0)
; #define PG8_LDB(dst, b, h) do { _Pragma("unroll") for (int n = 0; n < 2; ++n) _Pragma("unroll") for (int k = 0; k < 2; ++k) dst[n][k] = *(const PG8_LAS bf16x8*)(lds + PG8_SB(b, h) + boff + n * 2048 + k * 1024); } while (0)
; #define PG8_MMA(ai, bj, At, Bt) do { __builtin_amdgcn_s_setprio(1); _Pragma("unroll") for (int m = 0; m < 4; ++m) _Pragma("unroll") for (int n = 0; n < 2; ++n) _Pragma("unroll") for (int k = 0; k < 2; ++k) \
;         acc[ai][bj][m][n] = __builtin_amdgcn_mfma_f32_16x16x32_bf16(Bt[n][k], At[m][k], acc[ai][bj][m][n], 0, 0, 0); __builtin_amdgcn_s_setprio(0); } while (0)
; #define PG8_BAR __builtin_amdgcn_s_barrier()
; template <class Epi, class Sched, bool ALIGN_EPI = false, bool SP2 = false, bool ABLK = false>
; __device__ __forceinline__ void gemm_phase(PG8_LAS unsigned char* lds, const Gemm g, const Sched& S, const Epi& E) {
;     ...
;         for (int t = 0; t < nt; t += 2) {
;             const bool last = (t == nt - 2);
;             const char* a1 = cA + (size_t)(t + 1) * kstep;
;             const char* a2 = last ? nA : cA + (size_t)(t + 2) * kstep; const char* b2 = last ? nB : cB + (size_t)(t + 2) * kstepB;
;             const char* a3 = a2 + kstep; const char* b3 = b2 + kstepB;
;             if (last && has_next) S.a_ready(nxt);
;             if constexpr (SP2) {
;             PG8_LDB(B0, 0, 0); PG8_LDB(B1, 0, 1); PG8_SCHED; PG8_LDA(At, 0, 0); PG8_STAGE(PG8_SA(1, 1), a1 + hstep, voffA);
;             PG8_WAIT_V(8); PG8_WAIT_L(0); PG8_BAR; PG8_MMA(0, 0, At, B0); PG8_MMA(0, 1, At, B1); PG8_BAR; PG8_SCHED;
;             PG8_LDA(At, 0, 1); PG8_STAGE(PG8_SB(0, 0), b2, voffB); PG8_STAGE(PG8_SB(0, 1), b2 + hstep, voffB); PG8_STAGE(PG8_SA(0, 0), a2, voffA);
;             PG8_WAIT_V(8); PG8_WAIT_L(0); PG8_BAR; PG8_MMA(1, 0, At, B0); PG8_MMA(1, 1, At, B1); PG8_BAR; PG8_SCHED;
.LBB0_2399:
	ds_read_b128 v[130:133], v175
	ds_read_b128 v[134:137], v175 offset:1024
	ds_read_b128 v[138:141], v175 offset:2048
	ds_read_b128 v[142:145], v175 offset:3072
	ds_read_b128 v[146:149], v176
	ds_read_b128 v[150:153], v176 offset:1024
	ds_read_b128 v[154:157], v176 offset:2048
	ds_read_b128 v[158:161], v176 offset:3072
	s_add_i32 s55, s53, 2
	s_add_u32 s64, s62, 0xfff00800
	s_addc_u32 s65, s63, -1
	s_cmp_eq_u32 s3, s53
	s_cselect_b32 s65, s57, s65
	s_cselect_b32 s64, s56, s64
	s_cselect_b32 s91, s59, s49
	s_cselect_b32 s90, s58, s11
	v_lshl_add_u64 v[170:171], s[62:63], 0, v[166:167]
	s_add_i32 m0, s61, 0xc000
	ds_read_b128 v[184:187], v177
	ds_read_b128 v[188:191], v177 offset:1024
	ds_read_b128 v[192:195], v177 offset:2048
	ds_read_b128 v[196:199], v177 offset:3072
	ds_read_b128 v[200:203], v177 offset:4096
	ds_read_b128 v[204:207], v177 offset:5120
	ds_read_b128 v[208:211], v177 offset:6144
	ds_read_b128 v[212:215], v177 offset:7168
	global_load_lds_dwordx4 v[170:171], off
	v_lshl_add_u64 v[170:171], v[170:171], 0, s[12:13]
	s_add_i32 m0, s61, 0xe000
	s_nop 0
	global_load_lds_dwordx4 v[170:171], off
	s_waitcnt vmcnt(8)
	s_waitcnt lgkmcnt(0)
	s_barrier
	s_setprio 1
	s_waitcnt lgkmcnt(0)
	v_mfma_f32_16x16x32_bf16 v[126:129], v[130:133], v[184:187], v[126:129]
	v_mfma_f32_16x16x32_bf16 v[126:129], v[134:137], v[188:191], v[126:129]
	v_mfma_f32_16x16x32_bf16 v[122:125], v[138:141], v[184:187], v[122:125]
	v_mfma_f32_16x16x32_bf16 v[122:125], v[142:145], v[188:191], v[122:125]
	v_mfma_f32_16x16x32_bf16 v[110:113], v[130:133], v[192:195], v[110:113]
	v_mfma_f32_16x16x32_bf16 v[110:113], v[134:137], v[196:199], v[110:113]
	v_mfma_f32_16x16x32_bf16 v[106:109], v[138:141], v[192:195], v[106:109]
	v_mfma_f32_16x16x32_bf16 v[106:109], v[142:145], v[196:199], v[106:109]
	v_mfma_f32_16x16x32_bf16 v[94:97], v[130:133], v[200:203], v[94:97]
	v_mfma_f32_16x16x32_bf16 v[94:97], v[134:137], v[204:207], v[94:97]
	v_mfma_f32_16x16x32_bf16 v[90:93], v[138:141], v[200:203], v[90:93]
	v_mfma_f32_16x16x32_bf16 v[90:93], v[142:145], v[204:207], v[90:93]
	v_mfma_f32_16x16x32_bf16 v[78:81], v[130:133], v[208:211], v[78:81]
	v_mfma_f32_16x16x32_bf16 v[78:81], v[134:137], v[212:215], v[78:81]
	v_mfma_f32_16x16x32_bf16 v[74:77], v[138:141], v[208:211], v[74:77]
	v_mfma_f32_16x16x32_bf16 v[74:77], v[142:145], v[212:215], v[74:77]
	v_mfma_f32_16x16x32_bf16 v[118:121], v[146:149], v[184:187], v[118:121]
	v_mfma_f32_16x16x32_bf16 v[118:121], v[150:153], v[188:191], v[118:121]
	v_mfma_f32_16x16x32_bf16 v[114:117], v[154:157], v[184:187], v[114:117]
	v_mfma_f32_16x16x32_bf16 v[114:117], v[158:161], v[188:191], v[114:117]
	v_mfma_f32_16x16x32_bf16 v[102:105], v[146:149], v[192:195], v[102:105]
	v_mfma_f32_16x16x32_bf16 v[102:105], v[150:153], v[196:199], v[102:105]
	v_mfma_f32_16x16x32_bf16 v[98:101], v[154:157], v[192:195], v[98:101]
	v_mfma_f32_16x16x32_bf16 v[98:101], v[158:161], v[196:199], v[98:101]
	v_mfma_f32_16x16x32_bf16 v[86:89], v[146:149], v[200:203], v[86:89]
	v_mfma_f32_16x16x32_bf16 v[86:89], v[150:153], v[204:207], v[86:89]
	v_mfma_f32_16x16x32_bf16 v[82:85], v[154:157], v[200:203], v[82:85]
	v_mfma_f32_16x16x32_bf16 v[82:85], v[158:161], v[204:207], v[82:85]
	s_barrier
	s_setprio 2
	v_mfma_f32_16x16x32_bf16 v[70:73], v[146:149], v[208:211], v[70:73]
	v_mfma_f32_16x16x32_bf16 v[70:73], v[150:153], v[212:215], v[70:73]
	v_mfma_f32_16x16x32_bf16 v[66:69], v[154:157], v[208:211], v[66:69]
	v_mfma_f32_16x16x32_bf16 v[66:69], v[158:161], v[212:215], v[66:69]
	s_setprio 0
	s_add_i32 s53, s80, s69
	v_lshl_add_u64 v[170:171], s[90:91], 0, v[162:163]
	s_mov_b32 m0, s53
	ds_read_b128 v[184:187], v177 offset:16384
	ds_read_b128 v[188:191], v177 offset:17408
	ds_read_b128 v[192:195], v177 offset:18432
	ds_read_b128 v[196:199], v177 offset:19456
	ds_read_b128 v[200:203], v177 offset:20480
	ds_read_b128 v[204:207], v177 offset:21504
	ds_read_b128 v[208:211], v177 offset:22528
	ds_read_b128 v[212:215], v177 offset:23552
	global_load_lds_dwordx4 v[170:171], off
	v_lshl_add_u64 v[216:217], v[170:171], 0, s[12:13]
	s_add_i32 m0, s53, 0x2000
	s_add_i32 s53, s81, s69
	global_load_lds_dwordx4 v[216:217], off
	v_lshl_add_u64 v[216:217], v[170:171], 0, s[14:15]
	s_mov_b32 m0, s53
	s_nop 0
	global_load_lds_dwordx4 v[216:217], off
	v_lshl_add_u64 v[216:217], v[170:171], 0, s[16:17]
	s_add_i32 m0, s53, 0x2000
	s_nop 0
	global_load_lds_dwordx4 v[216:217], off
	v_lshl_add_u64 v[216:217], s[64:65], 0, v[162:163]
	s_mov_b32 m0, s61
	v_lshl_add_u64 v[218:219], v[216:217], 0, s[12:13]
	global_load_lds_dwordx4 v[216:217], off
	s_mov_b32 m0, s70
	s_nop 0
	global_load_lds_dwordx4 v[218:219], off
	s_waitcnt vmcnt(8)
	s_waitcnt lgkmcnt(0)
	s_barrier
; #define PG8_STAGE(bufoff, gbase, voff) do { if constexpr (!pg8_noload<Epi>::value) { _Pragma("unroll") for (int _i = 0; _i < 2; ++_i) \
;         __builtin_amdgcn_global_load_lds((const unsigned*)((const char*)(gbase) + (size_t)_i * pstep + (voff)[0]), (PG8_LAS unsigned*)(lds + (bufoff) + ldsw + _i * 8192), 16, 0, 0); } } while (0)
; #define PG8_LDA(dst, b, h) do { _Pragma("unroll") for (int m = 0; m < 4; ++m) _Pragma("unroll") for (int k = 0; k < 2; ++k) dst[m][k] = *(const PG8_LAS bf16x8*)(lds + PG8_SA(b, h) + aoff + m * 2048 + k * 1024); } while (0)
; #define PG8_LDB(dst, b, h) do { _Pragma("unroll") for (int n = 0; n < 2; ++n) _Pragma("unroll") for (int k = 0; k < 2; ++k) dst[n][k] = *(const PG8_LAS bf16x8*)(lds + PG8_SB(b, h) + boff + n * 2048 + k * 1024); } while (0)
; #define PG8_MMA(ai, bj, At, Bt) do { __builtin_amdgcn_s_setprio(1); _Pragma("unroll") for (int m = 0; m < 4; ++m) _Pragma("unroll") for (int n = 0; n < 2; ++n) _Pragma("unroll") for (int k = 0; k < 2; ++k) \
;         acc[ai][bj][m][n] = __builtin_amdgcn_mfma_f32_16x16x32_bf16(Bt[n][k], At[m][k], acc[ai][bj][m][n], 0, 0, 0); __builtin_amdgcn_s_setprio(0); } while (0)
; #define PG8_WAIT_V(n) asm volatile("s_waitcnt vmcnt(" #n ")" ::: "memory")
; #define PG8_WAIT_L(n) asm volatile("s_waitcnt lgkmcnt(" #n ")" ::: "memory")
; #define PG8_BAR __builtin_amdgcn_s_barrier()
; #define PG8_SCHED __builtin_amdgcn_sched_barrier(0)
; template <class Epi, class Sched, bool ALIGN_EPI = false, bool SP2 = false, bool ABLK = false>
; __device__ __forceinline__ void gemm_phase(PG8_LAS unsigned char* lds, const Gemm g, const Sched& S, const Epi& E) {
;     ...
;             PG8_WAIT_V(8); PG8_WAIT_L(0); PG8_BAR; PG8_MMA(1, 0, At, B0); PG8_MMA(1, 1, At, B1); PG8_BAR; PG8_SCHED;
;             PG8_LDB(B0, 1, 0); PG8_LDB(B1, 1, 1); PG8_SCHED; PG8_LDA(At, 1, 0); PG8_STAGE(PG8_SA(0, 1), a2 + hstep, voffA);
;             PG8_WAIT_V(8); PG8_WAIT_L(0); PG8_BAR; PG8_MMA(0, 0, At, B0); PG8_MMA(0, 1, At, B1); PG8_BAR; PG8_SCHED;
	s_setprio 1
	s_waitcnt lgkmcnt(0)
	v_mfma_f32_16x16x32_bf16 v[62:65], v[130:133], v[184:187], v[62:65]
	v_mfma_f32_16x16x32_bf16 v[62:65], v[134:137], v[188:191], v[62:65]
	v_mfma_f32_16x16x32_bf16 v[58:61], v[138:141], v[184:187], v[58:61]
	v_mfma_f32_16x16x32_bf16 v[58:61], v[142:145], v[188:191], v[58:61]
	v_mfma_f32_16x16x32_bf16 v[46:49], v[130:133], v[192:195], v[46:49]
	v_mfma_f32_16x16x32_bf16 v[46:49], v[134:137], v[196:199], v[46:49]
	v_mfma_f32_16x16x32_bf16 v[42:45], v[138:141], v[192:195], v[42:45]
	v_mfma_f32_16x16x32_bf16 v[42:45], v[142:145], v[196:199], v[42:45]
	v_mfma_f32_16x16x32_bf16 v[30:33], v[130:133], v[200:203], v[30:33]
	v_mfma_f32_16x16x32_bf16 v[30:33], v[134:137], v[204:207], v[30:33]
	v_mfma_f32_16x16x32_bf16 v[26:29], v[138:141], v[200:203], v[26:29]
	v_mfma_f32_16x16x32_bf16 v[26:29], v[142:145], v[204:207], v[26:29]
	v_mfma_f32_16x16x32_bf16 v[14:17], v[130:133], v[208:211], v[14:17]
	v_mfma_f32_16x16x32_bf16 v[14:17], v[134:137], v[212:215], v[14:17]
	v_mfma_f32_16x16x32_bf16 v[10:13], v[138:141], v[208:211], v[10:13]
	v_mfma_f32_16x16x32_bf16 v[10:13], v[142:145], v[212:215], v[10:13]
	v_mfma_f32_16x16x32_bf16 v[54:57], v[146:149], v[184:187], v[54:57]
	v_mfma_f32_16x16x32_bf16 v[54:57], v[150:153], v[188:191], v[54:57]
	v_mfma_f32_16x16x32_bf16 v[50:53], v[154:157], v[184:187], v[50:53]
	v_mfma_f32_16x16x32_bf16 v[50:53], v[158:161], v[188:191], v[50:53]
	v_mfma_f32_16x16x32_bf16 v[38:41], v[146:149], v[192:195], v[38:41]
	v_mfma_f32_16x16x32_bf16 v[38:41], v[150:153], v[196:199], v[38:41]
	v_mfma_f32_16x16x32_bf16 v[34:37], v[154:157], v[192:195], v[34:37]
	v_mfma_f32_16x16x32_bf16 v[34:37], v[158:161], v[196:199], v[34:37]
	v_mfma_f32_16x16x32_bf16 v[22:25], v[146:149], v[200:203], v[22:25]
	v_mfma_f32_16x16x32_bf16 v[22:25], v[150:153], v[204:207], v[22:25]
	v_mfma_f32_16x16x32_bf16 v[18:21], v[154:157], v[200:203], v[18:21]
	v_mfma_f32_16x16x32_bf16 v[18:21], v[158:161], v[204:207], v[18:21]
	s_barrier
	s_setprio 2
	v_mfma_f32_16x16x32_bf16 v[6:9], v[146:149], v[208:211], v[6:9]
	v_mfma_f32_16x16x32_bf16 v[6:9], v[150:153], v[212:215], v[6:9]
	v_mfma_f32_16x16x32_bf16 v[2:5], v[154:157], v[208:211], v[2:5]
	v_mfma_f32_16x16x32_bf16 v[2:5], v[158:161], v[212:215], v[2:5]
	s_setprio 0
	s_add_i32 s53, 0, 0x18000
	s_add_i32 s64, 0, 0x1c000
	v_add_u32_e32 v142, s53, v1
	v_add_u32_e32 v158, s64, v1
	ds_read_b128 v[130:133], v142
	ds_read_b128 v[134:137], v142 offset:1024
	ds_read_b128 v[138:141], v142 offset:2048
	ds_read_b128 v[142:145], v142 offset:3072
	ds_read_b128 v[146:149], v158
	ds_read_b128 v[150:153], v158 offset:1024
	ds_read_b128 v[154:157], v158 offset:2048
	ds_read_b128 v[158:161], v158 offset:3072
	s_mov_b32 m0, s71
	v_lshl_add_u64 v[218:219], v[216:217], 0, s[14:15]
	ds_read_b128 v[184:187], v177 offset:32768
	ds_read_b128 v[188:191], v177 offset:33792
	ds_read_b128 v[192:195], v177 offset:34816
	ds_read_b128 v[196:199], v177 offset:35840
	ds_read_b128 v[200:203], v177 offset:36864
	ds_read_b128 v[204:207], v177 offset:37888
	ds_read_b128 v[208:211], v177 offset:38912
	ds_read_b128 v[212:215], v177 offset:39936
	global_load_lds_dwordx4 v[218:219], off
	v_lshl_add_u64 v[218:219], v[216:217], 0, s[16:17]
	s_mov_b32 m0, s72
	s_nop 0
	global_load_lds_dwordx4 v[218:219], off
	s_waitcnt vmcnt(8)
	s_waitcnt lgkmcnt(0)
	s_barrier
	s_setprio 1
	s_waitcnt lgkmcnt(0)
	v_mfma_f32_16x16x32_bf16 v[126:129], v[130:133], v[184:187], v[126:129]
	v_mfma_f32_16x16x32_bf16 v[126:129], v[134:137], v[188:191], v[126:129]
	v_mfma_f32_16x16x32_bf16 v[122:125], v[138:141], v[184:187], v[122:125]
	v_mfma_f32_16x16x32_bf16 v[122:125], v[142:145], v[188:191], v[122:125]
	v_mfma_f32_16x16x32_bf16 v[110:113], v[130:133], v[192:195], v[110:113]
	v_mfma_f32_16x16x32_bf16 v[110:113], v[134:137], v[196:199], v[110:113]
	v_mfma_f32_16x16x32_bf16 v[106:109], v[138:141], v[192:195], v[106:109]
	v_mfma_f32_16x16x32_bf16 v[106:109], v[142:145], v[196:199], v[106:109]
	v_mfma_f32_16x16x32_bf16 v[94:97], v[130:133], v[200:203], v[94:97]
	v_mfma_f32_16x16x32_bf16 v[94:97], v[134:137], v[204:207], v[94:97]
	v_mfma_f32_16x16x32_bf16 v[90:93], v[138:141], v[200:203], v[90:93]
	v_mfma_f32_16x16x32_bf16 v[90:93], v[142:145], v[204:207], v[90:93]
	v_mfma_f32_16x16x32_bf16 v[78:81], v[130:133], v[208:211], v[78:81]
	v_mfma_f32_16x16x32_bf16 v[78:81], v[134:137], v[212:215], v[78:81]
	v_mfma_f32_16x16x32_bf16 v[74:77], v[138:141], v[208:211], v[74:77]
	v_mfma_f32_16x16x32_bf16 v[74:77], v[142:145], v[212:215], v[74:77]
	v_mfma_f32_16x16x32_bf16 v[118:121], v[146:149], v[184:187], v[118:121]
	v_mfma_f32_16x16x32_bf16 v[118:121], v[150:153], v[188:191], v[118:121]
	v_mfma_f32_16x16x32_bf16 v[114:117], v[154:157], v[184:187], v[114:117]
	v_mfma_f32_16x16x32_bf16 v[114:117], v[158:161], v[188:191], v[114:117]
	v_mfma_f32_16x16x32_bf16 v[102:105], v[146:149], v[192:195], v[102:105]
	v_mfma_f32_16x16x32_bf16 v[102:105], v[150:153], v[196:199], v[102:105]
	v_mfma_f32_16x16x32_bf16 v[98:101], v[154:157], v[192:195], v[98:101]
	v_mfma_f32_16x16x32_bf16 v[98:101], v[158:161], v[196:199], v[98:101]
	v_mfma_f32_16x16x32_bf16 v[86:89], v[146:149], v[200:203], v[86:89]
	v_mfma_f32_16x16x32_bf16 v[86:89], v[150:153], v[204:207], v[86:89]
	v_mfma_f32_16x16x32_bf16 v[82:85], v[154:157], v[200:203], v[82:85]
	v_mfma_f32_16x16x32_bf16 v[82:85], v[158:161], v[204:207], v[82:85]
	s_barrier
; #define PG8_STAGE(bufoff, gbase, voff) do { if constexpr (!pg8_noload<Epi>::value) { _Pragma("unroll") for (int _i = 0; _i < 2; ++_i) \
;         __builtin_amdgcn_global_load_lds((const unsigned*)((const char*)(gbase) + (size_t)_i * pstep + (voff)[0]), (PG8_LAS unsigned*)(lds + (bufoff) + ldsw + _i * 8192), 16, 0, 0); } } while (0)
; #define PG8_LDA(dst, b, h) do { _Pragma("unroll") for (int m = 0; m < 4; ++m) _Pragma("unroll") for (int k = 0; k < 2; ++k) dst[m][k] = *(const PG8_LAS bf16x8*)(lds + PG8_SA(b, h) + aoff + m * 2048 + k * 1024); } while (0)
; #define PG8_MMA(ai, bj, At, Bt) do { __builtin_amdgcn_s_setprio(1); _Pragma("unroll") for (int m = 0; m < 4; ++m) _Pragma("unroll") for (int n = 0; n < 2; ++n) _Pragma("unroll") for (int k = 0; k < 2; ++k) \
;         acc[ai][bj][m][n] = __builtin_amdgcn_mfma_f32_16x16x32_bf16(Bt[n][k], At[m][k], acc[ai][bj][m][n], 0, 0, 0); __builtin_amdgcn_s_setprio(0); } while (0)
; #define PG8_WAIT_V(n) asm volatile("s_waitcnt vmcnt(" #n ")" ::: "memory")
; #define PG8_WAIT_L(n) asm volatile("s_waitcnt lgkmcnt(" #n ")" ::: "memory")
; #define PG8_BAR __builtin_amdgcn_s_barrier()
; #define PG8_SCHED __builtin_amdgcn_sched_barrier(0)
; template <class Epi, class Sched, bool ALIGN_EPI = false, bool SP2 = false, bool ABLK = false>
; __device__ __forceinline__ void gemm_phase(PG8_LAS unsigned char* lds, const Gemm g, const Sched& S, const Epi& E) {
;     ...
;             PG8_WAIT_V(8); PG8_WAIT_L(0); PG8_BAR; PG8_MMA(0, 0, At, B0); PG8_MMA(0, 1, At, B1); PG8_BAR; PG8_SCHED;
;             PG8_LDA(At, 1, 1); PG8_STAGE(PG8_SB(1, 0), b3, voffB); PG8_STAGE(PG8_SB(1, 1), b3 + hstep, voffB); PG8_STAGE(PG8_SA(1, 0), a3, voffA);
;             PG8_WAIT_V(8); PG8_WAIT_L(0); PG8_BAR; PG8_MMA(1, 0, At, B0); PG8_MMA(1, 1, At, B1); PG8_BAR; PG8_SCHED;
	s_setprio 2
	v_mfma_f32_16x16x32_bf16 v[70:73], v[146:149], v[208:211], v[70:73]
	v_mfma_f32_16x16x32_bf16 v[70:73], v[150:153], v[212:215], v[70:73]
	v_mfma_f32_16x16x32_bf16 v[66:69], v[154:157], v[208:211], v[66:69]
	v_mfma_f32_16x16x32_bf16 v[66:69], v[158:161], v[212:215], v[66:69]
	s_setprio 0
	s_add_i32 s53, s53, s69
	v_lshl_add_u64 v[218:219], v[170:171], 0, s[24:25]
	s_mov_b32 m0, s53
	ds_read_b128 v[184:187], v177 offset:49152
	ds_read_b128 v[188:191], v177 offset:50176
	ds_read_b128 v[192:195], v177 offset:51200
	ds_read_b128 v[196:199], v177 offset:52224
	ds_read_b128 v[200:203], v177 offset:53248
	ds_read_b128 v[204:207], v177 offset:54272
	ds_read_b128 v[208:211], v177 offset:55296
	ds_read_b128 v[212:215], v177 offset:56320
	global_load_lds_dwordx4 v[218:219], off
	v_lshl_add_u64 v[218:219], v[170:171], 0, s[26:27]
	s_add_i32 m0, s53, 0x2000
	s_add_i32 s53, s64, s69
	global_load_lds_dwordx4 v[218:219], off
	v_lshl_add_u64 v[218:219], v[170:171], 0, s[28:29]
	s_mov_b32 m0, s53
	v_lshl_add_u64 v[170:171], v[170:171], 0, s[30:31]
	global_load_lds_dwordx4 v[218:219], off
	s_add_i32 m0, s53, 0x2000
	s_nop 0
	global_load_lds_dwordx4 v[170:171], off
	v_lshl_add_u64 v[170:171], v[216:217], 0, s[24:25]
	s_mov_b32 m0, s75
	s_nop 0
	global_load_lds_dwordx4 v[170:171], off
	v_lshl_add_u64 v[170:171], v[216:217], 0, s[26:27]
	s_mov_b32 m0, s76
	s_nop 0
	global_load_lds_dwordx4 v[170:171], off
	s_waitcnt vmcnt(8)
	s_waitcnt lgkmcnt(0)
	s_barrier
	s_setprio 1
	s_waitcnt lgkmcnt(0)
	v_mfma_f32_16x16x32_bf16 v[62:65], v[130:133], v[184:187], v[62:65]
	v_mfma_f32_16x16x32_bf16 v[62:65], v[134:137], v[188:191], v[62:65]
	v_mfma_f32_16x16x32_bf16 v[58:61], v[138:141], v[184:187], v[58:61]
	v_mfma_f32_16x16x32_bf16 v[58:61], v[142:145], v[188:191], v[58:61]
	v_mfma_f32_16x16x32_bf16 v[46:49], v[130:133], v[192:195], v[46:49]
	v_mfma_f32_16x16x32_bf16 v[46:49], v[134:137], v[196:199], v[46:49]
	v_mfma_f32_16x16x32_bf16 v[42:45], v[138:141], v[192:195], v[42:45]
	v_mfma_f32_16x16x32_bf16 v[42:45], v[142:145], v[196:199], v[42:45]
	v_mfma_f32_16x16x32_bf16 v[30:33], v[130:133], v[200:203], v[30:33]
	v_mfma_f32_16x16x32_bf16 v[30:33], v[134:137], v[204:207], v[30:33]
	v_mfma_f32_16x16x32_bf16 v[26:29], v[138:141], v[200:203], v[26:29]
	v_mfma_f32_16x16x32_bf16 v[26:29], v[142:145], v[204:207], v[26:29]
	v_mfma_f32_16x16x32_bf16 v[14:17], v[130:133], v[208:211], v[14:17]
	v_mfma_f32_16x16x32_bf16 v[14:17], v[134:137], v[212:215], v[14:17]
	v_mfma_f32_16x16x32_bf16 v[10:13], v[138:141], v[208:211], v[10:13]
	v_mfma_f32_16x16x32_bf16 v[10:13], v[142:145], v[212:215], v[10:13]
	v_mfma_f32_16x16x32_bf16 v[54:57], v[146:149], v[184:187], v[54:57]
	v_mfma_f32_16x16x32_bf16 v[54:57], v[150:153], v[188:191], v[54:57]
	v_mfma_f32_16x16x32_bf16 v[50:53], v[154:157], v[184:187], v[50:53]
	v_mfma_f32_16x16x32_bf16 v[50:53], v[158:161], v[188:191], v[50:53]
	v_mfma_f32_16x16x32_bf16 v[38:41], v[146:149], v[192:195], v[38:41]
	v_mfma_f32_16x16x32_bf16 v[38:41], v[150:153], v[196:199], v[38:41]
	v_mfma_f32_16x16x32_bf16 v[34:37], v[154:157], v[192:195], v[34:37]
	v_mfma_f32_16x16x32_bf16 v[34:37], v[158:161], v[196:199], v[34:37]
	v_mfma_f32_16x16x32_bf16 v[22:25], v[146:149], v[200:203], v[22:25]
	v_mfma_f32_16x16x32_bf16 v[22:25], v[150:153], v[204:207], v[22:25]
	v_mfma_f32_16x16x32_bf16 v[18:21], v[154:157], v[200:203], v[18:21]
	v_mfma_f32_16x16x32_bf16 v[18:21], v[158:161], v[204:207], v[18:21]
	s_barrier
	s_setprio 2
	v_mfma_f32_16x16x32_bf16 v[6:9], v[146:149], v[208:211], v[6:9]
	v_mfma_f32_16x16x32_bf16 v[6:9], v[150:153], v[212:215], v[6:9]
	v_mfma_f32_16x16x32_bf16 v[2:5], v[154:157], v[208:211], v[2:5]
	v_mfma_f32_16x16x32_bf16 v[2:5], v[158:161], v[212:215], v[2:5]
	s_setprio 0
	s_add_u32 s62, s62, 0x1000
	s_addc_u32 s63, s63, 0
	s_add_u32 s11, s11, 0x1000
	s_addc_u32 s49, s49, 0
	s_cmp_ge_i32 s55, s89
	s_mov_b32 s53, s55
	s_cbranch_scc0 .LBB0_2399
	s_and_b64 vcc, exec, s[34:35]
	s_cbranch_vccnz .LBB0_2404
	s_lshl_b32 s11, s2, 8
	s_cmp_gt_i32 s2, 63
	s_mov_b64 s[62:63], -1
	s_cbranch_scc1 .LBB0_2405
